# speedup vs baseline: 1.0145x; 1.0051x over previous
; __device__ __forceinline__ u16 f2bf(float x) { return (u16)(cvtpk(x, 0.f) & 0xffffu); }
; __device__ __forceinline__ int crow(int r, int hi) { return (r & 3) + 8 * (r >> 2) + 4 * hi; }
; template <int DQK, int ldq, int ldk, int ldo> ...
;     ...
;   if (hi == 0) li_l[r32] = l_reg; asm volatile("s_waitcnt lgkmcnt(0)" ::: "memory");
;   u16* Ow = Ob + (long)(wid * 32) * ldo;
; #pragma unroll
;   for (int r = 0; r < 16; ++r) { int orow = crow(r, hi); float rl = __builtin_amdgcn_rcpf(li_l[orow]);
; #pragma unroll
;     for (int d0 = 0; d0 < 4; ++d0) Ow[(long)orow * ldo + d0 * 32 + r32] = f2bf(o[d0][r] * rl); }
.LBB0_482:
	s_or_b64 exec, exec, s[0:1]
	s_waitcnt lgkmcnt(0)
	v_add_u32_e32 v6, s31, v182
	ds_read_b128 v[100:103], v6
	ds_read_b128 v[104:107], v6 offset:32
	ds_read_b128 v[108:111], v6 offset:64
	ds_read_b128 v[112:115], v6 offset:96
	s_lshl_b64 s[0:1], s[10:11], 11
	v_readlane_b32 s6, v254, 6
	s_add_u32 s0, s6, s0
	v_readlane_b32 s6, v254, 7
	s_addc_u32 s1, s6, s1
	s_lshl_b32 s6, s13, 8
	s_add_u32 s6, s0, s6
	s_addc_u32 s7, s1, 0
	s_ashr_i32 s13, s12, 31
	s_waitcnt lgkmcnt(0)
	v_mov_b32_e32 v2, v100
	v_rcp_f32_e32 v7, v2
	s_lshl_b64 s[0:1], s[12:13], 11
	s_add_u32 s0, s6, s0
	s_addc_u32 s1, s7, s1
	v_lshlrev_b32_e32 v0, 1, v194
	v_lshl_add_u64 v[2:3], s[0:1], 0, v[0:1]
	v_lshlrev_b32_e32 v0, 13, v193
	v_mul_f32_e32 v8, v48, v7
	v_lshl_add_u64 v[4:5], v[2:3], 0, v[0:1]
	v_cvt_pk_bf16_f32 v8, v8, v1
	global_store_short v[4:5], v8, off
	v_mul_f32_e32 v8, v32, v7
	v_cvt_pk_bf16_f32 v8, v8, v1
	global_store_short v[4:5], v8, off offset:64
	v_mul_f32_e32 v8, v16, v7
	v_cvt_pk_bf16_f32 v8, v8, v1
	v_mul_f32_e32 v7, v64, v7
	global_store_short v[4:5], v8, off offset:128
	v_cvt_pk_bf16_f32 v7, v7, v1
	global_store_short v[4:5], v7, off offset:192
	v_or_b32_e32 v4, 0x800, v0
	v_mov_b32_e32 v5, v1
	v_lshl_add_u64 v[4:5], v[2:3], 0, v[4:5]
	s_waitcnt lgkmcnt(0)
	v_mov_b32_e32 v8, v101
	v_rcp_f32_e32 v7, v8
	v_readlane_b32 s0, v253, 8
	s_add_i32 s30, s30, s0
	s_cmpk_gt_i32 s30, 0x3ff
	v_mul_f32_e32 v8, v49, v7
	v_cvt_pk_bf16_f32 v8, v8, v1
	global_store_short v[4:5], v8, off
	v_mul_f32_e32 v8, v33, v7
	v_cvt_pk_bf16_f32 v8, v8, v1
	global_store_short v[4:5], v8, off offset:64
	v_mul_f32_e32 v8, v17, v7
	v_cvt_pk_bf16_f32 v8, v8, v1
	v_mul_f32_e32 v7, v65, v7
	global_store_short v[4:5], v8, off offset:128
	v_cvt_pk_bf16_f32 v7, v7, v1
	global_store_short v[4:5], v7, off offset:192
	v_or_b32_e32 v4, 0x1000, v0
	v_mov_b32_e32 v5, v1
	v_lshl_add_u64 v[4:5], v[2:3], 0, v[4:5]
	s_waitcnt lgkmcnt(0)
	v_mov_b32_e32 v8, v102
	v_rcp_f32_e32 v7, v8
	s_mov_b32 s59, 0x42b504f3
	v_mul_f32_e32 v8, v50, v7
	v_cvt_pk_bf16_f32 v8, v8, v1
	global_store_short v[4:5], v8, off
	v_mul_f32_e32 v8, v34, v7
	v_cvt_pk_bf16_f32 v8, v8, v1
	global_store_short v[4:5], v8, off offset:64
	v_mul_f32_e32 v8, v18, v7
	v_cvt_pk_bf16_f32 v8, v8, v1
	v_mul_f32_e32 v7, v66, v7
	global_store_short v[4:5], v8, off offset:128
	v_cvt_pk_bf16_f32 v7, v7, v1
	global_store_short v[4:5], v7, off offset:192
	v_or_b32_e32 v4, 0x1800, v0
	v_mov_b32_e32 v5, v1
	v_lshl_add_u64 v[4:5], v[2:3], 0, v[4:5]
	s_waitcnt lgkmcnt(0)
	v_mov_b32_e32 v8, v103
	v_rcp_f32_e32 v7, v8
	s_nop 0
	v_mul_f32_e32 v8, v51, v7
	v_cvt_pk_bf16_f32 v8, v8, v1
	global_store_short v[4:5], v8, off
	v_mul_f32_e32 v8, v35, v7
	v_cvt_pk_bf16_f32 v8, v8, v1
	global_store_short v[4:5], v8, off offset:64
	v_mul_f32_e32 v8, v19, v7
	v_cvt_pk_bf16_f32 v8, v8, v1
	v_mul_f32_e32 v7, v67, v7
	global_store_short v[4:5], v8, off offset:128
	v_cvt_pk_bf16_f32 v7, v7, v1
	global_store_short v[4:5], v7, off offset:192
	v_or_b32_e32 v4, 0x4000, v0
	v_mov_b32_e32 v5, v1
	v_lshl_add_u64 v[4:5], v[2:3], 0, v[4:5]
	s_waitcnt lgkmcnt(0)
	v_mov_b32_e32 v8, v104
	v_rcp_f32_e32 v7, v8
	s_nop 0
	v_mul_f32_e32 v8, v52, v7
	v_cvt_pk_bf16_f32 v8, v8, v1
	global_store_short v[4:5], v8, off
	v_mul_f32_e32 v8, v36, v7
	v_cvt_pk_bf16_f32 v8, v8, v1
	global_store_short v[4:5], v8, off offset:64
	v_mul_f32_e32 v8, v20, v7
	v_cvt_pk_bf16_f32 v8, v8, v1
	v_mul_f32_e32 v7, v68, v7
	global_store_short v[4:5], v8, off offset:128
	v_cvt_pk_bf16_f32 v7, v7, v1
	global_store_short v[4:5], v7, off offset:192
	v_or_b32_e32 v4, 0x4800, v0
	v_mov_b32_e32 v5, v1
	v_lshl_add_u64 v[4:5], v[2:3], 0, v[4:5]
	s_waitcnt lgkmcnt(0)
	v_mov_b32_e32 v8, v105
	v_rcp_f32_e32 v7, v8
	s_nop 0
	v_mul_f32_e32 v8, v53, v7
	v_cvt_pk_bf16_f32 v8, v8, v1
	global_store_short v[4:5], v8, off
	v_mul_f32_e32 v8, v37, v7
	v_cvt_pk_bf16_f32 v8, v8, v1
	global_store_short v[4:5], v8, off offset:64
	v_mul_f32_e32 v8, v21, v7
	v_cvt_pk_bf16_f32 v8, v8, v1
	v_mul_f32_e32 v7, v69, v7
	global_store_short v[4:5], v8, off offset:128
	v_cvt_pk_bf16_f32 v7, v7, v1
	global_store_short v[4:5], v7, off offset:192
	v_or_b32_e32 v4, 0x5000, v0
	v_mov_b32_e32 v5, v1
	v_lshl_add_u64 v[4:5], v[2:3], 0, v[4:5]
	s_waitcnt lgkmcnt(0)
	v_mov_b32_e32 v8, v106
	v_rcp_f32_e32 v7, v8
	s_nop 0
	v_mul_f32_e32 v8, v54, v7
	v_cvt_pk_bf16_f32 v8, v8, v1
	global_store_short v[4:5], v8, off
	v_mul_f32_e32 v8, v38, v7
	v_cvt_pk_bf16_f32 v8, v8, v1
	global_store_short v[4:5], v8, off offset:64
	v_mul_f32_e32 v8, v22, v7
	v_cvt_pk_bf16_f32 v8, v8, v1
	v_mul_f32_e32 v7, v70, v7
	global_store_short v[4:5], v8, off offset:128
	v_cvt_pk_bf16_f32 v7, v7, v1
	global_store_short v[4:5], v7, off offset:192
	v_or_b32_e32 v4, 0x5800, v0
	v_mov_b32_e32 v5, v1
	v_lshl_add_u64 v[4:5], v[2:3], 0, v[4:5]
	s_waitcnt lgkmcnt(0)
; __device__ __forceinline__ u16 f2bf(float x) { return (u16)(cvtpk(x, 0.f) & 0xffffu); }
; __device__ __forceinline__ int crow(int r, int hi) { return (r & 3) + 8 * (r >> 2) + 4 * hi; }
; template <int DQK, int ldq, int ldk, int ldo> ...
;     ...
;   for (int r = 0; r < 16; ++r) { int orow = crow(r, hi); float rl = __builtin_amdgcn_rcpf(li_l[orow]);
; #pragma unroll
;     for (int d0 = 0; d0 < 4; ++d0) Ow[(long)orow * ldo + d0 * 32 + r32] = f2bf(o[d0][r] * rl); }
	v_mov_b32_e32 v8, v107
	v_rcp_f32_e32 v7, v8
	s_nop 0
	v_mul_f32_e32 v8, v55, v7
	v_cvt_pk_bf16_f32 v8, v8, v1
	global_store_short v[4:5], v8, off
	v_mul_f32_e32 v8, v39, v7
	v_cvt_pk_bf16_f32 v8, v8, v1
	global_store_short v[4:5], v8, off offset:64
	v_mul_f32_e32 v8, v23, v7
	v_cvt_pk_bf16_f32 v8, v8, v1
	v_mul_f32_e32 v7, v71, v7
	global_store_short v[4:5], v8, off offset:128
	v_cvt_pk_bf16_f32 v7, v7, v1
	global_store_short v[4:5], v7, off offset:192
	v_or_b32_e32 v4, 0x8000, v0
	v_mov_b32_e32 v5, v1
	v_lshl_add_u64 v[4:5], v[2:3], 0, v[4:5]
	s_waitcnt lgkmcnt(0)
	v_mov_b32_e32 v8, v108
	v_rcp_f32_e32 v7, v8
	s_nop 0
	v_mul_f32_e32 v8, v56, v7
	v_cvt_pk_bf16_f32 v8, v8, v1
	global_store_short v[4:5], v8, off
	v_mul_f32_e32 v8, v40, v7
	v_cvt_pk_bf16_f32 v8, v8, v1
	global_store_short v[4:5], v8, off offset:64
	v_mul_f32_e32 v8, v24, v7
	v_cvt_pk_bf16_f32 v8, v8, v1
	v_mul_f32_e32 v7, v72, v7
	global_store_short v[4:5], v8, off offset:128
	v_cvt_pk_bf16_f32 v7, v7, v1
	global_store_short v[4:5], v7, off offset:192
	v_or_b32_e32 v4, 0x8800, v0
	v_mov_b32_e32 v5, v1
	v_lshl_add_u64 v[4:5], v[2:3], 0, v[4:5]
	s_waitcnt lgkmcnt(0)
	v_mov_b32_e32 v8, v109
	v_rcp_f32_e32 v7, v8
	s_nop 0
	v_mul_f32_e32 v8, v57, v7
	v_cvt_pk_bf16_f32 v8, v8, v1
	global_store_short v[4:5], v8, off
	v_mul_f32_e32 v8, v41, v7
	v_cvt_pk_bf16_f32 v8, v8, v1
	global_store_short v[4:5], v8, off offset:64
	v_mul_f32_e32 v8, v25, v7
	v_cvt_pk_bf16_f32 v8, v8, v1
	v_mul_f32_e32 v7, v73, v7
	global_store_short v[4:5], v8, off offset:128
	v_cvt_pk_bf16_f32 v7, v7, v1
	global_store_short v[4:5], v7, off offset:192
	v_or_b32_e32 v4, 0x9000, v0
	v_mov_b32_e32 v5, v1
	v_lshl_add_u64 v[4:5], v[2:3], 0, v[4:5]
	s_waitcnt lgkmcnt(0)
	v_mov_b32_e32 v8, v110
	v_rcp_f32_e32 v7, v8
	s_nop 0
	v_mul_f32_e32 v8, v58, v7
	v_cvt_pk_bf16_f32 v8, v8, v1
	global_store_short v[4:5], v8, off
	v_mul_f32_e32 v8, v42, v7
	v_cvt_pk_bf16_f32 v8, v8, v1
	global_store_short v[4:5], v8, off offset:64
	v_mul_f32_e32 v8, v26, v7
	v_cvt_pk_bf16_f32 v8, v8, v1
	v_mul_f32_e32 v7, v74, v7
	global_store_short v[4:5], v8, off offset:128
	v_cvt_pk_bf16_f32 v7, v7, v1
	global_store_short v[4:5], v7, off offset:192
	v_or_b32_e32 v4, 0x9800, v0
	v_mov_b32_e32 v5, v1
	v_lshl_add_u64 v[4:5], v[2:3], 0, v[4:5]
	s_waitcnt lgkmcnt(0)
	v_mov_b32_e32 v8, v111
	v_rcp_f32_e32 v7, v8
	s_nop 0
	v_mul_f32_e32 v8, v59, v7
	v_cvt_pk_bf16_f32 v8, v8, v1
	global_store_short v[4:5], v8, off
	v_mul_f32_e32 v8, v43, v7
	v_cvt_pk_bf16_f32 v8, v8, v1
	global_store_short v[4:5], v8, off offset:64
	v_mul_f32_e32 v8, v27, v7
	v_cvt_pk_bf16_f32 v8, v8, v1
	v_mul_f32_e32 v7, v75, v7
	global_store_short v[4:5], v8, off offset:128
	v_cvt_pk_bf16_f32 v7, v7, v1
	global_store_short v[4:5], v7, off offset:192
	v_or_b32_e32 v4, 0xc000, v0
	v_mov_b32_e32 v5, v1
	v_lshl_add_u64 v[4:5], v[2:3], 0, v[4:5]
	s_waitcnt lgkmcnt(0)
	v_mov_b32_e32 v8, v112
	v_rcp_f32_e32 v7, v8
	s_nop 0
	v_mul_f32_e32 v8, v60, v7
	v_cvt_pk_bf16_f32 v8, v8, v1
	global_store_short v[4:5], v8, off
	v_mul_f32_e32 v8, v44, v7
	v_cvt_pk_bf16_f32 v8, v8, v1
	global_store_short v[4:5], v8, off offset:64
	v_mul_f32_e32 v8, v28, v7
	v_cvt_pk_bf16_f32 v8, v8, v1
	v_mul_f32_e32 v7, v76, v7
	global_store_short v[4:5], v8, off offset:128
	v_cvt_pk_bf16_f32 v7, v7, v1
	global_store_short v[4:5], v7, off offset:192
	v_or_b32_e32 v4, 0xc800, v0
	v_mov_b32_e32 v5, v1
	v_lshl_add_u64 v[4:5], v[2:3], 0, v[4:5]
	s_waitcnt lgkmcnt(0)
	v_mov_b32_e32 v8, v113
	v_rcp_f32_e32 v7, v8
	s_nop 0
	v_mul_f32_e32 v8, v61, v7
	v_cvt_pk_bf16_f32 v8, v8, v1
	global_store_short v[4:5], v8, off
	v_mul_f32_e32 v8, v45, v7
	v_cvt_pk_bf16_f32 v8, v8, v1
	global_store_short v[4:5], v8, off offset:64
	v_mul_f32_e32 v8, v29, v7
	v_cvt_pk_bf16_f32 v8, v8, v1
	v_mul_f32_e32 v7, v77, v7
	global_store_short v[4:5], v8, off offset:128
	v_cvt_pk_bf16_f32 v7, v7, v1
	global_store_short v[4:5], v7, off offset:192
	v_or_b32_e32 v4, 0xd000, v0
	v_mov_b32_e32 v5, v1
	v_lshl_add_u64 v[4:5], v[2:3], 0, v[4:5]
	s_waitcnt lgkmcnt(0)
	v_mov_b32_e32 v8, v114
	v_rcp_f32_e32 v7, v8
	v_or_b32_e32 v0, 0xd800, v0
	v_lshl_add_u64 v[2:3], v[2:3], 0, v[0:1]
	v_mul_f32_e32 v8, v62, v7
	v_cvt_pk_bf16_f32 v8, v8, v1
	global_store_short v[4:5], v8, off
	v_mul_f32_e32 v8, v46, v7
	v_cvt_pk_bf16_f32 v8, v8, v1
	global_store_short v[4:5], v8, off offset:64
	v_mul_f32_e32 v8, v30, v7
	v_mul_f32_e32 v7, v78, v7
	v_cvt_pk_bf16_f32 v8, v8, v1
	global_store_short v[4:5], v8, off offset:128
	v_cvt_pk_bf16_f32 v7, v7, v1
	global_store_short v[4:5], v7, off offset:192
	s_waitcnt lgkmcnt(0)
	v_mov_b32_e32 v6, v115
	v_rcp_f32_e32 v6, v6
	s_nop 0
	v_mul_f32_e32 v0, v63, v6
	v_cvt_pk_bf16_f32 v0, v0, v1
	global_store_short v[2:3], v0, off
	v_mul_f32_e32 v0, v47, v6
	v_cvt_pk_bf16_f32 v0, v0, v1
	global_store_short v[2:3], v0, off offset:64
	v_mul_f32_e32 v0, v31, v6
	v_cvt_pk_bf16_f32 v0, v0, v1
	global_store_short v[2:3], v0, off offset:128
	v_mul_f32_e32 v0, v79, v6
	v_cvt_pk_bf16_f32 v0, v0, v1
	global_store_short v[2:3], v0, off offset:192
	s_cbranch_scc1 .LBB0_505

; __device__ __forceinline__ u16 f2bf(float x) { return (u16)(cvtpk(x, 0.f) & 0xffffu); }
; __device__ __forceinline__ float bf2f(u16 x) { return __uint_as_float(((unsigned)x) << 16); }
; __device__ __forceinline__ int opaque_tid() { int t = threadIdx.x; asm volatile("" : "+v"(t)); return t; }
; __device__ __forceinline__ int v_st(int k, int c) { const int kk = (k & ~0xC) | ((k & 4) << 1) | ((k & 8) >> 1); return ((kk >> 3) * 4 + (c >> 5)) * 512 + ((kk & 7) * 32 + (c & 31)) * 2; }
; __device__ __forceinline__ int v_rd_base(int lane) { return ((lane & 3) << 3) | (((lane >> 2) & 3) << 6) | (((lane >> 4) & 1) << 5) | (((lane >> 5) & 1) << 8); }
; template <int DQK, int ldq, int ldk, int ldo> ...
;     ...
;   const int tid = opaque_tid(), wid = __builtin_amdgcn_readfirstlane(tid >> 6), lane = tid & 63, r32 = lane & 31, hi = lane >> 5;
;   char* V_lds = lds; char* K_lds = lds + 2 * SHM_V;
;   float* wsl = (float*)(lds + 2 * SHM_V + 2 * SHM_K) + wid * 64; float* li_l = wsl; float* al_l = wsl + 32;
;   float m_reg = -1e30f, l_reg = 0; f32x16 o[4] = {}; bf16x8 qr[ND];
;   const u16* Qw = Qb + (long)(wid * 32 + r32) * ldq + hi * 8;
; #pragma unroll
;   for (int d0 = 0; d0 < ND; ++d0) qr[d0] = *reinterpret_cast<const bf16x8*>(Qw + d0 * 16);
;   if constexpr (DQK == 192) {
;     const int pos = pos0 + wid * 32 + r32;
; #pragma unroll
;     for (int hh = 0; hh < 2; ++hh) {
;       const float* cp = ropeC + pos * 32 + hh * 16 + hi * 8; const float* sp = ropeS + pos * 32 + hh * 16 + hi * 8;
;       bf16x8 x1 = qr[8 + hh], x2 = qr[10 + hh]; bf16x8 y1, y2;
; #pragma unroll
;       for (int t = 0; t < 8; ++t) {
;         float a = bf2f((u16)x1[t]), b = bf2f((u16)x2[t]), c = cp[t], s = sp[t];
;         y1[t] = (short)f2bf(a * c - b * s); y2[t] = (short)f2bf(a * s + b * c);
;       }
;       qr[8 + hh] = y1; qr[10 + hh] = y2;
;     }
;   }
;   const int sr = tid >> 4, sc = (tid & 15) * 8, vst0 = v_st(sr, sc), vst1 = v_st(32 + sr, sc);
;   const int kr_row = tid >> 3, kr_c = (tid & 7) * 8;
;   const int vb0 = (int)(uintptr_t)V_lds + v_rd_base(lane);
;   struct Stg { bf16x8 vs0, vs1, ks0, ks1, ks2; } sa;
;     ...
;   const unsigned voff0 = sr * ldk + sc, voff1 = (32 + sr) * ldk + sc, kroff = kr_row * 64 + kr_c;
.LBB0_487:
	s_sub_i32 s0, s7, s16
	s_cmp_ge_u32 s7, s16
	s_cselect_b32 s0, s0, s7
	s_xor_b32 s0, s0, s6
	s_sub_i32 s6, s0, s6
	s_ashr_i32 s0, s8, 3
	s_ashr_i32 s1, s0, 31
	v_readlane_b32 s7, v252, 24
	s_lshl_b64 s[58:59], s[0:1], s7
	s_lshl_b32 s7, s6, 8
	s_and_b32 s13, s8, 7
	s_ashr_i32 s0, s7, 31
	s_add_u32 s10, s58, s7
	s_addc_u32 s11, s59, s0
	s_lshl_b64 s[0:1], s[58:59], 12
	v_readlane_b32 s6, v254, 8
	s_add_u32 s8, s6, s0
	v_readlane_b32 s6, v254, 9
	s_addc_u32 s9, s6, s1
	s_lshl_b32 s6, s13, 9
	s_add_u32 s8, s8, s6
	s_mul_i32 s12, s11, 0xc00
	s_mul_hi_u32 s14, s10, 0xc00
	s_addc_u32 s9, s9, 0
	s_add_i32 s14, s14, s12
	s_mul_i32 s12, s10, 0xc00
	v_readlane_b32 s15, v253, 62
	s_add_u32 s12, s15, s12
	v_readlane_b32 s15, v253, 63
	s_addc_u32 s14, s15, s14
	s_mul_i32 s15, s13, 0x180
	s_add_u32 s60, s12, s15
	s_addc_u32 s61, s14, 0
	s_lshl_b64 s[64:65], s[58:59], 7
	v_readlane_b32 s12, v254, 2
	s_add_u32 s80, s12, s64
	v_readlane_b32 s12, v254, 3
	v_mov_b32_e32 v23, v181
	s_barrier
	s_addc_u32 s81, s12, s65
	v_mov_b64_e32 v[2:3], s[60:61]
	v_readfirstlane_b32 s12, v23
	s_and_b32 s14, s12, 0x3fffffc0
	s_lshl_b32 s14, s14, 2
	s_add_i32 s31, s14, 16
	s_ashr_i32 s14, s12, 1
	s_and_b32 s12, s14, 0xffffffe0
	v_mov_b32_e32 v0, s14
	s_movk_i32 s14, 0xffe0
	v_and_b32_e32 v194, 31, v23
	v_bfi_b32 v0, s14, v0, v23
	s_movk_i32 s14, 0xc00
	v_mad_i64_i32 v[2:3], s[58:59], v0, s14, v[2:3]
	v_or_b32_e32 v0, s7, v194
	v_add_lshl_u32 v18, v0, s12, 5
	v_ashrrev_i32_e32 v19, 31, v18
	v_readlane_b32 s14, v253, 38
	v_lshlrev_b64 v[20:21], 2, v[18:19]
	v_readlane_b32 s15, v253, 39
	v_bfe_u32 v193, v23, 5, 1
	v_lshlrev_b32_e32 v182, 4, v193
	v_lshl_add_u64 v[18:19], s[14:15], 0, v[20:21]
	v_readlane_b32 s14, v253, 40
	v_mov_b32_e32 v183, v1
	v_and_b32_e32 v0, 32, v23
	v_readlane_b32 s15, v253, 41
	v_lshl_add_u64 v[6:7], v[2:3], 0, v[182:183]
	v_lshl_add_u64 v[18:19], v[18:19], 0, v[0:1]
	v_lshl_add_u64 v[20:21], s[14:15], 0, v[20:21]
	global_load_dwordx4 v[112:115], v[6:7], off
	global_load_dwordx4 v[116:119], v[6:7], off offset:32
	global_load_dwordx4 v[120:123], v[6:7], off offset:64
	global_load_dwordx4 v[124:127], v[6:7], off offset:96
	global_load_dwordx4 v[128:131], v[6:7], off offset:128
	global_load_dwordx4 v[132:135], v[6:7], off offset:160
	global_load_dwordx4 v[136:139], v[6:7], off offset:192
	global_load_dwordx4 v[140:143], v[6:7], off offset:224
	global_load_dwordx4 v[10:13], v[6:7], off offset:256
	global_load_dwordx4 v[2:5], v[6:7], off offset:288
	global_load_dwordx4 v[14:17], v[6:7], off offset:320
	s_nop 0
	global_load_dwordx4 v[6:9], v[6:7], off offset:352
	v_lshl_add_u64 v[20:21], v[20:21], 0, v[0:1]
	global_load_dwordx4 v[72:75], v[18:19], off
	global_load_dwordx4 v[76:79], v[18:19], off offset:16
	global_load_dwordx4 v[80:83], v[18:19], off offset:64
	global_load_dwordx4 v[84:87], v[18:19], off offset:80
	global_load_dwordx4 v[88:91], v[20:21], off
	global_load_dwordx4 v[92:95], v[20:21], off offset:16
	global_load_dwordx4 v[96:99], v[20:21], off offset:64
	global_load_dwordx4 v[100:103], v[20:21], off offset:80
	v_ashrrev_i32_e32 v64, 4, v23
	v_lshlrev_b32_e32 v65, 3, v23
	v_and_b32_e32 v108, 0x78, v65
	v_lshl_or_b32 v104, v64, 11, v108
	v_add_u32_e32 v109, 32, v64
	v_lshl_or_b32 v106, v109, 11, v108
	v_lshlrev_b32_e32 v104, 1, v104
	v_lshlrev_b32_e32 v106, 1, v106
	v_mov_b32_e32 v105, 0
	v_mov_b32_e32 v107, 0
	v_lshl_add_u64 v[108:109], s[8:9], 0, v[104:105]
	v_lshl_add_u64 v[110:111], s[8:9], 0, v[106:107]
	global_load_dwordx4 v[144:147], v[108:109], off offset:256
	global_load_dwordx4 v[148:151], v[110:111], off offset:256
	global_load_dwordx4 v[152:155], v[108:109], off
	global_load_dwordx4 v[156:159], v[110:111], off
	v_and_b32_e32 v22, 63, v23
	s_add_i32 s31, s31, 0x14000
	v_ashrrev_i32_e32 v69, 3, v23
	v_and_b32_e32 v70, 56, v65
	s_cmp_lg_u32 16, -1
	s_movk_i32 s15, 0x180
	s_movk_i32 s14, 0x70
	s_cselect_b32 s7, 16, 0
	s_add_u32 s60, s8, 0x40100
	s_addc_u32 s61, s9, 0
	v_mad_u32_u24 v200, v194, s15, 16
	v_bitop3_b32 v203, v182, v65, s14 bitop3:0x78
	s_mov_b32 s58, 0
	v_lshl_add_u32 v211, v194, 2, s31
	v_add_u32_e32 v214, 0xe000, v200
	v_mov_b32_e32 v217, 0xf149f2ca
	v_mov_b32_e32 v216, 0
	s_waitcnt vmcnt(0)
	v_lshlrev_b32_e32 v28, 16, v10
	s_waitcnt vmcnt(3)
	v_lshlrev_b32_e32 v29, 16, v14
	s_waitcnt vmcnt(1)
	v_mov_b32_e32 v26, v72
	v_mov_b32_e32 v31, v26
	s_waitcnt vmcnt(0)
	v_mov_b32_e32 v27, v88
	v_pk_mul_f32 v[24:25], v[26:27], v[28:29]
	v_mov_b32_e32 v30, v27
	v_sub_f32_e32 v0, v24, v25
	v_pk_mul_f32 v[26:27], v[30:31], v[28:29]
	v_cvt_pk_bf16_f32 v24, v0, v1
	v_and_b32_e32 v29, 0xffff0000, v10
	v_add_f32_e32 v0, v26, v27
	v_cvt_pk_bf16_f32 v25, v0, v1
	v_and_b32_e32 v28, 0xffff0000, v14
	s_waitcnt vmcnt(0)
	v_mov_b32_e32 v27, v73
	v_mov_b32_e32 v26, v89
	v_pk_mul_f32 v[30:31], v[26:27], v[28:29]
	s_nop 0
	v_sub_f32_e32 v0, v31, v30
	v_mov_b32_e32 v30, v27
	v_mov_b32_e32 v31, v26
	v_pk_mul_f32 v[26:27], v[30:31], v[28:29]
	v_cvt_pk_bf16_f32 v10, v0, v1
	v_lshlrev_b32_e32 v31, 16, v11
	v_add_f32_e32 v0, v26, v27
	v_cvt_pk_bf16_f32 v14, v0, v1
	v_lshlrev_b32_e32 v30, 16, v15
	s_waitcnt vmcnt(1)
	v_mov_b32_e32 v29, v74
	v_mov_b32_e32 v32, v29
	s_waitcnt vmcnt(0)
	v_mov_b32_e32 v28, v90
	v_pk_mul_f32 v[26:27], v[28:29], v[30:31]
	v_mov_b32_e32 v33, v28
	v_sub_f32_e32 v0, v27, v26
	v_pk_mul_f32 v[28:29], v[32:33], v[30:31]
	v_cvt_pk_bf16_f32 v26, v0, v1
	v_and_b32_e32 v31, 0xffff0000, v11
	v_add_f32_e32 v0, v28, v29
	v_cvt_pk_bf16_f32 v27, v0, v1
	v_and_b32_e32 v30, 0xffff0000, v15
	s_waitcnt vmcnt(0)
; __device__ __forceinline__ u16 f2bf(float x) { return (u16)(cvtpk(x, 0.f) & 0xffffu); }
; __device__ __forceinline__ float bf2f(u16 x) { return __uint_as_float(((unsigned)x) << 16); }
; template <int DQK, int ldq, int ldk, int ldo> ...
;     ...
;     for (int hh = 0; hh < 2; ++hh) {
;       const float* cp = ropeC + pos * 32 + hh * 16 + hi * 8; const float* sp = ropeS + pos * 32 + hh * 16 + hi * 8;
;       bf16x8 x1 = qr[8 + hh], x2 = qr[10 + hh]; bf16x8 y1, y2;
; #pragma unroll
;       for (int t = 0; t < 8; ++t) {
;         float a = bf2f((u16)x1[t]), b = bf2f((u16)x2[t]), c = cp[t], s = sp[t];
;         y1[t] = (short)f2bf(a * c - b * s); y2[t] = (short)f2bf(a * s + b * c);
;       }
;       qr[8 + hh] = y1; qr[10 + hh] = y2;
;     }
	v_mov_b32_e32 v29, v75
	v_mov_b32_e32 v28, v91
	v_pk_mul_f32 v[32:33], v[28:29], v[30:31]
	s_nop 0
	v_sub_f32_e32 v0, v33, v32
	v_mov_b32_e32 v32, v29
	v_mov_b32_e32 v33, v28
	v_pk_mul_f32 v[28:29], v[32:33], v[30:31]
	v_cvt_pk_bf16_f32 v11, v0, v1
	v_lshlrev_b32_e32 v33, 16, v12
	v_add_f32_e32 v0, v28, v29
	v_cvt_pk_bf16_f32 v15, v0, v1
	v_lshlrev_b32_e32 v32, 16, v16
	s_waitcnt vmcnt(1)
	v_mov_b32_e32 v31, v76
	v_mov_b32_e32 v34, v31
	s_waitcnt vmcnt(0)
	v_mov_b32_e32 v30, v92
	v_pk_mul_f32 v[28:29], v[30:31], v[32:33]
	v_mov_b32_e32 v35, v30
	v_sub_f32_e32 v0, v29, v28
	v_pk_mul_f32 v[30:31], v[34:35], v[32:33]
	v_cvt_pk_bf16_f32 v28, v0, v1
	v_and_b32_e32 v33, 0xffff0000, v12
	v_add_f32_e32 v0, v30, v31
	v_cvt_pk_bf16_f32 v29, v0, v1
	v_and_b32_e32 v32, 0xffff0000, v16
	s_waitcnt vmcnt(0)
	v_mov_b32_e32 v31, v77
	v_mov_b32_e32 v30, v93
	v_pk_mul_f32 v[34:35], v[30:31], v[32:33]
	s_nop 0
	v_sub_f32_e32 v0, v35, v34
	v_mov_b32_e32 v34, v31
	v_mov_b32_e32 v35, v30
	v_pk_mul_f32 v[30:31], v[34:35], v[32:33]
	v_cvt_pk_bf16_f32 v12, v0, v1
	v_lshlrev_b32_e32 v35, 16, v13
	v_add_f32_e32 v0, v30, v31
	v_cvt_pk_bf16_f32 v16, v0, v1
	v_lshlrev_b32_e32 v34, 16, v17
	s_waitcnt vmcnt(1)
	v_mov_b32_e32 v33, v78
	v_mov_b32_e32 v36, v33
	s_waitcnt vmcnt(0)
	v_mov_b32_e32 v32, v94
	v_pk_mul_f32 v[30:31], v[32:33], v[34:35]
	v_mov_b32_e32 v37, v32
	v_sub_f32_e32 v0, v31, v30
	v_pk_mul_f32 v[32:33], v[36:37], v[34:35]
	v_cvt_pk_bf16_f32 v30, v0, v1
	v_and_b32_e32 v35, 0xffff0000, v13
	v_add_f32_e32 v0, v32, v33
	v_cvt_pk_bf16_f32 v31, v0, v1
	v_and_b32_e32 v34, 0xffff0000, v17
	s_waitcnt vmcnt(0)
	v_mov_b32_e32 v33, v79
	v_mov_b32_e32 v32, v95
	v_pk_mul_f32 v[36:37], v[32:33], v[34:35]
	s_nop 0
	v_sub_f32_e32 v0, v37, v36
	v_mov_b32_e32 v36, v33
	v_mov_b32_e32 v37, v32
	v_pk_mul_f32 v[32:33], v[36:37], v[34:35]
	v_cvt_pk_bf16_f32 v13, v0, v1
	v_lshlrev_b32_e32 v37, 16, v2
	v_add_f32_e32 v0, v32, v33
	v_cvt_pk_bf16_f32 v17, v0, v1
	v_lshlrev_b32_e32 v36, 16, v6
	s_waitcnt vmcnt(1)
	v_mov_b32_e32 v35, v80
	v_mov_b32_e32 v38, v35
	s_waitcnt vmcnt(0)
	v_mov_b32_e32 v34, v96
	v_pk_mul_f32 v[32:33], v[34:35], v[36:37]
	v_mov_b32_e32 v39, v34
	v_sub_f32_e32 v0, v33, v32
	v_pk_mul_f32 v[34:35], v[38:39], v[36:37]
	v_cvt_pk_bf16_f32 v32, v0, v1
	v_and_b32_e32 v39, 0xffff0000, v2
	v_add_f32_e32 v0, v34, v35
	v_cvt_pk_bf16_f32 v33, v0, v1
	v_and_b32_e32 v38, 0xffff0000, v6
	v_and_b32_e32 v2, 0xffff0000, v7
	s_waitcnt vmcnt(1)
	v_mov_b32_e32 v37, v81
	v_mov_b32_e32 v40, v37
	s_waitcnt vmcnt(0)
	v_mov_b32_e32 v36, v97
	v_pk_mul_f32 v[34:35], v[36:37], v[38:39]
	v_mov_b32_e32 v41, v36
	v_sub_f32_e32 v0, v35, v34
	v_pk_mul_f32 v[36:37], v[40:41], v[38:39]
	v_cvt_pk_bf16_f32 v34, v0, v1
	v_lshlrev_b32_e32 v41, 16, v3
	v_add_f32_e32 v0, v36, v37
	v_cvt_pk_bf16_f32 v35, v0, v1
	v_lshlrev_b32_e32 v40, 16, v7
	v_and_b32_e32 v3, 0xffff0000, v3
	s_waitcnt vmcnt(1)
	v_mov_b32_e32 v39, v82
	v_mov_b32_e32 v42, v39
	s_waitcnt vmcnt(0)
	v_mov_b32_e32 v38, v98
	v_pk_mul_f32 v[36:37], v[38:39], v[40:41]
	v_mov_b32_e32 v43, v38
	v_sub_f32_e32 v0, v37, v36
	v_pk_mul_f32 v[38:39], v[42:43], v[40:41]
	v_cvt_pk_bf16_f32 v36, v0, v1
	s_nop 0
	v_add_f32_e32 v0, v38, v39
	v_cvt_pk_bf16_f32 v37, v0, v1
	s_waitcnt vmcnt(0)
	v_mov_b32_e32 v41, v83
	v_mov_b32_e32 v40, v99
	v_pk_mul_f32 v[6:7], v[40:41], v[2:3]
	s_nop 0
	v_sub_f32_e32 v0, v7, v6
	v_mov_b32_e32 v6, v41
	v_mov_b32_e32 v7, v40
	v_pk_mul_f32 v[2:3], v[6:7], v[2:3]
	v_cvt_pk_bf16_f32 v38, v0, v1
	v_lshlrev_b32_e32 v7, 16, v4
	v_add_f32_e32 v0, v2, v3
	v_cvt_pk_bf16_f32 v39, v0, v1
	v_lshlrev_b32_e32 v6, 16, v8
	s_waitcnt vmcnt(1)
	v_mov_b32_e32 v3, v84
	v_mov_b32_e32 v42, v3
	s_waitcnt vmcnt(0)
	v_mov_b32_e32 v2, v100
	v_pk_mul_f32 v[40:41], v[2:3], v[6:7]
	v_mov_b32_e32 v43, v2
	v_sub_f32_e32 v0, v41, v40
	v_pk_mul_f32 v[2:3], v[42:43], v[6:7]
	v_cvt_pk_bf16_f32 v40, v0, v1
	v_and_b32_e32 v7, 0xffff0000, v4
	v_add_f32_e32 v0, v2, v3
	v_cvt_pk_bf16_f32 v41, v0, v1
	v_and_b32_e32 v6, 0xffff0000, v8
	v_and_b32_e32 v4, 0xffff0000, v9
	v_lshl_or_b32 v8, v69, 6, v70
	s_waitcnt vmcnt(0)
	v_mov_b32_e32 v3, v85
	v_mov_b32_e32 v2, v101
	v_pk_mul_f32 v[42:43], v[2:3], v[6:7]
	s_nop 0
	v_sub_f32_e32 v0, v43, v42
	v_mov_b32_e32 v42, v3
	v_mov_b32_e32 v43, v2
	v_pk_mul_f32 v[2:3], v[42:43], v[6:7]
	v_cvt_pk_bf16_f32 v58, v0, v1
	v_lshlrev_b32_e32 v7, 16, v5
	v_add_f32_e32 v0, v2, v3
	v_cvt_pk_bf16_f32 v59, v0, v1
	v_lshlrev_b32_e32 v6, 16, v9
	v_and_b32_e32 v5, 0xffff0000, v5
	v_mov_b32_e32 v9, v1
	v_lshlrev_b64 v[8:9], 1, v[8:9]
	v_lshl_add_u64 v[56:57], s[80:81], 0, v[8:9]
	v_lshl_add_u64 v[184:185], s[64:65], 0, v[8:9]
	v_mov_b32_e32 v8, v1
	v_mov_b32_e32 v9, v1
	s_waitcnt vmcnt(0)
	v_mov_b32_e32 v3, v86
	v_mov_b32_e32 v2, v102
	v_pk_mul_f32 v[42:43], v[2:3], v[6:7]
	s_nop 0
	v_sub_f32_e32 v0, v43, v42
	v_mov_b32_e32 v42, v3
	v_mov_b32_e32 v43, v2
	v_pk_mul_f32 v[2:3], v[42:43], v[6:7]
	v_cvt_pk_bf16_f32 v60, v0, v1
	s_nop 0
	v_add_f32_e32 v0, v2, v3
	v_cvt_pk_bf16_f32 v61, v0, v1
	v_mov_b32_e32 v19, v1
	s_waitcnt vmcnt(0)
; __device__ __forceinline__ int v_st(int k, int c) { const int kk = (k & ~0xC) | ((k & 4) << 1) | ((k & 8) >> 1); return ((kk >> 3) * 4 + (c >> 5)) * 512 + ((kk & 7) * 32 + (c & 31)) * 2; }
; __device__ __forceinline__ int v_rd_base(int lane) { return ((lane & 3) << 3) | (((lane >> 2) & 3) << 6) | (((lane >> 4) & 1) << 5) | (((lane >> 5) & 1) << 8); }
; #define SWRITE(S, b) do { *(bf16x8*)(V_lds + (b) * SHM_V + vst0) = S.vs0; *(bf16x8*)(V_lds + (b) * SHM_V + vst1) = S.vs1; int kc = sc * 2; \
;     *(bf16x8*)(K_lds + (b) * SHM_K + KSWZB(sr, kc)) = S.ks0; *(bf16x8*)(K_lds + (b) * SHM_K + KSWZB(32 + sr, kc)) = S.ks1; \
;     if constexpr (DQK == 192) *(bf16x8*)(K_lds + (b) * SHM_K + KSWZB(kr_row, 256 + kr_c * 2)) = S.ks2; } while (0)
; template <int DQK, int ldq, int ldk, int ldo> ...
;     ...
;   const int sr = tid >> 4, sc = (tid & 15) * 8, vst0 = v_st(sr, sc), vst1 = v_st(32 + sr, sc);
;   const int kr_row = tid >> 3, kr_c = (tid & 7) * 8;
;   const int vb0 = (int)(uintptr_t)V_lds + v_rd_base(lane);
;   struct Stg { bf16x8 vs0, vs1, ks0, ks1, ks2; } sa;
;     ...
;   const unsigned voff0 = sr * ldk + sc, voff1 = (32 + sr) * ldk + sc, kroff = kr_row * 64 + kr_c;
;     ...
;   f32x16 pA0, pA1; float mnA, alA; bf16x8 pa0, pa1, pa2, pa3; const int NT = seq / KVBLK;
;   SLOAD(sa, 0); SWRITE(sa, 0);
;   SLOAD(sa, KVBLK);
;   __syncthreads();
	v_mov_b32_e32 v3, v87
	v_mov_b32_e32 v2, v103
	v_pk_mul_f32 v[6:7], v[2:3], v[4:5]
	s_nop 0
	v_sub_f32_e32 v0, v7, v6
	v_mov_b32_e32 v6, v3
	v_mov_b32_e32 v7, v2
	v_pk_mul_f32 v[2:3], v[6:7], v[4:5]
	v_cvt_pk_bf16_f32 v62, v0, v1
	v_bfe_u32 v4, v65, 5, 2
	v_add_f32_e32 v0, v2, v3
	v_cvt_pk_bf16_f32 v63, v0, v1
	v_and_b32_e32 v0, 0xfffff0, v64
	v_lshlrev_b32_e32 v3, 1, v64
	v_and_or_b32 v0, v3, 8, v0
	v_and_b32_e32 v2, 0x78, v65
	v_lshrrev_b32_e32 v3, 1, v64
	v_lshrrev_b32_e32 v0, 1, v0
	v_and_b32_e32 v5, 3, v64
	v_or_b32_e32 v0, v0, v4
	v_and_or_b32 v3, v3, 4, v5
	v_lshlrev_b32_e32 v66, 1, v2
	v_lshlrev_b32_e32 v0, 9, v0
	v_lshlrev_b32_e32 v3, 6, v3
	v_and_b32_e32 v5, 48, v66
	v_add_u32_e32 v6, 32, v64
	v_or3_b32 v67, v0, v3, v5
	v_and_b32_e32 v0, 0xfffff0, v6
	v_lshlrev_b32_e32 v7, 1, v6
	v_and_or_b32 v0, v7, 8, v0
	v_lshrrev_b32_e32 v0, 1, v0
	v_or_b32_e32 v0, v0, v4
	v_lshlrev_b32_e32 v0, 9, v0
	v_or3_b32 v68, v0, v3, v5
	v_lshlrev_b32_e32 v3, 4, v23
	v_lshlrev_b32_e32 v0, 3, v22
	v_and_b32_e32 v3, 0xc0, v3
	v_lshlrev_b32_e32 v4, 1, v23
	v_and_or_b32 v3, v0, 24, v3
	v_and_b32_e32 v4, 32, v4
	v_and_b32_e32 v0, 0x100, v0
	v_or3_b32 v71, v3, v4, v0
	v_lshl_or_b32 v0, v64, 11, v2
	v_lshl_or_b32 v18, v6, 11, v2
	v_lshlrev_b64 v[6:7], 1, v[0:1]
	v_lshl_add_u64 v[42:43], s[8:9], 0, v[6:7]
	v_mov_b64_e32 v[2:3], v[144:145]
	v_mov_b64_e32 v[4:5], v[146:147]
	v_lshlrev_b64 v[54:55], 1, v[18:19]
	v_lshl_add_u64 v[46:47], s[8:9], 0, v[54:55]
	v_add_u32_e32 v195, 16, v67
	v_mov_b64_e32 v[18:19], v[148:149]
	v_mov_b64_e32 v[20:21], v[150:151]
	s_nop 0
	v_mov_b64_e32 v[42:43], v[152:153]
	v_mov_b64_e32 v[44:45], v[154:155]
	s_nop 0
	v_mov_b64_e32 v[46:47], v[156:157]
	v_mov_b64_e32 v[48:49], v[158:159]
	v_mul_lo_u32 v0, v64, s15
	s_add_u32 s8, s8, 0x40000
	global_load_dwordx4 v[50:53], v[56:57], off
	s_addc_u32 s9, s9, 0
	v_add_u32_e32 v183, s7, v71
	s_addk_i32 s7, 0x4000
	v_add_u32_e32 v215, s7, v71
	s_mov_b32 s7, 0x5040100
	v_add_u32_e32 v196, 16, v68
	v_perm_b32 v172, v14, v25, s7
	v_perm_b32 v173, v15, v27, s7
	s_or_b32 s0, s0, s6
	v_mov_b32_e32 v14, v1
	v_mov_b32_e32 v15, v1
	v_perm_b32 v164, v10, v24, s7
	v_perm_b32 v165, v11, v26, s7
	v_perm_b32 v166, v12, v28, s7
	v_perm_b32 v167, v13, v30, s7
	v_perm_b32 v168, v34, v32, s7
	v_perm_b32 v169, v38, v36, s7
	v_perm_b32 v170, v58, v40, s7
	v_perm_b32 v171, v62, v60, s7
	v_perm_b32 v174, v16, v29, s7
	v_perm_b32 v175, v17, v31, s7
	v_perm_b32 v176, v35, v33, s7
	v_perm_b32 v177, v39, v37, s7
	v_perm_b32 v178, v59, v41, s7
	v_perm_b32 v179, v63, v61, s7
	v_lshl_add_u64 v[186:187], s[0:1], 0, v[54:55]
	v_lshl_add_u64 v[188:189], s[0:1], 0, v[6:7]
	v_mov_b32_e32 v10, v1
	v_mov_b32_e32 v11, v1
	v_mov_b32_e32 v12, v1
	v_mov_b32_e32 v13, v1
	s_waitcnt vmcnt(4)
	ds_write_b128 v195, v[2:5]
	v_lshrrev_b32_e32 v2, 1, v23
	v_bitop3_b32 v2, v66, v2, s14 bitop3:0x78
	v_add3_u32 v197, v2, v0, 16
	v_mul_lo_u32 v0, v69, s15
	v_lshl_or_b32 v2, v70, 1, v191
	v_and_b32_e32 v3, 0x70, v23
	v_xad_u32 v0, v2, v3, v0
	v_lshl_add_u64 v[2:3], s[60:61], 0, v[6:7]
	global_load_dwordx4 v[144:147], v[2:3], off
	v_lshl_add_u64 v[2:3], s[60:61], 0, v[54:55]
	global_load_dwordx4 v[148:151], v[2:3], off
	v_lshl_add_u64 v[2:3], s[8:9], 0, v[6:7]
	global_load_dwordx4 v[152:155], v[2:3], off
	v_lshl_add_u64 v[2:3], s[8:9], 0, v[54:55]
	s_movk_i32 s8, 0x2000
	global_load_dwordx4 v[156:159], v[2:3], off
	v_add_co_u32_e32 v2, vcc, s8, v56
	v_add_u32_e32 v199, 16, v0
	s_nop 0
	v_addc_co_u32_e32 v3, vcc, 0, v57, vcc
	global_load_dwordx4 v[160:163], v[2:3], off
	v_and_b32_e32 v0, 0x70, v65
	s_movk_i32 s8, 0x60
	v_bitop3_b32 v204, v182, v0, s8 bitop3:0x36
	s_movk_i32 s8, 0x80
	v_bitop3_b32 v205, v182, v0, s8 bitop3:0x36
	s_movk_i32 s8, 0xa0
	v_bitop3_b32 v206, v182, v0, s8 bitop3:0x36
	s_movk_i32 s8, 0xc0
	v_bitop3_b32 v207, v182, v0, s8 bitop3:0x36
	s_movk_i32 s8, 0xe0
	v_bitop3_b32 v208, v182, v0, s8 bitop3:0x36
	s_movk_i32 s8, 0x100
	v_bitop3_b32 v209, v182, v0, s8 bitop3:0x36
	s_movk_i32 s8, 0x120
	v_bitop3_b32 v210, v182, v0, s8 bitop3:0x36
	s_movk_i32 s8, 0x140
	v_bitop3_b32 v212, v182, v0, s8 bitop3:0x36
	s_movk_i32 s8, 0x160
	s_waitcnt vmcnt(8)
	ds_write_b128 v196, v[18:21]
	s_waitcnt vmcnt(7)
	ds_write_b128 v197, v[42:45] offset:32768
	s_waitcnt vmcnt(6)
	ds_write_b128 v197, v[46:49] offset:45056
	s_waitcnt vmcnt(5)
	ds_write_b128 v199, v[50:53] offset:32768
	v_bitop3_b32 v201, v182, v0, 32 bitop3:0x36
	v_bitop3_b32 v202, v182, v0, 64 bitop3:0x36
	v_bitop3_b32 v213, v182, v0, s8 bitop3:0x36
	v_cmp_gt_u32_e64 s[8:9], 32, v22
	v_mov_b32_e32 v0, v1
	v_mov_b32_e32 v2, v1
	v_mov_b32_e32 v3, v1
	v_mov_b32_e32 v4, v1
	v_mov_b32_e32 v5, v1
	v_mov_b32_e32 v6, v1
	v_mov_b32_e32 v7, v1
	v_mov_b64_e32 v[62:63], v[14:15]
	v_mov_b64_e32 v[46:47], v[14:15]
	v_mov_b64_e32 v[30:31], v[14:15]
	v_mov_b64_e32 v[78:79], v[14:15]
	v_add_u32_e32 v198, 0x3000, v197
	v_mov_b64_e32 v[60:61], v[12:13]
	v_mov_b64_e32 v[58:59], v[10:11]
	v_mov_b64_e32 v[56:57], v[8:9]
	v_mov_b64_e32 v[54:55], v[6:7]
	v_mov_b64_e32 v[52:53], v[4:5]
	v_mov_b64_e32 v[50:51], v[2:3]
	v_mov_b64_e32 v[48:49], v[0:1]
	v_mov_b64_e32 v[44:45], v[12:13]
	v_mov_b64_e32 v[42:43], v[10:11]
	v_mov_b64_e32 v[40:41], v[8:9]
	v_mov_b64_e32 v[38:39], v[6:7]
	v_mov_b64_e32 v[36:37], v[4:5]
	v_mov_b64_e32 v[34:35], v[2:3]
	v_mov_b64_e32 v[32:33], v[0:1]
	v_mov_b64_e32 v[28:29], v[12:13]
	v_mov_b64_e32 v[26:27], v[10:11]
	v_mov_b64_e32 v[24:25], v[8:9]
	v_mov_b64_e32 v[22:23], v[6:7]
	v_mov_b64_e32 v[20:21], v[4:5]
	v_mov_b64_e32 v[18:19], v[2:3]
	v_mov_b64_e32 v[16:17], v[0:1]
	v_mov_b64_e32 v[76:77], v[12:13]
	v_mov_b64_e32 v[74:75], v[10:11]
	v_mov_b64_e32 v[72:73], v[8:9]
	v_mov_b64_e32 v[70:71], v[6:7]
	v_mov_b64_e32 v[68:69], v[4:5]
	v_mov_b64_e32 v[66:67], v[2:3]
	v_mov_b64_e32 v[64:65], v[0:1]
	s_waitcnt lgkmcnt(0)
	s_barrier

; __device__ __forceinline__ float bflo(unsigned w) { return __uint_as_float(w << 16); }
; __device__ __forceinline__ float bfhi(unsigned w) { return __uint_as_float(w & 0xffff0000u); }
; template <int MODE, bool PRE = false, bool NEXT = false> ...
;     ...
;         const u16* grow = (const u16*)e.aux + (long)row * e.ldaux + cbase;
;         u16* orow = (u16*)e.out + (long)row * e.ldo + cbase;
; #pragma unroll
;         for (int bj = 0; bj < 2; ++bj)
; #pragma unroll
;           for (int n = 0; n < 2; ++n) {
;             const int sidx = ((ai * 4 + m) * 2 + bj) * 2 + n;
;             const u32x2 gw = *reinterpret_cast<const u32x2*>(grow + bj * 128 + n * 16);
;             f32x4 g = {bflo(gw[0]), bfhi(gw[0]), bflo(gw[1]), bfhi(gw[1])};
;             f32x4 mval = g * acc[ai][bj][m][n];
;             u32x2* sp = reinterpret_cast<u32x2*>(e.scr) + sidx * NTHR + tid;
;             if constexpr (MODE != EP_M0) { const u32x2 pw = *sp; mval += f32x4{bflo(pw[0]), bfhi(pw[0]), bflo(pw[1]), bfhi(pw[1])}; }
;             const u32x2 w = {cvtpk(mval[0], mval[1]), cvtpk(mval[2], mval[3])};
;             if constexpr (MODE == EP_M2) *reinterpret_cast<u32x2*>(orow + bj * 128 + n * 16) = w;
;             else *sp = w;
;           }
.LBB0_576:
	v_readlane_b32 s0, v254, 43
	s_add_u32 s0, s0, s6
	v_readlane_b32 s1, v254, 44
	s_addc_u32 s1, s1, s7
	s_add_u32 s0, s0, s12
	v_readfirstlane_b32 s6, v130
	s_addc_u32 s1, s1, s13
	s_ashr_i32 s7, s6, 2
	s_lshr_b32 s6, s6, 1
	s_and_b32 s6, s6, 0x60
	v_lshrrev_b32_e32 v0, 2, v130
	v_and_or_b32 v0, v0, 12, s6
	v_mov_b32_e32 v132, 1.0
	s_andn2_b32 s7, s7, 63
	v_lshlrev_b32_e32 v0, 1, v0
	v_or_b32_e32 v136, s7, v143
	v_lshl_add_u64 v[132:133], s[10:11], 0, v[0:1]
	s_mov_b64 s[6:7], 0x1000
	v_lshl_add_u64 v[134:135], v[132:133], 0, s[6:7]
	v_lshl_add_u64 v[132:133], s[0:1], 0, v[0:1]
	v_readlane_b32 s0, v254, 10
	v_readlane_b32 s1, v254, 11
	s_movk_i32 s6, 0x1800
	v_ashrrev_i32_e32 v137, 31, v136
	v_lshl_add_u64 v[130:131], v[130:131], 3, s[0:1]
	v_mad_i64_i32 v[140:141], s[0:1], v136, s6, v[134:135]
	v_mov_b32_e32 v170, v136
	v_mad_i64_i32 v[168:169], s[98:99], v170, s6, v[134:135]
	global_load_dwordx2 v[192:193], v[168:169], off
	global_load_dwordx2 v[196:197], v[168:169], off offset:32
	global_load_dwordx2 v[200:201], v[168:169], off offset:256
	global_load_dwordx2 v[204:205], v[168:169], off offset:288
	v_add_co_u32_e32 v172, vcc, 0x1000, v130
	s_nop 1
	v_addc_co_u32_e32 v173, vcc, 0, v131, vcc
	global_load_dwordx2 v[194:195], v[172:173], off offset:-4096
	global_load_dwordx2 v[198:199], v[172:173], off
	v_add_co_u32_e32 v172, vcc, 0x3000, v130
	s_nop 1
	v_addc_co_u32_e32 v173, vcc, 0, v131, vcc
	global_load_dwordx2 v[202:203], v[172:173], off offset:-4096
	global_load_dwordx2 v[206:207], v[172:173], off
	v_add_u32_e32 v170, 0x10, v136
	v_mad_i64_i32 v[168:169], s[98:99], v170, s6, v[134:135]
	global_load_dwordx2 v[208:209], v[168:169], off
	global_load_dwordx2 v[212:213], v[168:169], off offset:32
	global_load_dwordx2 v[216:217], v[168:169], off offset:256
	global_load_dwordx2 v[220:221], v[168:169], off offset:288
	v_add_co_u32_e32 v172, vcc, 0x5000, v130
	s_nop 1
	v_addc_co_u32_e32 v173, vcc, 0, v131, vcc
	global_load_dwordx2 v[210:211], v[172:173], off offset:-4096
	global_load_dwordx2 v[214:215], v[172:173], off
	v_add_co_u32_e32 v172, vcc, 0x7000, v130
	s_nop 1
	v_addc_co_u32_e32 v173, vcc, 0, v131, vcc
	global_load_dwordx2 v[218:219], v[172:173], off offset:-4096
	global_load_dwordx2 v[222:223], v[172:173], off
	v_add_u32_e32 v170, 0x20, v136
	v_mad_i64_i32 v[168:169], s[98:99], v170, s6, v[134:135]
	global_load_dwordx2 v[224:225], v[168:169], off
	global_load_dwordx2 v[228:229], v[168:169], off offset:32
	global_load_dwordx2 v[232:233], v[168:169], off offset:256
	global_load_dwordx2 v[236:237], v[168:169], off offset:288
	v_add_co_u32_e32 v172, vcc, 0x9000, v130
	s_nop 1
	v_addc_co_u32_e32 v173, vcc, 0, v131, vcc
	global_load_dwordx2 v[226:227], v[172:173], off offset:-4096
	global_load_dwordx2 v[230:231], v[172:173], off
	v_add_co_u32_e32 v172, vcc, 0xb000, v130
	s_nop 1
	v_addc_co_u32_e32 v173, vcc, 0, v131, vcc
	global_load_dwordx2 v[234:235], v[172:173], off offset:-4096
	global_load_dwordx2 v[238:239], v[172:173], off
	v_add_u32_e32 v170, 0x30, v136
	v_mad_i64_i32 v[168:169], s[98:99], v170, s6, v[134:135]
	global_load_dwordx2 v[240:241], v[168:169], off
	global_load_dwordx2 v[244:245], v[168:169], off offset:32
	global_load_dwordx2 v[248:249], v[168:169], off offset:256
	global_load_dwordx2 v[182:183], v[168:169], off offset:288
	v_add_co_u32_e32 v172, vcc, 0xd000, v130
	s_nop 1
	v_addc_co_u32_e32 v173, vcc, 0, v131, vcc
	global_load_dwordx2 v[242:243], v[172:173], off offset:-4096
	global_load_dwordx2 v[246:247], v[172:173], off
	v_add_co_u32_e32 v172, vcc, 0xf000, v130
	s_nop 1
	v_addc_co_u32_e32 v173, vcc, 0, v131, vcc
	global_load_dwordx2 v[250:251], v[172:173], off offset:-4096
	global_load_dwordx2 v[184:185], v[172:173], off
	s_waitcnt vmcnt(0)
	v_lshlrev_b64 v[138:139], 11, v[136:137]
	s_movk_i32 s0, 0x2000
	v_lshl_add_u64 v[138:139], v[132:133], 0, v[138:139]
	v_mov_b64_e32 v[144:145], v[192:193]
	v_mov_b64_e32 v[148:149], v[194:195]
	v_lshlrev_b32_e32 v146, 16, v144
	v_and_b32_e32 v147, 0xffff0000, v144
	v_lshlrev_b32_e32 v144, 16, v145
	v_and_b32_e32 v145, 0xffff0000, v145
	v_lshlrev_b32_e32 v150, 16, v148
	v_and_b32_e32 v151, 0xffff0000, v148
	v_lshlrev_b32_e32 v148, 16, v149
	v_and_b32_e32 v149, 0xffff0000, v149
	v_pk_fma_f32 v[128:129], v[128:129], v[144:145], v[148:149]
	v_pk_fma_f32 v[126:127], v[126:127], v[146:147], v[150:151]
	v_add_co_u32_e32 v144, vcc, s0, v130
	v_cvt_pk_bf16_f32 v126, v126, v127
	v_cvt_pk_bf16_f32 v127, v128, v129
	global_store_dwordx2 v[138:139], v[126:127], off
	s_nop 0
	v_addc_co_u32_e32 v145, vcc, 0, v131, vcc
	s_movk_i32 s0, 0x4000
	v_mov_b64_e32 v[126:127], v[196:197]
	v_lshlrev_b32_e32 v128, 16, v126
	v_and_b32_e32 v129, 0xffff0000, v126
	v_mov_b64_e32 v[146:147], v[198:199]
	v_lshlrev_b32_e32 v148, 16, v146
	v_and_b32_e32 v149, 0xffff0000, v146
	v_lshlrev_b32_e32 v126, 16, v127
	v_and_b32_e32 v127, 0xffff0000, v127
	v_lshlrev_b32_e32 v146, 16, v147
	v_and_b32_e32 v147, 0xffff0000, v147
	v_pk_fma_f32 v[122:123], v[122:123], v[128:129], v[148:149]
	v_pk_fma_f32 v[124:125], v[124:125], v[126:127], v[146:147]
	v_cvt_pk_bf16_f32 v122, v122, v123
	s_nop 0
	v_cvt_pk_bf16_f32 v123, v124, v125
	global_store_dwordx2 v[138:139], v[122:123], off offset:32
	s_nop 0
	v_mov_b64_e32 v[122:123], v[200:201]
	v_lshlrev_b32_e32 v124, 16, v122
	v_and_b32_e32 v125, 0xffff0000, v122
	v_lshlrev_b32_e32 v122, 16, v123
	v_and_b32_e32 v123, 0xffff0000, v123
	v_mov_b64_e32 v[126:127], v[202:203]
	v_lshlrev_b32_e32 v128, 16, v126
	v_and_b32_e32 v129, 0xffff0000, v126
	v_lshlrev_b32_e32 v126, 16, v127
	v_and_b32_e32 v127, 0xffff0000, v127
	v_pk_fma_f32 v[120:121], v[120:121], v[122:123], v[126:127]
; __device__ __forceinline__ float bflo(unsigned w) { return __uint_as_float(w << 16); }
; __device__ __forceinline__ float bfhi(unsigned w) { return __uint_as_float(w & 0xffff0000u); }
; template <int MODE, bool PRE = false, bool NEXT = false> ...
;     ...
;         const u16* grow = (const u16*)e.aux + (long)row * e.ldaux + cbase;
;         u16* orow = (u16*)e.out + (long)row * e.ldo + cbase;
; #pragma unroll
;         for (int bj = 0; bj < 2; ++bj)
; #pragma unroll
;           for (int n = 0; n < 2; ++n) {
;             const int sidx = ((ai * 4 + m) * 2 + bj) * 2 + n;
;             const u32x2 gw = *reinterpret_cast<const u32x2*>(grow + bj * 128 + n * 16);
;             f32x4 g = {bflo(gw[0]), bfhi(gw[0]), bflo(gw[1]), bfhi(gw[1])};
;             f32x4 mval = g * acc[ai][bj][m][n];
;             u32x2* sp = reinterpret_cast<u32x2*>(e.scr) + sidx * NTHR + tid;
;             if constexpr (MODE != EP_M0) { const u32x2 pw = *sp; mval += f32x4{bflo(pw[0]), bfhi(pw[0]), bflo(pw[1]), bfhi(pw[1])}; }
;             const u32x2 w = {cvtpk(mval[0], mval[1]), cvtpk(mval[2], mval[3])};
;             if constexpr (MODE == EP_M2) *reinterpret_cast<u32x2*>(orow + bj * 128 + n * 16) = w;
;             else *sp = w;
;           }
	v_pk_fma_f32 v[118:119], v[118:119], v[124:125], v[128:129]
	v_add_co_u32_e32 v122, vcc, s0, v130
	v_cvt_pk_bf16_f32 v118, v118, v119
	v_cvt_pk_bf16_f32 v119, v120, v121
	global_store_dwordx2 v[138:139], v[118:119], off offset:256
	s_nop 0
	v_addc_co_u32_e32 v123, vcc, 0, v131, vcc
	v_mov_b64_e32 v[118:119], v[204:205]
	v_lshlrev_b32_e32 v120, 16, v118
	v_and_b32_e32 v121, 0xffff0000, v118
	v_mov_b64_e32 v[124:125], v[206:207]
	v_lshlrev_b32_e32 v126, 16, v124
	v_and_b32_e32 v127, 0xffff0000, v124
	v_pk_fma_f32 v[114:115], v[114:115], v[120:121], v[126:127]
	v_lshlrev_b32_e32 v118, 16, v119
	v_and_b32_e32 v119, 0xffff0000, v119
	v_lshlrev_b32_e32 v124, 16, v125
	v_and_b32_e32 v125, 0xffff0000, v125
	v_cvt_pk_bf16_f32 v114, v114, v115
	v_pk_fma_f32 v[116:117], v[116:117], v[118:119], v[124:125]
	s_nop 0
	v_cvt_pk_bf16_f32 v115, v116, v117
	global_store_dwordx2 v[138:139], v[114:115], off offset:288
	v_or_b32_e32 v114, 16, v136
	v_mad_i64_i32 v[116:117], s[0:1], v114, s6, v[134:135]
	v_ashrrev_i32_e32 v115, 31, v114
	v_lshlrev_b64 v[114:115], 11, v[114:115]
	s_movk_i32 s0, 0x6000
	v_lshl_add_u64 v[114:115], v[132:133], 0, v[114:115]
	v_mov_b64_e32 v[118:119], v[208:209]
	v_lshlrev_b32_e32 v120, 16, v118
	v_and_b32_e32 v121, 0xffff0000, v118
	v_lshlrev_b32_e32 v118, 16, v119
	v_and_b32_e32 v119, 0xffff0000, v119
	v_mov_b64_e32 v[122:123], v[210:211]
	v_lshlrev_b32_e32 v124, 16, v122
	v_and_b32_e32 v125, 0xffff0000, v122
	v_lshlrev_b32_e32 v122, 16, v123
	v_and_b32_e32 v123, 0xffff0000, v123
	v_pk_fma_f32 v[112:113], v[112:113], v[118:119], v[122:123]
	v_pk_fma_f32 v[110:111], v[110:111], v[120:121], v[124:125]
	v_add_co_u32_e32 v118, vcc, s0, v130
	v_cvt_pk_bf16_f32 v110, v110, v111
	v_cvt_pk_bf16_f32 v111, v112, v113
	global_store_dwordx2 v[114:115], v[110:111], off
	s_nop 0
	v_addc_co_u32_e32 v119, vcc, 0, v131, vcc
	s_mov_b32 s0, 0x8000
	v_mov_b64_e32 v[110:111], v[212:213]
	v_lshlrev_b32_e32 v112, 16, v110
	v_and_b32_e32 v113, 0xffff0000, v110
	v_mov_b64_e32 v[120:121], v[214:215]
	v_lshlrev_b32_e32 v122, 16, v120
	v_and_b32_e32 v123, 0xffff0000, v120
	v_lshlrev_b32_e32 v110, 16, v111
	v_and_b32_e32 v111, 0xffff0000, v111
	v_lshlrev_b32_e32 v120, 16, v121
	v_and_b32_e32 v121, 0xffff0000, v121
	v_pk_fma_f32 v[106:107], v[106:107], v[112:113], v[122:123]
	v_pk_fma_f32 v[108:109], v[108:109], v[110:111], v[120:121]
	v_cvt_pk_bf16_f32 v106, v106, v107
	s_nop 0
	v_cvt_pk_bf16_f32 v107, v108, v109
	global_store_dwordx2 v[114:115], v[106:107], off offset:32
	s_nop 0
	v_mov_b64_e32 v[106:107], v[216:217]
	v_lshlrev_b32_e32 v108, 16, v106
	v_and_b32_e32 v109, 0xffff0000, v106
	v_lshlrev_b32_e32 v106, 16, v107
	v_and_b32_e32 v107, 0xffff0000, v107
	v_mov_b64_e32 v[110:111], v[218:219]
	v_lshlrev_b32_e32 v112, 16, v110
	v_and_b32_e32 v113, 0xffff0000, v110
	v_lshlrev_b32_e32 v110, 16, v111
	v_and_b32_e32 v111, 0xffff0000, v111
	v_pk_fma_f32 v[104:105], v[104:105], v[106:107], v[110:111]
	v_pk_fma_f32 v[102:103], v[102:103], v[108:109], v[112:113]
	v_add_co_u32_e32 v106, vcc, s0, v130
	v_cvt_pk_bf16_f32 v102, v102, v103
	v_cvt_pk_bf16_f32 v103, v104, v105
	global_store_dwordx2 v[114:115], v[102:103], off offset:256
	s_nop 0
	v_addc_co_u32_e32 v107, vcc, 0, v131, vcc
	v_mov_b64_e32 v[102:103], v[220:221]
	v_lshlrev_b32_e32 v104, 16, v102
	v_and_b32_e32 v105, 0xffff0000, v102
	v_mov_b64_e32 v[108:109], v[222:223]
	v_lshlrev_b32_e32 v110, 16, v108
	v_and_b32_e32 v111, 0xffff0000, v108
	v_pk_fma_f32 v[98:99], v[98:99], v[104:105], v[110:111]
	v_lshlrev_b32_e32 v102, 16, v103
	v_and_b32_e32 v103, 0xffff0000, v103
	v_lshlrev_b32_e32 v108, 16, v109
	v_and_b32_e32 v109, 0xffff0000, v109
	v_cvt_pk_bf16_f32 v98, v98, v99
	v_pk_fma_f32 v[100:101], v[100:101], v[102:103], v[108:109]
	s_nop 0
	v_cvt_pk_bf16_f32 v99, v100, v101
	global_store_dwordx2 v[114:115], v[98:99], off offset:288
	v_or_b32_e32 v98, 32, v136
	v_mad_i64_i32 v[100:101], s[0:1], v98, s6, v[134:135]
	v_ashrrev_i32_e32 v99, 31, v98
	v_lshlrev_b64 v[98:99], 11, v[98:99]
	s_mov_b32 s0, 0xa000
	v_lshl_add_u64 v[98:99], v[132:133], 0, v[98:99]
	v_mov_b64_e32 v[102:103], v[224:225]
	v_lshlrev_b32_e32 v104, 16, v102
	v_and_b32_e32 v105, 0xffff0000, v102
	v_lshlrev_b32_e32 v102, 16, v103
	v_and_b32_e32 v103, 0xffff0000, v103
	v_mov_b64_e32 v[106:107], v[226:227]
	v_lshlrev_b32_e32 v108, 16, v106
	v_and_b32_e32 v109, 0xffff0000, v106
	v_lshlrev_b32_e32 v106, 16, v107
	v_and_b32_e32 v107, 0xffff0000, v107
	v_pk_fma_f32 v[96:97], v[96:97], v[102:103], v[106:107]
	v_pk_fma_f32 v[94:95], v[94:95], v[104:105], v[108:109]
	v_add_co_u32_e32 v102, vcc, s0, v130
	v_cvt_pk_bf16_f32 v94, v94, v95
	v_cvt_pk_bf16_f32 v95, v96, v97
	global_store_dwordx2 v[98:99], v[94:95], off
	s_nop 0
	v_addc_co_u32_e32 v103, vcc, 0, v131, vcc
	s_mov_b32 s0, 0xc000
	v_mov_b64_e32 v[94:95], v[228:229]
	v_lshlrev_b32_e32 v96, 16, v94
	v_and_b32_e32 v97, 0xffff0000, v94
	v_mov_b64_e32 v[104:105], v[230:231]
	v_lshlrev_b32_e32 v106, 16, v104
	v_and_b32_e32 v107, 0xffff0000, v104
	v_lshlrev_b32_e32 v94, 16, v95
	v_and_b32_e32 v95, 0xffff0000, v95
	v_lshlrev_b32_e32 v104, 16, v105
	v_and_b32_e32 v105, 0xffff0000, v105
	v_pk_fma_f32 v[90:91], v[90:91], v[96:97], v[106:107]
	v_pk_fma_f32 v[92:93], v[92:93], v[94:95], v[104:105]
	v_cvt_pk_bf16_f32 v90, v90, v91
	s_nop 0
	v_cvt_pk_bf16_f32 v91, v92, v93
	global_store_dwordx2 v[98:99], v[90:91], off offset:32
	s_nop 0
	v_mov_b64_e32 v[90:91], v[232:233]
	v_lshlrev_b32_e32 v92, 16, v90
	v_and_b32_e32 v93, 0xffff0000, v90
	v_lshlrev_b32_e32 v90, 16, v91
	v_and_b32_e32 v91, 0xffff0000, v91
	v_mov_b64_e32 v[94:95], v[234:235]
	v_lshlrev_b32_e32 v96, 16, v94
	v_and_b32_e32 v97, 0xffff0000, v94
; __device__ __forceinline__ float bflo(unsigned w) { return __uint_as_float(w << 16); }
; __device__ __forceinline__ float bfhi(unsigned w) { return __uint_as_float(w & 0xffff0000u); }
; template <int MODE, bool PRE = false, bool NEXT = false> ...
;     ...
;         const u16* grow = (const u16*)e.aux + (long)row * e.ldaux + cbase;
;         u16* orow = (u16*)e.out + (long)row * e.ldo + cbase;
; #pragma unroll
;         for (int bj = 0; bj < 2; ++bj)
; #pragma unroll
;           for (int n = 0; n < 2; ++n) {
;             const int sidx = ((ai * 4 + m) * 2 + bj) * 2 + n;
;             const u32x2 gw = *reinterpret_cast<const u32x2*>(grow + bj * 128 + n * 16);
;             f32x4 g = {bflo(gw[0]), bfhi(gw[0]), bflo(gw[1]), bfhi(gw[1])};
;             f32x4 mval = g * acc[ai][bj][m][n];
;             u32x2* sp = reinterpret_cast<u32x2*>(e.scr) + sidx * NTHR + tid;
;             if constexpr (MODE != EP_M0) { const u32x2 pw = *sp; mval += f32x4{bflo(pw[0]), bfhi(pw[0]), bflo(pw[1]), bfhi(pw[1])}; }
;             const u32x2 w = {cvtpk(mval[0], mval[1]), cvtpk(mval[2], mval[3])};
;             if constexpr (MODE == EP_M2) *reinterpret_cast<u32x2*>(orow + bj * 128 + n * 16) = w;
;             else *sp = w;
;           }
	v_lshlrev_b32_e32 v94, 16, v95
	v_and_b32_e32 v95, 0xffff0000, v95
	v_pk_fma_f32 v[88:89], v[88:89], v[90:91], v[94:95]
	v_pk_fma_f32 v[86:87], v[86:87], v[92:93], v[96:97]
	v_add_co_u32_e32 v90, vcc, s0, v130
	v_cvt_pk_bf16_f32 v86, v86, v87
	v_cvt_pk_bf16_f32 v87, v88, v89
	global_store_dwordx2 v[98:99], v[86:87], off offset:256
	s_nop 0
	v_addc_co_u32_e32 v91, vcc, 0, v131, vcc
	v_mov_b64_e32 v[86:87], v[236:237]
	v_lshlrev_b32_e32 v88, 16, v86
	v_and_b32_e32 v89, 0xffff0000, v86
	v_mov_b64_e32 v[92:93], v[238:239]
	v_lshlrev_b32_e32 v94, 16, v92
	v_and_b32_e32 v95, 0xffff0000, v92
	v_pk_fma_f32 v[82:83], v[82:83], v[88:89], v[94:95]
	v_lshlrev_b32_e32 v86, 16, v87
	v_and_b32_e32 v87, 0xffff0000, v87
	v_lshlrev_b32_e32 v92, 16, v93
	v_and_b32_e32 v93, 0xffff0000, v93
	v_cvt_pk_bf16_f32 v82, v82, v83
	v_pk_fma_f32 v[84:85], v[84:85], v[86:87], v[92:93]
	s_nop 0
	v_cvt_pk_bf16_f32 v83, v84, v85
	global_store_dwordx2 v[98:99], v[82:83], off offset:288
	v_or_b32_e32 v82, 48, v136
	v_mad_i64_i32 v[84:85], s[0:1], v82, s6, v[134:135]
	v_ashrrev_i32_e32 v83, 31, v82
	v_lshlrev_b64 v[82:83], 11, v[82:83]
	s_mov_b32 s0, 0xe000
	v_lshl_add_u64 v[82:83], v[132:133], 0, v[82:83]
	v_mov_b64_e32 v[86:87], v[240:241]
	v_lshlrev_b32_e32 v88, 16, v86
	v_and_b32_e32 v89, 0xffff0000, v86
	v_lshlrev_b32_e32 v86, 16, v87
	v_and_b32_e32 v87, 0xffff0000, v87
	v_mov_b64_e32 v[90:91], v[242:243]
	v_lshlrev_b32_e32 v92, 16, v90
	v_and_b32_e32 v93, 0xffff0000, v90
	v_lshlrev_b32_e32 v90, 16, v91
	v_and_b32_e32 v91, 0xffff0000, v91
	v_pk_fma_f32 v[80:81], v[80:81], v[86:87], v[90:91]
	v_pk_fma_f32 v[78:79], v[78:79], v[88:89], v[92:93]
	v_add_co_u32_e32 v86, vcc, s0, v130
	v_cvt_pk_bf16_f32 v78, v78, v79
	v_cvt_pk_bf16_f32 v79, v80, v81
	global_store_dwordx2 v[82:83], v[78:79], off
	s_nop 0
	v_addc_co_u32_e32 v87, vcc, 0, v131, vcc
	s_mov_b32 s0, 0x10000
	v_mov_b64_e32 v[78:79], v[244:245]
	v_lshlrev_b32_e32 v80, 16, v78
	v_and_b32_e32 v81, 0xffff0000, v78
	v_mov_b64_e32 v[88:89], v[246:247]
	v_lshlrev_b32_e32 v90, 16, v88
	v_and_b32_e32 v91, 0xffff0000, v88
	v_lshlrev_b32_e32 v78, 16, v79
	v_and_b32_e32 v79, 0xffff0000, v79
	v_lshlrev_b32_e32 v88, 16, v89
	v_and_b32_e32 v89, 0xffff0000, v89
	v_pk_fma_f32 v[74:75], v[74:75], v[80:81], v[90:91]
	v_pk_fma_f32 v[76:77], v[76:77], v[78:79], v[88:89]
	v_cvt_pk_bf16_f32 v74, v74, v75
	s_nop 0
	v_cvt_pk_bf16_f32 v75, v76, v77
	global_store_dwordx2 v[82:83], v[74:75], off offset:32
	s_nop 0
	v_mov_b64_e32 v[74:75], v[248:249]
	v_lshlrev_b32_e32 v76, 16, v74
	v_and_b32_e32 v77, 0xffff0000, v74
	v_lshlrev_b32_e32 v74, 16, v75
	v_and_b32_e32 v75, 0xffff0000, v75
	v_mov_b64_e32 v[78:79], v[250:251]
	v_lshlrev_b32_e32 v80, 16, v78
	v_and_b32_e32 v81, 0xffff0000, v78
	v_lshlrev_b32_e32 v78, 16, v79
	v_and_b32_e32 v79, 0xffff0000, v79
	v_pk_fma_f32 v[72:73], v[72:73], v[74:75], v[78:79]
	v_pk_fma_f32 v[70:71], v[70:71], v[76:77], v[80:81]
	v_add_co_u32_e32 v74, vcc, s0, v130
	v_cvt_pk_bf16_f32 v70, v70, v71
	v_cvt_pk_bf16_f32 v71, v72, v73
	global_store_dwordx2 v[82:83], v[70:71], off offset:256
	s_nop 0
	v_addc_co_u32_e32 v75, vcc, 0, v131, vcc
	v_mov_b64_e32 v[70:71], v[182:183]
	v_lshlrev_b32_e32 v72, 16, v70
	v_and_b32_e32 v73, 0xffff0000, v70
	v_mov_b64_e32 v[76:77], v[184:185]
	v_lshlrev_b32_e32 v78, 16, v76
	v_and_b32_e32 v79, 0xffff0000, v76
	v_lshlrev_b32_e32 v70, 16, v71
	v_and_b32_e32 v71, 0xffff0000, v71
	v_lshlrev_b32_e32 v76, 16, v77
	v_and_b32_e32 v77, 0xffff0000, v77
	v_pk_fma_f32 v[66:67], v[66:67], v[72:73], v[78:79]
	v_pk_fma_f32 v[68:69], v[68:69], v[70:71], v[76:77]
	v_cvt_pk_bf16_f32 v66, v66, v67
	s_nop 0
	v_cvt_pk_bf16_f32 v67, v68, v69
	global_store_dwordx2 v[82:83], v[66:67], off offset:288
	v_add_u32_e32 v66, 0x80, v136
	v_mad_i64_i32 v[68:69], s[0:1], v66, s6, v[134:135]
	v_add_u32_e32 v170, 0x80, v136
	v_mad_i64_i32 v[168:169], s[98:99], v170, s6, v[134:135]
	global_load_dwordx2 v[192:193], v[168:169], off
	global_load_dwordx2 v[196:197], v[168:169], off offset:32
	global_load_dwordx2 v[200:201], v[168:169], off offset:256
	global_load_dwordx2 v[204:205], v[168:169], off offset:288
	v_add_co_u32_e32 v172, vcc, 0x11000, v130
	s_nop 1
	v_addc_co_u32_e32 v173, vcc, 0, v131, vcc
	global_load_dwordx2 v[194:195], v[172:173], off offset:-4096
	global_load_dwordx2 v[198:199], v[172:173], off
	v_add_co_u32_e32 v172, vcc, 0x13000, v130
	s_nop 1
	v_addc_co_u32_e32 v173, vcc, 0, v131, vcc
	global_load_dwordx2 v[202:203], v[172:173], off offset:-4096
	global_load_dwordx2 v[206:207], v[172:173], off
	v_add_u32_e32 v170, 0x90, v136
	v_mad_i64_i32 v[168:169], s[98:99], v170, s6, v[134:135]
	global_load_dwordx2 v[208:209], v[168:169], off
	global_load_dwordx2 v[212:213], v[168:169], off offset:32
	global_load_dwordx2 v[216:217], v[168:169], off offset:256
	global_load_dwordx2 v[220:221], v[168:169], off offset:288
	v_add_co_u32_e32 v172, vcc, 0x15000, v130
	s_nop 1
	v_addc_co_u32_e32 v173, vcc, 0, v131, vcc
	global_load_dwordx2 v[210:211], v[172:173], off offset:-4096
	global_load_dwordx2 v[214:215], v[172:173], off
	v_add_co_u32_e32 v172, vcc, 0x17000, v130
	s_nop 1
	v_addc_co_u32_e32 v173, vcc, 0, v131, vcc
	global_load_dwordx2 v[218:219], v[172:173], off offset:-4096
	global_load_dwordx2 v[222:223], v[172:173], off
	v_add_u32_e32 v170, 0xa0, v136
	v_mad_i64_i32 v[168:169], s[98:99], v170, s6, v[134:135]
	global_load_dwordx2 v[224:225], v[168:169], off
	global_load_dwordx2 v[228:229], v[168:169], off offset:32
	global_load_dwordx2 v[232:233], v[168:169], off offset:256
	global_load_dwordx2 v[236:237], v[168:169], off offset:288
	v_add_co_u32_e32 v172, vcc, 0x19000, v130
	s_nop 1
	v_addc_co_u32_e32 v173, vcc, 0, v131, vcc
	global_load_dwordx2 v[226:227], v[172:173], off offset:-4096
	global_load_dwordx2 v[230:231], v[172:173], off
	v_add_co_u32_e32 v172, vcc, 0x1b000, v130
	s_nop 1
	v_addc_co_u32_e32 v173, vcc, 0, v131, vcc
	global_load_dwordx2 v[234:235], v[172:173], off offset:-4096
	global_load_dwordx2 v[238:239], v[172:173], off
	v_add_u32_e32 v170, 0xb0, v136
	v_mad_i64_i32 v[168:169], s[98:99], v170, s6, v[134:135]
	global_load_dwordx2 v[240:241], v[168:169], off
	global_load_dwordx2 v[244:245], v[168:169], off offset:32
	global_load_dwordx2 v[248:249], v[168:169], off offset:256
	global_load_dwordx2 v[182:183], v[168:169], off offset:288
	v_add_co_u32_e32 v172, vcc, 0x1d000, v130
	s_nop 1
	v_addc_co_u32_e32 v173, vcc, 0, v131, vcc
	global_load_dwordx2 v[242:243], v[172:173], off offset:-4096
	global_load_dwordx2 v[246:247], v[172:173], off
	v_add_co_u32_e32 v172, vcc, 0x1f000, v130
	s_nop 1
	v_addc_co_u32_e32 v173, vcc, 0, v131, vcc
	global_load_dwordx2 v[250:251], v[172:173], off offset:-4096
	global_load_dwordx2 v[184:185], v[172:173], off
	s_waitcnt vmcnt(0)
; __device__ __forceinline__ float bflo(unsigned w) { return __uint_as_float(w << 16); }
; __device__ __forceinline__ float bfhi(unsigned w) { return __uint_as_float(w & 0xffff0000u); }
; template <int MODE, bool PRE = false, bool NEXT = false> ...
;     ...
;         const u16* grow = (const u16*)e.aux + (long)row * e.ldaux + cbase;
;         u16* orow = (u16*)e.out + (long)row * e.ldo + cbase;
; #pragma unroll
;         for (int bj = 0; bj < 2; ++bj)
; #pragma unroll
;           for (int n = 0; n < 2; ++n) {
;             const int sidx = ((ai * 4 + m) * 2 + bj) * 2 + n;
;             const u32x2 gw = *reinterpret_cast<const u32x2*>(grow + bj * 128 + n * 16);
;             f32x4 g = {bflo(gw[0]), bfhi(gw[0]), bflo(gw[1]), bfhi(gw[1])};
;             f32x4 mval = g * acc[ai][bj][m][n];
;             u32x2* sp = reinterpret_cast<u32x2*>(e.scr) + sidx * NTHR + tid;
;             if constexpr (MODE != EP_M0) { const u32x2 pw = *sp; mval += f32x4{bflo(pw[0]), bfhi(pw[0]), bflo(pw[1]), bfhi(pw[1])}; }
;             const u32x2 w = {cvtpk(mval[0], mval[1]), cvtpk(mval[2], mval[3])};
;             if constexpr (MODE == EP_M2) *reinterpret_cast<u32x2*>(orow + bj * 128 + n * 16) = w;
;             else *sp = w;
;           }
	v_ashrrev_i32_e32 v67, 31, v66
	v_lshlrev_b64 v[66:67], 11, v[66:67]
	s_mov_b32 s0, 0x12000
	v_lshl_add_u64 v[66:67], v[132:133], 0, v[66:67]
	v_mov_b64_e32 v[70:71], v[192:193]
	v_lshlrev_b32_e32 v72, 16, v70
	v_and_b32_e32 v73, 0xffff0000, v70
	v_lshlrev_b32_e32 v70, 16, v71
	v_and_b32_e32 v71, 0xffff0000, v71
	v_mov_b64_e32 v[74:75], v[194:195]
	v_lshlrev_b32_e32 v76, 16, v74
	v_and_b32_e32 v77, 0xffff0000, v74
	v_lshlrev_b32_e32 v74, 16, v75
	v_and_b32_e32 v75, 0xffff0000, v75
	v_pk_fma_f32 v[64:65], v[64:65], v[70:71], v[74:75]
	v_pk_fma_f32 v[62:63], v[62:63], v[72:73], v[76:77]
	v_add_co_u32_e32 v70, vcc, s0, v130
	v_cvt_pk_bf16_f32 v62, v62, v63
	v_cvt_pk_bf16_f32 v63, v64, v65
	global_store_dwordx2 v[66:67], v[62:63], off
	s_nop 0
	v_addc_co_u32_e32 v71, vcc, 0, v131, vcc
	s_mov_b32 s0, 0x14000
	v_mov_b64_e32 v[62:63], v[196:197]
	v_lshlrev_b32_e32 v64, 16, v62
	v_and_b32_e32 v65, 0xffff0000, v62
	v_mov_b64_e32 v[72:73], v[198:199]
	v_lshlrev_b32_e32 v74, 16, v72
	v_and_b32_e32 v75, 0xffff0000, v72
	v_lshlrev_b32_e32 v62, 16, v63
	v_and_b32_e32 v63, 0xffff0000, v63
	v_lshlrev_b32_e32 v72, 16, v73
	v_and_b32_e32 v73, 0xffff0000, v73
	v_pk_fma_f32 v[58:59], v[58:59], v[64:65], v[74:75]
	v_pk_fma_f32 v[60:61], v[60:61], v[62:63], v[72:73]
	v_cvt_pk_bf16_f32 v58, v58, v59
	s_nop 0
	v_cvt_pk_bf16_f32 v59, v60, v61
	global_store_dwordx2 v[66:67], v[58:59], off offset:32
	s_nop 0
	v_mov_b64_e32 v[58:59], v[200:201]
	v_lshlrev_b32_e32 v60, 16, v58
	v_and_b32_e32 v61, 0xffff0000, v58
	v_lshlrev_b32_e32 v58, 16, v59
	v_and_b32_e32 v59, 0xffff0000, v59
	v_mov_b64_e32 v[62:63], v[202:203]
	v_lshlrev_b32_e32 v64, 16, v62
	v_and_b32_e32 v65, 0xffff0000, v62
	v_lshlrev_b32_e32 v62, 16, v63
	v_and_b32_e32 v63, 0xffff0000, v63
	v_pk_fma_f32 v[56:57], v[56:57], v[58:59], v[62:63]
	v_pk_fma_f32 v[54:55], v[54:55], v[60:61], v[64:65]
	v_add_co_u32_e32 v58, vcc, s0, v130
	v_cvt_pk_bf16_f32 v54, v54, v55
	v_cvt_pk_bf16_f32 v55, v56, v57
	global_store_dwordx2 v[66:67], v[54:55], off offset:256
	s_nop 0
	v_addc_co_u32_e32 v59, vcc, 0, v131, vcc
	v_mov_b64_e32 v[54:55], v[204:205]
	v_lshlrev_b32_e32 v56, 16, v54
	v_and_b32_e32 v57, 0xffff0000, v54
	v_mov_b64_e32 v[60:61], v[206:207]
	v_lshlrev_b32_e32 v62, 16, v60
	v_and_b32_e32 v63, 0xffff0000, v60
	v_pk_fma_f32 v[50:51], v[50:51], v[56:57], v[62:63]
	v_lshlrev_b32_e32 v54, 16, v55
	v_and_b32_e32 v55, 0xffff0000, v55
	v_lshlrev_b32_e32 v60, 16, v61
	v_and_b32_e32 v61, 0xffff0000, v61
	v_cvt_pk_bf16_f32 v50, v50, v51
	v_pk_fma_f32 v[52:53], v[52:53], v[54:55], v[60:61]
	s_nop 0
	v_cvt_pk_bf16_f32 v51, v52, v53
	global_store_dwordx2 v[66:67], v[50:51], off offset:288
	v_add_u32_e32 v50, 0x90, v136
	v_mad_i64_i32 v[52:53], s[0:1], v50, s6, v[134:135]
	v_ashrrev_i32_e32 v51, 31, v50
	v_lshlrev_b64 v[50:51], 11, v[50:51]
	s_mov_b32 s0, 0x16000
	v_lshl_add_u64 v[50:51], v[132:133], 0, v[50:51]
	v_mov_b64_e32 v[54:55], v[208:209]
	v_lshlrev_b32_e32 v56, 16, v54
	v_and_b32_e32 v57, 0xffff0000, v54
	v_lshlrev_b32_e32 v54, 16, v55
	v_and_b32_e32 v55, 0xffff0000, v55
	v_mov_b64_e32 v[58:59], v[210:211]
	v_lshlrev_b32_e32 v60, 16, v58
	v_and_b32_e32 v61, 0xffff0000, v58
	v_lshlrev_b32_e32 v58, 16, v59
	v_and_b32_e32 v59, 0xffff0000, v59
	v_pk_fma_f32 v[48:49], v[48:49], v[54:55], v[58:59]
	v_pk_fma_f32 v[46:47], v[46:47], v[56:57], v[60:61]
	v_add_co_u32_e32 v54, vcc, s0, v130
	v_cvt_pk_bf16_f32 v46, v46, v47
	v_cvt_pk_bf16_f32 v47, v48, v49
	global_store_dwordx2 v[50:51], v[46:47], off
	s_nop 0
	v_addc_co_u32_e32 v55, vcc, 0, v131, vcc
	s_mov_b32 s0, 0x18000
	v_mov_b64_e32 v[46:47], v[212:213]
	v_lshlrev_b32_e32 v48, 16, v46
	v_and_b32_e32 v49, 0xffff0000, v46
	v_mov_b64_e32 v[56:57], v[214:215]
	v_lshlrev_b32_e32 v58, 16, v56
	v_and_b32_e32 v59, 0xffff0000, v56
	v_lshlrev_b32_e32 v46, 16, v47
	v_and_b32_e32 v47, 0xffff0000, v47
	v_lshlrev_b32_e32 v56, 16, v57
	v_and_b32_e32 v57, 0xffff0000, v57
	v_pk_fma_f32 v[42:43], v[42:43], v[48:49], v[58:59]
	v_pk_fma_f32 v[44:45], v[44:45], v[46:47], v[56:57]
	v_cvt_pk_bf16_f32 v42, v42, v43
	s_nop 0
	v_cvt_pk_bf16_f32 v43, v44, v45
	global_store_dwordx2 v[50:51], v[42:43], off offset:32
	s_nop 0
	v_mov_b64_e32 v[42:43], v[216:217]
	v_lshlrev_b32_e32 v44, 16, v42
	v_and_b32_e32 v45, 0xffff0000, v42
	v_lshlrev_b32_e32 v42, 16, v43
	v_and_b32_e32 v43, 0xffff0000, v43
	v_mov_b64_e32 v[46:47], v[218:219]
	v_lshlrev_b32_e32 v48, 16, v46
	v_and_b32_e32 v49, 0xffff0000, v46
	v_lshlrev_b32_e32 v46, 16, v47
	v_and_b32_e32 v47, 0xffff0000, v47
	v_pk_fma_f32 v[40:41], v[40:41], v[42:43], v[46:47]
	v_pk_fma_f32 v[38:39], v[38:39], v[44:45], v[48:49]
	v_add_co_u32_e32 v42, vcc, s0, v130
	v_cvt_pk_bf16_f32 v38, v38, v39
	v_cvt_pk_bf16_f32 v39, v40, v41
	global_store_dwordx2 v[50:51], v[38:39], off offset:256
	s_nop 0
	v_addc_co_u32_e32 v43, vcc, 0, v131, vcc
	v_mov_b64_e32 v[38:39], v[220:221]
	v_lshlrev_b32_e32 v40, 16, v38
	v_and_b32_e32 v41, 0xffff0000, v38
	v_mov_b64_e32 v[44:45], v[222:223]
	v_lshlrev_b32_e32 v46, 16, v44
	v_and_b32_e32 v47, 0xffff0000, v44
	v_pk_fma_f32 v[34:35], v[34:35], v[40:41], v[46:47]
	v_lshlrev_b32_e32 v38, 16, v39
	v_and_b32_e32 v39, 0xffff0000, v39
	v_lshlrev_b32_e32 v44, 16, v45
	v_and_b32_e32 v45, 0xffff0000, v45
	v_cvt_pk_bf16_f32 v34, v34, v35
	v_pk_fma_f32 v[36:37], v[36:37], v[38:39], v[44:45]
	s_nop 0
	v_cvt_pk_bf16_f32 v35, v36, v37
	global_store_dwordx2 v[50:51], v[34:35], off offset:288
	v_add_u32_e32 v34, 0xa0, v136
	v_mad_i64_i32 v[36:37], s[0:1], v34, s6, v[134:135]
	v_ashrrev_i32_e32 v35, 31, v34
; __device__ __forceinline__ float bflo(unsigned w) { return __uint_as_float(w << 16); }
; __device__ __forceinline__ float bfhi(unsigned w) { return __uint_as_float(w & 0xffff0000u); }
; template <int MODE, bool PRE = false, bool NEXT = false> ...
;     ...
;         const u16* grow = (const u16*)e.aux + (long)row * e.ldaux + cbase;
;         u16* orow = (u16*)e.out + (long)row * e.ldo + cbase;
; #pragma unroll
;         for (int bj = 0; bj < 2; ++bj)
; #pragma unroll
;           for (int n = 0; n < 2; ++n) {
;             const int sidx = ((ai * 4 + m) * 2 + bj) * 2 + n;
;             const u32x2 gw = *reinterpret_cast<const u32x2*>(grow + bj * 128 + n * 16);
;             f32x4 g = {bflo(gw[0]), bfhi(gw[0]), bflo(gw[1]), bfhi(gw[1])};
;             f32x4 mval = g * acc[ai][bj][m][n];
;             u32x2* sp = reinterpret_cast<u32x2*>(e.scr) + sidx * NTHR + tid;
;             if constexpr (MODE != EP_M0) { const u32x2 pw = *sp; mval += f32x4{bflo(pw[0]), bfhi(pw[0]), bflo(pw[1]), bfhi(pw[1])}; }
;             const u32x2 w = {cvtpk(mval[0], mval[1]), cvtpk(mval[2], mval[3])};
;             if constexpr (MODE == EP_M2) *reinterpret_cast<u32x2*>(orow + bj * 128 + n * 16) = w;
;             else *sp = w;
;           }
	v_lshlrev_b64 v[34:35], 11, v[34:35]
	s_mov_b32 s0, 0x1a000
	v_lshl_add_u64 v[34:35], v[132:133], 0, v[34:35]
	v_mov_b64_e32 v[38:39], v[224:225]
	v_lshlrev_b32_e32 v40, 16, v38
	v_and_b32_e32 v41, 0xffff0000, v38
	v_lshlrev_b32_e32 v38, 16, v39
	v_and_b32_e32 v39, 0xffff0000, v39
	v_mov_b64_e32 v[42:43], v[226:227]
	v_lshlrev_b32_e32 v44, 16, v42
	v_and_b32_e32 v45, 0xffff0000, v42
	v_lshlrev_b32_e32 v42, 16, v43
	v_and_b32_e32 v43, 0xffff0000, v43
	v_pk_fma_f32 v[32:33], v[32:33], v[38:39], v[42:43]
	v_pk_fma_f32 v[30:31], v[30:31], v[40:41], v[44:45]
	v_add_co_u32_e32 v38, vcc, s0, v130
	v_cvt_pk_bf16_f32 v30, v30, v31
	v_cvt_pk_bf16_f32 v31, v32, v33
	global_store_dwordx2 v[34:35], v[30:31], off
	s_nop 0
	v_addc_co_u32_e32 v39, vcc, 0, v131, vcc
	s_mov_b32 s0, 0x1c000
	v_mov_b64_e32 v[30:31], v[228:229]
	v_lshlrev_b32_e32 v32, 16, v30
	v_and_b32_e32 v33, 0xffff0000, v30
	v_mov_b64_e32 v[40:41], v[230:231]
	v_lshlrev_b32_e32 v42, 16, v40
	v_and_b32_e32 v43, 0xffff0000, v40
	v_lshlrev_b32_e32 v30, 16, v31
	v_and_b32_e32 v31, 0xffff0000, v31
	v_lshlrev_b32_e32 v40, 16, v41
	v_and_b32_e32 v41, 0xffff0000, v41
	v_pk_fma_f32 v[26:27], v[26:27], v[32:33], v[42:43]
	v_pk_fma_f32 v[28:29], v[28:29], v[30:31], v[40:41]
	v_cvt_pk_bf16_f32 v26, v26, v27
	s_nop 0
	v_cvt_pk_bf16_f32 v27, v28, v29
	global_store_dwordx2 v[34:35], v[26:27], off offset:32
	s_nop 0
	v_mov_b64_e32 v[26:27], v[232:233]
	v_lshlrev_b32_e32 v28, 16, v26
	v_and_b32_e32 v29, 0xffff0000, v26
	v_lshlrev_b32_e32 v26, 16, v27
	v_and_b32_e32 v27, 0xffff0000, v27
	v_mov_b64_e32 v[30:31], v[234:235]
	v_lshlrev_b32_e32 v32, 16, v30
	v_and_b32_e32 v33, 0xffff0000, v30
	v_lshlrev_b32_e32 v30, 16, v31
	v_and_b32_e32 v31, 0xffff0000, v31
	v_pk_fma_f32 v[24:25], v[24:25], v[26:27], v[30:31]
	v_pk_fma_f32 v[22:23], v[22:23], v[28:29], v[32:33]
	v_add_co_u32_e32 v26, vcc, s0, v130
	v_cvt_pk_bf16_f32 v22, v22, v23
	v_cvt_pk_bf16_f32 v23, v24, v25
	global_store_dwordx2 v[34:35], v[22:23], off offset:256
	s_nop 0
	v_addc_co_u32_e32 v27, vcc, 0, v131, vcc
	v_mov_b64_e32 v[22:23], v[236:237]
	v_lshlrev_b32_e32 v24, 16, v22
	v_and_b32_e32 v25, 0xffff0000, v22
	v_mov_b64_e32 v[28:29], v[238:239]
	v_lshlrev_b32_e32 v30, 16, v28
	v_and_b32_e32 v31, 0xffff0000, v28
	v_pk_fma_f32 v[18:19], v[18:19], v[24:25], v[30:31]
	v_lshlrev_b32_e32 v22, 16, v23
	v_and_b32_e32 v23, 0xffff0000, v23
	v_lshlrev_b32_e32 v28, 16, v29
	v_and_b32_e32 v29, 0xffff0000, v29
	v_cvt_pk_bf16_f32 v18, v18, v19
	v_pk_fma_f32 v[20:21], v[20:21], v[22:23], v[28:29]
	s_nop 0
	v_cvt_pk_bf16_f32 v19, v20, v21
	global_store_dwordx2 v[34:35], v[18:19], off offset:288
	v_add_u32_e32 v18, 0xb0, v136
	v_mad_i64_i32 v[20:21], s[0:1], v18, s6, v[134:135]
	v_ashrrev_i32_e32 v19, 31, v18
	v_lshlrev_b64 v[18:19], 11, v[18:19]
	s_mov_b32 s0, 0x1e000
	v_lshl_add_u64 v[18:19], v[132:133], 0, v[18:19]
	v_mov_b64_e32 v[22:23], v[240:241]
	v_lshlrev_b32_e32 v24, 16, v22
	v_and_b32_e32 v25, 0xffff0000, v22
	v_lshlrev_b32_e32 v22, 16, v23
	v_and_b32_e32 v23, 0xffff0000, v23
	v_mov_b64_e32 v[26:27], v[242:243]
	v_lshlrev_b32_e32 v28, 16, v26
	v_and_b32_e32 v29, 0xffff0000, v26
	v_lshlrev_b32_e32 v26, 16, v27
	v_and_b32_e32 v27, 0xffff0000, v27
	v_pk_fma_f32 v[16:17], v[16:17], v[22:23], v[26:27]
	v_pk_fma_f32 v[14:15], v[14:15], v[24:25], v[28:29]
	v_add_co_u32_e32 v22, vcc, s0, v130
	v_cvt_pk_bf16_f32 v14, v14, v15
	v_cvt_pk_bf16_f32 v15, v16, v17
	global_store_dwordx2 v[18:19], v[14:15], off
	s_nop 0
	v_addc_co_u32_e32 v23, vcc, 0, v131, vcc
	s_mov_b32 s0, 0x1f000
	v_mov_b64_e32 v[14:15], v[244:245]
	v_lshlrev_b32_e32 v16, 16, v14
	v_and_b32_e32 v17, 0xffff0000, v14
	v_mov_b64_e32 v[24:25], v[246:247]
	v_lshlrev_b32_e32 v26, 16, v24
	v_and_b32_e32 v27, 0xffff0000, v24
	v_lshlrev_b32_e32 v14, 16, v15
	v_and_b32_e32 v15, 0xffff0000, v15
	v_lshlrev_b32_e32 v24, 16, v25
	v_and_b32_e32 v25, 0xffff0000, v25
	v_pk_fma_f32 v[10:11], v[10:11], v[16:17], v[26:27]
	v_pk_fma_f32 v[12:13], v[12:13], v[14:15], v[24:25]
	v_cvt_pk_bf16_f32 v10, v10, v11
	s_nop 0
	v_cvt_pk_bf16_f32 v11, v12, v13
	global_store_dwordx2 v[18:19], v[10:11], off offset:32
	s_nop 0
	v_mov_b64_e32 v[10:11], v[248:249]
	v_lshlrev_b32_e32 v12, 16, v10
	v_and_b32_e32 v13, 0xffff0000, v10
	v_lshlrev_b32_e32 v10, 16, v11
	v_and_b32_e32 v11, 0xffff0000, v11
	v_mov_b64_e32 v[14:15], v[250:251]
	v_lshlrev_b32_e32 v16, 16, v14
	v_and_b32_e32 v17, 0xffff0000, v14
	v_lshlrev_b32_e32 v14, 16, v15
	v_and_b32_e32 v15, 0xffff0000, v15
	v_pk_fma_f32 v[8:9], v[8:9], v[10:11], v[14:15]
	v_pk_fma_f32 v[6:7], v[6:7], v[12:13], v[16:17]
	v_add_co_u32_e32 v10, vcc, s0, v130
	v_cvt_pk_bf16_f32 v6, v6, v7
	v_cvt_pk_bf16_f32 v7, v8, v9
	global_store_dwordx2 v[18:19], v[6:7], off offset:256
	s_nop 0
	v_addc_co_u32_e32 v11, vcc, 0, v131, vcc
	s_nop 0
	v_mov_b64_e32 v[6:7], v[182:183]
	v_lshlrev_b32_e32 v8, 16, v6
	v_and_b32_e32 v9, 0xffff0000, v6
	v_mov_b64_e32 v[10:11], v[184:185]
	v_lshlrev_b32_e32 v12, 16, v10
	v_and_b32_e32 v13, 0xffff0000, v10
	v_lshlrev_b32_e32 v6, 16, v7
	v_and_b32_e32 v7, 0xffff0000, v7
	v_lshlrev_b32_e32 v10, 16, v11
	v_and_b32_e32 v11, 0xffff0000, v11
	v_pk_fma_f32 v[2:3], v[2:3], v[8:9], v[12:13]
	v_pk_fma_f32 v[4:5], v[4:5], v[6:7], v[10:11]
	v_cvt_pk_bf16_f32 v2, v2, v3
	s_nop 0
	v_cvt_pk_bf16_f32 v3, v4, v5
	global_store_dwordx2 v[18:19], v[2:3], off offset:288
	v_readlane_b32 s0, v253, 8
	s_add_i32 s30, s30, s0
	s_cmpk_gt_i32 s30, 0x1ff
	s_mov_b32 s59, 0x42b504f3
	v_readlane_b32 s18, v252, 52
	v_readlane_b32 s19, v252, 53
	s_cbranch_scc1 .LBB0_599

; __device__ __forceinline__ float bflo(unsigned w) { return __uint_as_float(w << 16); }
; __device__ __forceinline__ float bfhi(unsigned w) { return __uint_as_float(w & 0xffff0000u); }
; template <bool PRE, bool NEXT> ...
;     ...
;     int tid2 = tid; asm volatile("" : "+v"(tid2));
;     int r0, c0, r1, c1; stage_rc(tid2 * 16, r0, c0); stage_rc(tid2 * 16 + 8192, r1, c1);
;     const unsigned off0_NA = r0 * lda + c0, off1_NA = r1 * lda + c1, off0_NB = r0 * ldb + c0, off1_NB = r1 * ldb + c1;
;     STAGE(SB(0, 0), NB, ldb, 0, 0); STAGE(SA(0, 0), NA, lda, 0, 0);
;     STAGE(SB(0, 1), NB, ldb, HALF, 0); STAGE(SA(0, 1), NA, lda, HALF, 0);
; template <int MODE, bool PRE = false, bool NEXT = false> ...
;     ...
;         const u16* grow = (const u16*)e.aux + (long)row * e.ldaux + cbase;
;         u16* orow = (u16*)e.out + (long)row * e.ldo + cbase;
; #pragma unroll
;         for (int bj = 0; bj < 2; ++bj)
; #pragma unroll
;           for (int n = 0; n < 2; ++n) {
;             const int sidx = ((ai * 4 + m) * 2 + bj) * 2 + n;
;             const u32x2 gw = *reinterpret_cast<const u32x2*>(grow + bj * 128 + n * 16);
;             f32x4 g = {bflo(gw[0]), bfhi(gw[0]), bflo(gw[1]), bfhi(gw[1])};
;             f32x4 mval = g * acc[ai][bj][m][n];
;             u32x2* sp = reinterpret_cast<u32x2*>(e.scr) + sidx * NTHR + tid;
;             if constexpr (MODE != EP_M0) { const u32x2 pw = *sp; mval += f32x4{bflo(pw[0]), bfhi(pw[0]), bflo(pw[1]), bfhi(pw[1])}; }
;             const u32x2 w = {cvtpk(mval[0], mval[1]), cvtpk(mval[2], mval[3])};
;             if constexpr (MODE == EP_M2) *reinterpret_cast<u32x2*>(orow + bj * 128 + n * 16) = w;
;             else *sp = w;
;           }
.LBB0_587:
	v_mov_b32_e32 v0, v130
	s_lshl_b32 s6, s6, 8
	v_ashrrev_i32_e32 v133, 31, v0
	v_lshrrev_b32_e32 v133, 26, v133
	v_lshlrev_b32_e32 v132, 4, v0
	v_add_u32_e32 v133, v0, v133
	v_bfe_i32 v0, v0, 27, 1
	v_lshrrev_b32_e32 v0, 22, v0
	v_add_u32_e32 v0, v132, v0
	v_and_b32_e32 v0, 0xfffffc00, v0
	v_sub_u32_e32 v0, v132, v0
	v_lshrrev_b32_e32 v134, 4, v0
	v_bitop3_b32 v0, v134, v0, 32 bitop3:0x6c
	v_ashrrev_i32_e32 v135, 31, v0
	v_lshrrev_b32_e32 v135, 26, v135
	v_add_u32_e32 v135, v0, v135
	v_lshrrev_b32_e32 v136, 6, v135
	v_and_b32_e32 v135, 0xc0, v135
	v_add_u32_e32 v132, 0x2000, v132
	v_sub_u32_e32 v0, v0, v135
	v_ashrrev_i32_e32 v135, 31, v132
	v_ashrrev_i32_e32 v133, 6, v133
	v_lshrrev_b32_e32 v135, 22, v135
	v_lshlrev_b32_e32 v134, 3, v133
	v_add_u32_e32 v135, v132, v135
	v_and_b32_e32 v134, 0x3ffff0, v134
	v_ashrrev_i32_e32 v135, 10, v135
	v_add_u32_e32 v134, v136, v134
	v_mul_i32_i24_e32 v136, 0x400, v135
	v_sub_u32_e32 v132, v132, v136
	s_ashr_i32 s7, s6, 31
	s_mul_hi_i32 s11, s10, 0x180000
	s_mul_i32 s10, s10, 0x180000
	v_readlane_b32 s12, v254, 0
	v_lshrrev_b32_e32 v136, 4, v132
	s_add_u32 s10, s12, s10
	v_readlane_b32 s12, v254, 1
	v_bitop3_b32 v132, v136, v132, 32 bitop3:0x6c
	s_addc_u32 s11, s12, s11
	s_lshl_b64 s[12:13], s[6:7], 1
	v_ashrrev_i32_e32 v137, 31, v132
	s_add_u32 s10, s10, s12
	v_lshrrev_b32_e32 v137, 26, v137
	s_addc_u32 s11, s11, s13
	s_lshl_b64 s[6:7], s[80:81], 1
	v_readlane_b32 s14, v254, 4
	v_lshlrev_b32_e32 v133, 5, v133
	v_lshlrev_b32_e32 v136, 3, v135
	v_add_u32_e32 v137, v132, v137
	s_add_u32 s80, s14, s6
	v_readlane_b32 s14, v254, 5
	v_and_b32_e32 v133, 32, v133
	v_and_b32_e32 v136, 0x3ffff0, v136
	v_lshrrev_b32_e32 v138, 6, v137
	v_lshlrev_b32_e32 v135, 5, v135
	v_and_b32_e32 v137, 0xc0, v137
	s_addc_u32 s81, s14, s7
	s_lshl_b64 s[58:59], s[64:65], 1
	v_readlane_b32 s14, v252, 49
	v_ashrrev_i16_sdwa v0, v190, sext(v0) dst_sel:DWORD dst_unused:UNUSED_PAD src0_sel:DWORD src1_sel:BYTE_0
	v_add_u32_e32 v136, v138, v136
	v_and_b32_e32 v135, 32, v135
	v_sub_u32_e32 v132, v132, v137
	v_lshl_or_b32 v133, v134, 10, v133
	s_add_u32 s64, s14, s58
	v_readlane_b32 s14, v252, 50
	v_ashrrev_i16_sdwa v132, v190, sext(v132) dst_sel:DWORD dst_unused:UNUSED_PAD src0_sel:DWORD src1_sel:BYTE_0
	v_add_u32_sdwa v0, v133, sext(v0) dst_sel:DWORD dst_unused:UNUSED_PAD src0_sel:DWORD src1_sel:WORD_0
	v_lshl_or_b32 v133, v136, 10, v135
	s_addc_u32 s65, s14, s59
	v_add_u32_sdwa v132, v133, sext(v132) dst_sel:DWORD dst_unused:UNUSED_PAD src0_sel:DWORD src1_sel:WORD_0
	v_lshlrev_b64 v[134:135], 1, v[0:1]
	v_readfirstlane_b32 s14, v143
	v_mov_b32_e32 v133, v1
	v_lshl_add_u64 v[136:137], s[64:65], 0, v[134:135]
	s_mov_b32 m0, s14
	v_lshlrev_b64 v[132:133], 1, v[132:133]
	v_readfirstlane_b32 s14, v144
	global_load_lds_dwordx4 v[136:137], off
	v_lshl_add_u64 v[136:137], s[64:65], 0, v[132:133]
	s_mov_b32 m0, s14
	v_readfirstlane_b32 s14, v145
	global_load_lds_dwordx4 v[136:137], off
	v_lshl_add_u64 v[136:137], s[80:81], 0, v[134:135]
	s_mov_b32 m0, s14
	v_readfirstlane_b32 s14, v146
	s_add_u32 s58, s64, 0x40000
	global_load_lds_dwordx4 v[136:137], off
	v_lshl_add_u64 v[136:137], s[80:81], 0, v[132:133]
	s_mov_b32 m0, s14
	s_addc_u32 s59, s65, 0
	v_readfirstlane_b32 s14, v147
	global_load_lds_dwordx4 v[136:137], off
	v_lshl_add_u64 v[136:137], s[58:59], 0, v[134:135]
	s_mov_b32 m0, s14
	v_readfirstlane_b32 s14, v148
	global_load_lds_dwordx4 v[136:137], off
	v_lshl_add_u64 v[136:137], s[58:59], 0, v[132:133]
	s_add_u32 s58, s80, 0x40000
	s_mov_b32 m0, s14
	s_addc_u32 s59, s81, 0
	v_readfirstlane_b32 s14, v149
	global_load_lds_dwordx4 v[136:137], off
	v_lshl_add_u64 v[134:135], s[58:59], 0, v[134:135]
	s_mov_b32 m0, s14
	v_readfirstlane_b32 s14, v151
	global_load_lds_dwordx4 v[134:135], off
	s_mov_b32 m0, s14
	v_readfirstlane_b32 s14, v130
	s_ashr_i32 s15, s14, 2
	s_lshr_b32 s14, s14, 1
	v_lshl_add_u64 v[132:133], s[58:59], 0, v[132:133]
	s_and_b32 s14, s14, 0x60
	v_lshrrev_b32_e32 v0, 2, v130
	global_load_lds_dwordx4 v[132:133], off
	v_and_or_b32 v0, v0, 12, s14
	v_mov_b32_e32 v132, 1.0
	s_andn2_b32 s15, s15, 63
	v_lshlrev_b32_e32 v0, 1, v0
	v_or_b32_e32 v134, s15, v150
	v_lshl_add_u64 v[132:133], s[10:11], 0, v[0:1]
	s_movk_i32 s22, 0x1800
	v_mad_i64_i32 v[136:137], s[58:59], v134, s22, v[132:133]
	v_mov_b32_e32 v170, v134
	v_mad_i64_i32 v[168:169], s[98:99], v170, s22, v[132:133]
	global_load_dwordx2 v[192:193], v[168:169], off
	global_load_dwordx2 v[194:195], v[168:169], off offset:32
	global_load_dwordx2 v[196:197], v[168:169], off offset:256
	global_load_dwordx2 v[198:199], v[168:169], off offset:288
	v_add_u32_e32 v170, 0x10, v134
	v_mad_i64_i32 v[168:169], s[98:99], v170, s22, v[132:133]
	global_load_dwordx2 v[200:201], v[168:169], off
	global_load_dwordx2 v[202:203], v[168:169], off offset:32
	global_load_dwordx2 v[204:205], v[168:169], off offset:256
	global_load_dwordx2 v[206:207], v[168:169], off offset:288
	v_add_u32_e32 v170, 0x20, v134
	v_mad_i64_i32 v[168:169], s[98:99], v170, s22, v[132:133]
	global_load_dwordx2 v[208:209], v[168:169], off
	global_load_dwordx2 v[210:211], v[168:169], off offset:32
	global_load_dwordx2 v[212:213], v[168:169], off offset:256
	global_load_dwordx2 v[214:215], v[168:169], off offset:288
	v_add_u32_e32 v170, 0x30, v134
	v_mad_i64_i32 v[168:169], s[98:99], v170, s22, v[132:133]
	global_load_dwordx2 v[216:217], v[168:169], off
	global_load_dwordx2 v[218:219], v[168:169], off offset:32
	global_load_dwordx2 v[220:221], v[168:169], off offset:256
	global_load_dwordx2 v[222:223], v[168:169], off offset:288
	v_add_u32_e32 v170, 0x80, v134
	v_mad_i64_i32 v[168:169], s[98:99], v170, s22, v[132:133]
	global_load_dwordx2 v[224:225], v[168:169], off
	global_load_dwordx2 v[226:227], v[168:169], off offset:32
	global_load_dwordx2 v[228:229], v[168:169], off offset:256
	global_load_dwordx2 v[230:231], v[168:169], off offset:288
	v_add_u32_e32 v170, 0x90, v134
	v_mad_i64_i32 v[168:169], s[98:99], v170, s22, v[132:133]
	global_load_dwordx2 v[232:233], v[168:169], off
	global_load_dwordx2 v[234:235], v[168:169], off offset:32
	global_load_dwordx2 v[236:237], v[168:169], off offset:256
	global_load_dwordx2 v[238:239], v[168:169], off offset:288
	v_add_u32_e32 v170, 0xa0, v134
	v_mad_i64_i32 v[168:169], s[98:99], v170, s22, v[132:133]
	global_load_dwordx2 v[240:241], v[168:169], off
	global_load_dwordx2 v[242:243], v[168:169], off offset:32
	global_load_dwordx2 v[244:245], v[168:169], off offset:256
	global_load_dwordx2 v[246:247], v[168:169], off offset:288
	v_add_u32_e32 v170, 0xb0, v134
	v_mad_i64_i32 v[168:169], s[98:99], v170, s22, v[132:133]
	global_load_dwordx2 v[248:249], v[168:169], off
	global_load_dwordx2 v[250:251], v[168:169], off offset:32
	global_load_dwordx2 v[182:183], v[168:169], off offset:256
	global_load_dwordx2 v[184:185], v[168:169], off offset:288
	s_waitcnt vmcnt(0)
; __device__ __forceinline__ float bflo(unsigned w) { return __uint_as_float(w << 16); }
; __device__ __forceinline__ float bfhi(unsigned w) { return __uint_as_float(w & 0xffff0000u); }
; template <int MODE, bool PRE = false, bool NEXT = false> ...
;     ...
;         const u16* grow = (const u16*)e.aux + (long)row * e.ldaux + cbase;
;         u16* orow = (u16*)e.out + (long)row * e.ldo + cbase;
; #pragma unroll
;         for (int bj = 0; bj < 2; ++bj)
; #pragma unroll
;           for (int n = 0; n < 2; ++n) {
;             const int sidx = ((ai * 4 + m) * 2 + bj) * 2 + n;
;             const u32x2 gw = *reinterpret_cast<const u32x2*>(grow + bj * 128 + n * 16);
;             f32x4 g = {bflo(gw[0]), bfhi(gw[0]), bflo(gw[1]), bfhi(gw[1])};
;             f32x4 mval = g * acc[ai][bj][m][n];
;             u32x2* sp = reinterpret_cast<u32x2*>(e.scr) + sidx * NTHR + tid;
;             if constexpr (MODE != EP_M0) { const u32x2 pw = *sp; mval += f32x4{bflo(pw[0]), bfhi(pw[0]), bflo(pw[1]), bfhi(pw[1])}; }
;             const u32x2 w = {cvtpk(mval[0], mval[1]), cvtpk(mval[2], mval[3])};
;             if constexpr (MODE == EP_M2) *reinterpret_cast<u32x2*>(orow + bj * 128 + n * 16) = w;
;             else *sp = w;
;           }
	v_readlane_b32 s14, v254, 10
	v_readlane_b32 s15, v254, 11
	v_or_b32_e32 v0, 16, v134
	v_mov_b64_e32 v[138:139], v[192:193]
	v_lshlrev_b32_e32 v140, 16, v138
	v_and_b32_e32 v141, 0xffff0000, v138
	v_lshl_add_u64 v[130:131], v[130:131], 3, s[14:15]
	v_lshlrev_b32_e32 v138, 16, v139
	v_and_b32_e32 v139, 0xffff0000, v139
	v_pk_mul_f32 v[126:127], v[126:127], v[140:141]
	v_pk_mul_f32 v[128:129], v[128:129], v[138:139]
	v_cvt_pk_bf16_f32 v126, v126, v127
	s_movk_i32 s14, 0x2000
	v_cvt_pk_bf16_f32 v127, v128, v129
	global_store_dwordx2 v[130:131], v[126:127], off
	v_add_co_u32_e32 v128, vcc, s14, v130
	s_movk_i32 s14, 0x4000
	s_nop 0
	v_addc_co_u32_e32 v129, vcc, 0, v131, vcc
	v_mov_b64_e32 v[126:127], v[194:195]
	v_lshlrev_b32_e32 v138, 16, v126
	v_and_b32_e32 v139, 0xffff0000, v126
	v_lshlrev_b32_e32 v126, 16, v127
	v_and_b32_e32 v127, 0xffff0000, v127
	v_pk_mul_f32 v[118:119], v[118:119], v[138:139]
	v_pk_mul_f32 v[120:121], v[120:121], v[126:127]
	v_cvt_pk_bf16_f32 v118, v118, v119
	s_nop 0
	v_cvt_pk_bf16_f32 v119, v120, v121
	global_store_dwordx2 v[128:129], v[118:119], off offset:-4096
	v_mov_b64_e32 v[118:119], v[196:197]
	v_lshlrev_b32_e32 v120, 16, v118
	v_and_b32_e32 v121, 0xffff0000, v118
	v_lshlrev_b32_e32 v118, 16, v119
	v_and_b32_e32 v119, 0xffff0000, v119
	v_pk_mul_f32 v[120:121], v[122:123], v[120:121]
	v_pk_mul_f32 v[118:119], v[124:125], v[118:119]
	v_cvt_pk_bf16_f32 v120, v120, v121
	v_mad_i64_i32 v[122:123], s[58:59], v0, s22, v[132:133]
	v_cvt_pk_bf16_f32 v121, v118, v119
	global_store_dwordx2 v[128:129], v[120:121], off
	v_add_co_u32_e32 v120, vcc, s14, v130
	s_movk_i32 s14, 0x6000
	s_nop 0
	v_addc_co_u32_e32 v121, vcc, 0, v131, vcc
	v_or_b32_e32 v0, 32, v134
	v_mov_b64_e32 v[118:119], v[198:199]
	v_lshlrev_b32_e32 v124, 16, v118
	v_and_b32_e32 v125, 0xffff0000, v118
	v_lshlrev_b32_e32 v118, 16, v119
	v_and_b32_e32 v119, 0xffff0000, v119
	v_pk_mul_f32 v[114:115], v[114:115], v[124:125]
	v_pk_mul_f32 v[116:117], v[116:117], v[118:119]
	v_cvt_pk_bf16_f32 v114, v114, v115
	s_nop 0
	v_cvt_pk_bf16_f32 v115, v116, v117
	global_store_dwordx2 v[120:121], v[114:115], off offset:-4096
	v_mov_b64_e32 v[114:115], v[200:201]
	v_lshlrev_b32_e32 v116, 16, v114
	v_and_b32_e32 v117, 0xffff0000, v114
	v_lshlrev_b32_e32 v114, 16, v115
	v_and_b32_e32 v115, 0xffff0000, v115
	v_pk_mul_f32 v[110:111], v[110:111], v[116:117]
	v_pk_mul_f32 v[112:113], v[112:113], v[114:115]
	v_cvt_pk_bf16_f32 v110, v110, v111
	s_nop 0
	v_cvt_pk_bf16_f32 v111, v112, v113
	global_store_dwordx2 v[120:121], v[110:111], off
	v_add_co_u32_e32 v112, vcc, s14, v130
	s_mov_b32 s14, 0x8000
	s_nop 0
	v_addc_co_u32_e32 v113, vcc, 0, v131, vcc
	v_mov_b64_e32 v[110:111], v[202:203]
	v_lshlrev_b32_e32 v114, 16, v110
	v_and_b32_e32 v115, 0xffff0000, v110
	v_lshlrev_b32_e32 v110, 16, v111
	v_and_b32_e32 v111, 0xffff0000, v111
	v_pk_mul_f32 v[102:103], v[102:103], v[114:115]
	v_pk_mul_f32 v[104:105], v[104:105], v[110:111]
	v_cvt_pk_bf16_f32 v102, v102, v103
	s_nop 0
	v_cvt_pk_bf16_f32 v103, v104, v105
	global_store_dwordx2 v[112:113], v[102:103], off offset:-4096
	v_mov_b64_e32 v[102:103], v[204:205]
	v_lshlrev_b32_e32 v104, 16, v102
	v_and_b32_e32 v105, 0xffff0000, v102
	v_lshlrev_b32_e32 v102, 16, v103
	v_and_b32_e32 v103, 0xffff0000, v103
	v_pk_mul_f32 v[104:105], v[106:107], v[104:105]
	v_pk_mul_f32 v[102:103], v[108:109], v[102:103]
	v_cvt_pk_bf16_f32 v104, v104, v105
	v_mad_i64_i32 v[106:107], s[58:59], v0, s22, v[132:133]
	v_cvt_pk_bf16_f32 v105, v102, v103
	global_store_dwordx2 v[112:113], v[104:105], off
	v_add_co_u32_e32 v104, vcc, s14, v130
	s_mov_b32 s14, 0xa000
	s_nop 0
	v_addc_co_u32_e32 v105, vcc, 0, v131, vcc
	v_or_b32_e32 v0, 48, v134
	v_mov_b64_e32 v[102:103], v[206:207]
	v_lshlrev_b32_e32 v108, 16, v102
	v_and_b32_e32 v109, 0xffff0000, v102
	v_lshlrev_b32_e32 v102, 16, v103
	v_and_b32_e32 v103, 0xffff0000, v103
	v_pk_mul_f32 v[98:99], v[98:99], v[108:109]
	v_pk_mul_f32 v[100:101], v[100:101], v[102:103]
	v_cvt_pk_bf16_f32 v98, v98, v99
	s_nop 0
	v_cvt_pk_bf16_f32 v99, v100, v101
	global_store_dwordx2 v[104:105], v[98:99], off offset:-4096
	v_mov_b64_e32 v[98:99], v[208:209]
	v_lshlrev_b32_e32 v100, 16, v98
	v_and_b32_e32 v101, 0xffff0000, v98
	v_lshlrev_b32_e32 v98, 16, v99
	v_and_b32_e32 v99, 0xffff0000, v99
	v_pk_mul_f32 v[94:95], v[94:95], v[100:101]
	v_pk_mul_f32 v[96:97], v[96:97], v[98:99]
	v_cvt_pk_bf16_f32 v94, v94, v95
	s_nop 0
	v_cvt_pk_bf16_f32 v95, v96, v97
	global_store_dwordx2 v[104:105], v[94:95], off
	v_add_co_u32_e32 v96, vcc, s14, v130
	s_mov_b32 s14, 0xc000
	s_nop 0
	v_addc_co_u32_e32 v97, vcc, 0, v131, vcc
	v_mov_b64_e32 v[94:95], v[210:211]
	v_lshlrev_b32_e32 v98, 16, v94
	v_and_b32_e32 v99, 0xffff0000, v94
	v_lshlrev_b32_e32 v94, 16, v95
	v_and_b32_e32 v95, 0xffff0000, v95
	v_pk_mul_f32 v[86:87], v[86:87], v[98:99]
	v_pk_mul_f32 v[88:89], v[88:89], v[94:95]
	v_cvt_pk_bf16_f32 v86, v86, v87
	s_nop 0
	v_cvt_pk_bf16_f32 v87, v88, v89
	global_store_dwordx2 v[96:97], v[86:87], off offset:-4096
	v_mov_b64_e32 v[86:87], v[212:213]
	v_lshlrev_b32_e32 v88, 16, v86
	v_and_b32_e32 v89, 0xffff0000, v86
	v_lshlrev_b32_e32 v86, 16, v87
	v_and_b32_e32 v87, 0xffff0000, v87
	v_pk_mul_f32 v[88:89], v[90:91], v[88:89]
	v_pk_mul_f32 v[86:87], v[92:93], v[86:87]
	v_cvt_pk_bf16_f32 v88, v88, v89
	v_mad_i64_i32 v[90:91], s[58:59], v0, s22, v[132:133]
	v_cvt_pk_bf16_f32 v89, v86, v87
	global_store_dwordx2 v[96:97], v[88:89], off
	v_add_co_u32_e32 v88, vcc, s14, v130
	s_mov_b32 s14, 0xe000
	s_nop 0
	v_addc_co_u32_e32 v89, vcc, 0, v131, vcc
	v_mov_b64_e32 v[86:87], v[214:215]
	v_lshlrev_b32_e32 v92, 16, v86
	v_and_b32_e32 v93, 0xffff0000, v86
	v_lshlrev_b32_e32 v86, 16, v87
; __device__ __forceinline__ float bflo(unsigned w) { return __uint_as_float(w << 16); }
; __device__ __forceinline__ float bfhi(unsigned w) { return __uint_as_float(w & 0xffff0000u); }
; template <int MODE, bool PRE = false, bool NEXT = false> ...
;     ...
;         const u16* grow = (const u16*)e.aux + (long)row * e.ldaux + cbase;
;         u16* orow = (u16*)e.out + (long)row * e.ldo + cbase;
; #pragma unroll
;         for (int bj = 0; bj < 2; ++bj)
; #pragma unroll
;           for (int n = 0; n < 2; ++n) {
;             const int sidx = ((ai * 4 + m) * 2 + bj) * 2 + n;
;             const u32x2 gw = *reinterpret_cast<const u32x2*>(grow + bj * 128 + n * 16);
;             f32x4 g = {bflo(gw[0]), bfhi(gw[0]), bflo(gw[1]), bfhi(gw[1])};
;             f32x4 mval = g * acc[ai][bj][m][n];
;             u32x2* sp = reinterpret_cast<u32x2*>(e.scr) + sidx * NTHR + tid;
;             if constexpr (MODE != EP_M0) { const u32x2 pw = *sp; mval += f32x4{bflo(pw[0]), bfhi(pw[0]), bflo(pw[1]), bfhi(pw[1])}; }
;             const u32x2 w = {cvtpk(mval[0], mval[1]), cvtpk(mval[2], mval[3])};
;             if constexpr (MODE == EP_M2) *reinterpret_cast<u32x2*>(orow + bj * 128 + n * 16) = w;
;             else *sp = w;
;           }
	v_and_b32_e32 v87, 0xffff0000, v87
	v_pk_mul_f32 v[82:83], v[82:83], v[92:93]
	v_pk_mul_f32 v[84:85], v[84:85], v[86:87]
	v_cvt_pk_bf16_f32 v82, v82, v83
	s_nop 0
	v_cvt_pk_bf16_f32 v83, v84, v85
	global_store_dwordx2 v[88:89], v[82:83], off offset:-4096
	v_mov_b64_e32 v[82:83], v[216:217]
	v_lshlrev_b32_e32 v84, 16, v82
	v_and_b32_e32 v85, 0xffff0000, v82
	v_lshlrev_b32_e32 v82, 16, v83
	v_and_b32_e32 v83, 0xffff0000, v83
	v_pk_mul_f32 v[78:79], v[78:79], v[84:85]
	v_pk_mul_f32 v[80:81], v[80:81], v[82:83]
	v_cvt_pk_bf16_f32 v78, v78, v79
	s_nop 0
	v_cvt_pk_bf16_f32 v79, v80, v81
	global_store_dwordx2 v[88:89], v[78:79], off
	v_add_co_u32_e32 v80, vcc, s14, v130
	s_mov_b32 s14, 0x10000
	s_nop 0
	v_addc_co_u32_e32 v81, vcc, 0, v131, vcc
	v_mov_b64_e32 v[78:79], v[218:219]
	v_lshlrev_b32_e32 v82, 16, v78
	v_and_b32_e32 v83, 0xffff0000, v78
	v_lshlrev_b32_e32 v78, 16, v79
	v_and_b32_e32 v79, 0xffff0000, v79
	v_pk_mul_f32 v[70:71], v[70:71], v[82:83]
	v_pk_mul_f32 v[72:73], v[72:73], v[78:79]
	v_cvt_pk_bf16_f32 v70, v70, v71
	s_nop 0
	v_cvt_pk_bf16_f32 v71, v72, v73
	global_store_dwordx2 v[80:81], v[70:71], off offset:-4096
	v_mov_b64_e32 v[70:71], v[220:221]
	v_lshlrev_b32_e32 v72, 16, v70
	v_and_b32_e32 v73, 0xffff0000, v70
	v_lshlrev_b32_e32 v70, 16, v71
	v_and_b32_e32 v71, 0xffff0000, v71
	v_pk_mul_f32 v[72:73], v[74:75], v[72:73]
	v_pk_mul_f32 v[70:71], v[76:77], v[70:71]
	v_cvt_pk_bf16_f32 v72, v72, v73
	s_nop 0
	v_cvt_pk_bf16_f32 v73, v70, v71
	global_store_dwordx2 v[80:81], v[72:73], off
	v_mov_b64_e32 v[70:71], v[222:223]
	v_lshlrev_b32_e32 v72, 16, v70
	v_and_b32_e32 v73, 0xffff0000, v70
	v_lshlrev_b32_e32 v70, 16, v71
	v_and_b32_e32 v71, 0xffff0000, v71
	v_pk_mul_f32 v[68:69], v[68:69], v[70:71]
	v_pk_mul_f32 v[66:67], v[66:67], v[72:73]
	s_nop 0
	v_cvt_pk_bf16_f32 v66, v66, v67
	v_cvt_pk_bf16_f32 v67, v68, v69
	v_add_co_u32_e32 v68, vcc, s14, v130
	s_nop 1
	v_addc_co_u32_e32 v69, vcc, 0, v131, vcc
	global_store_dwordx2 v[68:69], v[66:67], off offset:-4096
	v_add_u32_e32 v0, 0x80, v134
	v_mad_i64_i32 v[66:67], s[58:59], v0, s22, v[132:133]
	s_mov_b32 s14, 0x12000
	v_add_u32_e32 v0, 0x90, v134
	v_mov_b64_e32 v[70:71], v[224:225]
	v_lshlrev_b32_e32 v72, 16, v70
	v_and_b32_e32 v73, 0xffff0000, v70
	v_lshlrev_b32_e32 v70, 16, v71
	v_and_b32_e32 v71, 0xffff0000, v71
	v_pk_mul_f32 v[62:63], v[62:63], v[72:73]
	v_pk_mul_f32 v[64:65], v[64:65], v[70:71]
	v_cvt_pk_bf16_f32 v62, v62, v63
	s_nop 0
	v_cvt_pk_bf16_f32 v63, v64, v65
	global_store_dwordx2 v[68:69], v[62:63], off
	v_add_co_u32_e32 v64, vcc, s14, v130
	s_mov_b32 s14, 0x14000
	s_nop 0
	v_addc_co_u32_e32 v65, vcc, 0, v131, vcc
	v_mov_b64_e32 v[62:63], v[226:227]
	v_lshlrev_b32_e32 v68, 16, v62
	v_and_b32_e32 v69, 0xffff0000, v62
	v_lshlrev_b32_e32 v62, 16, v63
	v_and_b32_e32 v63, 0xffff0000, v63
	v_pk_mul_f32 v[58:59], v[58:59], v[68:69]
	v_pk_mul_f32 v[60:61], v[60:61], v[62:63]
	v_cvt_pk_bf16_f32 v58, v58, v59
	s_nop 0
	v_cvt_pk_bf16_f32 v59, v60, v61
	global_store_dwordx2 v[64:65], v[58:59], off offset:-4096
	v_mov_b64_e32 v[58:59], v[228:229]
	v_lshlrev_b32_e32 v60, 16, v58
	v_and_b32_e32 v61, 0xffff0000, v58
	v_lshlrev_b32_e32 v58, 16, v59
	v_and_b32_e32 v59, 0xffff0000, v59
	v_pk_mul_f32 v[54:55], v[54:55], v[60:61]
	v_pk_mul_f32 v[56:57], v[56:57], v[58:59]
	v_cvt_pk_bf16_f32 v54, v54, v55
	v_mad_i64_i32 v[58:59], s[58:59], v0, s22, v[132:133]
	v_cvt_pk_bf16_f32 v55, v56, v57
	global_store_dwordx2 v[64:65], v[54:55], off
	v_add_co_u32_e32 v56, vcc, s14, v130
	s_mov_b32 s14, 0x16000
	s_nop 0
	v_addc_co_u32_e32 v57, vcc, 0, v131, vcc
	v_add_u32_e32 v0, 0xa0, v134
	v_mov_b64_e32 v[54:55], v[230:231]
	v_lshlrev_b32_e32 v60, 16, v54
	v_and_b32_e32 v61, 0xffff0000, v54
	v_lshlrev_b32_e32 v54, 16, v55
	v_and_b32_e32 v55, 0xffff0000, v55
	v_pk_mul_f32 v[50:51], v[50:51], v[60:61]
	v_pk_mul_f32 v[52:53], v[52:53], v[54:55]
	v_cvt_pk_bf16_f32 v50, v50, v51
	s_nop 0
	v_cvt_pk_bf16_f32 v51, v52, v53
	global_store_dwordx2 v[56:57], v[50:51], off offset:-4096
	v_mov_b64_e32 v[50:51], v[232:233]
	v_lshlrev_b32_e32 v52, 16, v50
	v_and_b32_e32 v53, 0xffff0000, v50
	v_lshlrev_b32_e32 v50, 16, v51
	v_and_b32_e32 v51, 0xffff0000, v51
	v_pk_mul_f32 v[46:47], v[46:47], v[52:53]
	v_pk_mul_f32 v[48:49], v[48:49], v[50:51]
	v_cvt_pk_bf16_f32 v46, v46, v47
	s_nop 0
	v_cvt_pk_bf16_f32 v47, v48, v49
	global_store_dwordx2 v[56:57], v[46:47], off
	v_add_co_u32_e32 v48, vcc, s14, v130
	s_mov_b32 s14, 0x18000
	s_nop 0
	v_addc_co_u32_e32 v49, vcc, 0, v131, vcc
	v_mov_b64_e32 v[46:47], v[234:235]
	v_lshlrev_b32_e32 v50, 16, v46
	v_and_b32_e32 v51, 0xffff0000, v46
	v_lshlrev_b32_e32 v46, 16, v47
	v_and_b32_e32 v47, 0xffff0000, v47
	v_pk_mul_f32 v[42:43], v[42:43], v[50:51]
	v_pk_mul_f32 v[44:45], v[44:45], v[46:47]
; __device__ __forceinline__ float bflo(unsigned w) { return __uint_as_float(w << 16); }
; __device__ __forceinline__ float bfhi(unsigned w) { return __uint_as_float(w & 0xffff0000u); }
; template <int MODE, bool PRE = false, bool NEXT = false> ...
;     ...
;         const u16* grow = (const u16*)e.aux + (long)row * e.ldaux + cbase;
;         u16* orow = (u16*)e.out + (long)row * e.ldo + cbase;
; #pragma unroll
;         for (int bj = 0; bj < 2; ++bj)
; #pragma unroll
;           for (int n = 0; n < 2; ++n) {
;             const int sidx = ((ai * 4 + m) * 2 + bj) * 2 + n;
;             const u32x2 gw = *reinterpret_cast<const u32x2*>(grow + bj * 128 + n * 16);
;             f32x4 g = {bflo(gw[0]), bfhi(gw[0]), bflo(gw[1]), bfhi(gw[1])};
;             f32x4 mval = g * acc[ai][bj][m][n];
;             u32x2* sp = reinterpret_cast<u32x2*>(e.scr) + sidx * NTHR + tid;
;             if constexpr (MODE != EP_M0) { const u32x2 pw = *sp; mval += f32x4{bflo(pw[0]), bfhi(pw[0]), bflo(pw[1]), bfhi(pw[1])}; }
;             const u32x2 w = {cvtpk(mval[0], mval[1]), cvtpk(mval[2], mval[3])};
;             if constexpr (MODE == EP_M2) *reinterpret_cast<u32x2*>(orow + bj * 128 + n * 16) = w;
;             else *sp = w;
;           }
	v_cvt_pk_bf16_f32 v42, v42, v43
	s_nop 0
	v_cvt_pk_bf16_f32 v43, v44, v45
	global_store_dwordx2 v[48:49], v[42:43], off offset:-4096
	v_mov_b64_e32 v[42:43], v[236:237]
	v_lshlrev_b32_e32 v44, 16, v42
	v_and_b32_e32 v45, 0xffff0000, v42
	v_lshlrev_b32_e32 v42, 16, v43
	v_and_b32_e32 v43, 0xffff0000, v43
	v_pk_mul_f32 v[38:39], v[38:39], v[44:45]
	v_pk_mul_f32 v[40:41], v[40:41], v[42:43]
	v_cvt_pk_bf16_f32 v38, v38, v39
	v_mad_i64_i32 v[42:43], s[58:59], v0, s22, v[132:133]
	v_cvt_pk_bf16_f32 v39, v40, v41
	global_store_dwordx2 v[48:49], v[38:39], off
	v_add_co_u32_e32 v40, vcc, s14, v130
	s_mov_b32 s14, 0x1a000
	s_nop 0
	v_addc_co_u32_e32 v41, vcc, 0, v131, vcc
	v_add_u32_e32 v0, 0xb0, v134
	v_mov_b64_e32 v[38:39], v[238:239]
	v_lshlrev_b32_e32 v44, 16, v38
	v_and_b32_e32 v45, 0xffff0000, v38
	v_lshlrev_b32_e32 v38, 16, v39
	v_and_b32_e32 v39, 0xffff0000, v39
	v_pk_mul_f32 v[34:35], v[34:35], v[44:45]
	v_pk_mul_f32 v[36:37], v[36:37], v[38:39]
	v_cvt_pk_bf16_f32 v34, v34, v35
	s_nop 0
	v_cvt_pk_bf16_f32 v35, v36, v37
	global_store_dwordx2 v[40:41], v[34:35], off offset:-4096
	v_mov_b64_e32 v[34:35], v[240:241]
	v_lshlrev_b32_e32 v36, 16, v34
	v_and_b32_e32 v37, 0xffff0000, v34
	v_lshlrev_b32_e32 v34, 16, v35
	v_and_b32_e32 v35, 0xffff0000, v35
	v_pk_mul_f32 v[30:31], v[30:31], v[36:37]
	v_pk_mul_f32 v[32:33], v[32:33], v[34:35]
	v_cvt_pk_bf16_f32 v30, v30, v31
	s_nop 0
	v_cvt_pk_bf16_f32 v31, v32, v33
	global_store_dwordx2 v[40:41], v[30:31], off
	v_add_co_u32_e32 v32, vcc, s14, v130
	s_mov_b32 s14, 0x1c000
	s_nop 0
	v_addc_co_u32_e32 v33, vcc, 0, v131, vcc
	v_mov_b64_e32 v[30:31], v[242:243]
	v_lshlrev_b32_e32 v34, 16, v30
	v_and_b32_e32 v35, 0xffff0000, v30
	v_lshlrev_b32_e32 v30, 16, v31
	v_and_b32_e32 v31, 0xffff0000, v31
	v_pk_mul_f32 v[26:27], v[26:27], v[34:35]
	v_pk_mul_f32 v[28:29], v[28:29], v[30:31]
	v_cvt_pk_bf16_f32 v26, v26, v27
	s_nop 0
	v_cvt_pk_bf16_f32 v27, v28, v29
	global_store_dwordx2 v[32:33], v[26:27], off offset:-4096
	v_mov_b64_e32 v[26:27], v[244:245]
	v_lshlrev_b32_e32 v28, 16, v26
	v_and_b32_e32 v29, 0xffff0000, v26
	v_lshlrev_b32_e32 v26, 16, v27
	v_and_b32_e32 v27, 0xffff0000, v27
	v_pk_mul_f32 v[22:23], v[22:23], v[28:29]
	v_pk_mul_f32 v[24:25], v[24:25], v[26:27]
	v_cvt_pk_bf16_f32 v22, v22, v23
	v_mad_i64_i32 v[26:27], s[58:59], v0, s22, v[132:133]
	v_cvt_pk_bf16_f32 v23, v24, v25
	global_store_dwordx2 v[32:33], v[22:23], off
	v_add_co_u32_e32 v24, vcc, s14, v130
	s_mov_b32 s14, 0x1e000
	s_nop 0
	v_addc_co_u32_e32 v25, vcc, 0, v131, vcc
	v_mov_b64_e32 v[22:23], v[246:247]
	v_lshlrev_b32_e32 v28, 16, v22
	v_and_b32_e32 v29, 0xffff0000, v22
	v_lshlrev_b32_e32 v22, 16, v23
	v_and_b32_e32 v23, 0xffff0000, v23
	v_pk_mul_f32 v[18:19], v[18:19], v[28:29]
	v_pk_mul_f32 v[20:21], v[20:21], v[22:23]
	v_cvt_pk_bf16_f32 v18, v18, v19
	s_nop 0
	v_cvt_pk_bf16_f32 v19, v20, v21
	global_store_dwordx2 v[24:25], v[18:19], off offset:-4096
	v_mov_b64_e32 v[18:19], v[248:249]
	v_lshlrev_b32_e32 v20, 16, v18
	v_and_b32_e32 v21, 0xffff0000, v18
	v_lshlrev_b32_e32 v18, 16, v19
	v_and_b32_e32 v19, 0xffff0000, v19
	v_pk_mul_f32 v[14:15], v[14:15], v[20:21]
	v_pk_mul_f32 v[16:17], v[16:17], v[18:19]
	v_cvt_pk_bf16_f32 v14, v14, v15
	s_nop 0
	v_cvt_pk_bf16_f32 v15, v16, v17
	global_store_dwordx2 v[24:25], v[14:15], off
	v_add_co_u32_e32 v16, vcc, s14, v130
	v_mov_b64_e32 v[14:15], v[250:251]
	v_lshlrev_b32_e32 v18, 16, v14
	v_and_b32_e32 v19, 0xffff0000, v14
	v_addc_co_u32_e32 v17, vcc, 0, v131, vcc
	v_lshlrev_b32_e32 v14, 16, v15
	v_and_b32_e32 v15, 0xffff0000, v15
	v_pk_mul_f32 v[10:11], v[10:11], v[18:19]
	v_pk_mul_f32 v[12:13], v[12:13], v[14:15]
	v_cvt_pk_bf16_f32 v10, v10, v11
	s_nop 0
	v_cvt_pk_bf16_f32 v11, v12, v13
	global_store_dwordx2 v[16:17], v[10:11], off offset:-4096
	v_mov_b64_e32 v[10:11], v[182:183]
	v_lshlrev_b32_e32 v12, 16, v10
	v_and_b32_e32 v13, 0xffff0000, v10
	v_lshlrev_b32_e32 v10, 16, v11
	v_and_b32_e32 v11, 0xffff0000, v11
	v_pk_mul_f32 v[6:7], v[6:7], v[12:13]
	v_pk_mul_f32 v[8:9], v[8:9], v[10:11]
	v_cvt_pk_bf16_f32 v6, v6, v7
	s_nop 0
	v_cvt_pk_bf16_f32 v7, v8, v9
	global_store_dwordx2 v[16:17], v[6:7], off
	v_add_co_u32_e32 v8, vcc, 0x1f000, v130
	v_mov_b64_e32 v[6:7], v[184:185]
	v_lshlrev_b32_e32 v10, 16, v6
	v_and_b32_e32 v11, 0xffff0000, v6
	v_lshlrev_b32_e32 v6, 16, v7
	v_and_b32_e32 v7, 0xffff0000, v7
	v_pk_mul_f32 v[2:3], v[2:3], v[10:11]
	v_addc_co_u32_e32 v9, vcc, 0, v131, vcc
	v_pk_mul_f32 v[4:5], v[4:5], v[6:7]
	v_cvt_pk_bf16_f32 v2, v2, v3
	s_nop 0
	v_cvt_pk_bf16_f32 v3, v4, v5
	global_store_dwordx2 v[8:9], v[2:3], off
	v_mov_b32_e32 v130, v181
	s_nop 0
	v_readfirstlane_b32 s31, v130
	s_ashr_i32 s58, s31, 8
	s_cmp_lg_u32 s58, 1
	s_cbranch_scc1 .LBB0_589
	s_barrier

; __device__ __forceinline__ float bflo(unsigned w) { return __uint_as_float(w << 16); }
; __device__ __forceinline__ float bfhi(unsigned w) { return __uint_as_float(w & 0xffff0000u); }
; template <bool PRE, bool NEXT> ...
;     ...
;     int tid2 = tid; asm volatile("" : "+v"(tid2));
;     int r0, c0, r1, c1; stage_rc(tid2 * 16, r0, c0); stage_rc(tid2 * 16 + 8192, r1, c1);
;     const unsigned off0_NA = r0 * lda + c0, off1_NA = r1 * lda + c1, off0_NB = r0 * ldb + c0, off1_NB = r1 * ldb + c1;
;     STAGE(SB(0, 0), NB, ldb, 0, 0); STAGE(SA(0, 0), NA, lda, 0, 0);
;     STAGE(SB(0, 1), NB, ldb, HALF, 0); STAGE(SA(0, 1), NA, lda, HALF, 0);
; template <int MODE, bool PRE = false, bool NEXT = false> ...
;     ...
;         const u16* grow = (const u16*)e.aux + (long)row * e.ldaux + cbase;
;         u16* orow = (u16*)e.out + (long)row * e.ldo + cbase;
; #pragma unroll
;         for (int bj = 0; bj < 2; ++bj)
; #pragma unroll
;           for (int n = 0; n < 2; ++n) {
;             const int sidx = ((ai * 4 + m) * 2 + bj) * 2 + n;
;             const u32x2 gw = *reinterpret_cast<const u32x2*>(grow + bj * 128 + n * 16);
;             f32x4 g = {bflo(gw[0]), bfhi(gw[0]), bflo(gw[1]), bfhi(gw[1])};
;             f32x4 mval = g * acc[ai][bj][m][n];
;             u32x2* sp = reinterpret_cast<u32x2*>(e.scr) + sidx * NTHR + tid;
;             if constexpr (MODE != EP_M0) { const u32x2 pw = *sp; mval += f32x4{bflo(pw[0]), bfhi(pw[0]), bflo(pw[1]), bfhi(pw[1])}; }
;             const u32x2 w = {cvtpk(mval[0], mval[1]), cvtpk(mval[2], mval[3])};
;             if constexpr (MODE == EP_M2) *reinterpret_cast<u32x2*>(orow + bj * 128 + n * 16) = w;
;             else *sp = w;
;           }
.LBB0_593:
	v_mov_b32_e32 v0, v130
	s_mov_b64 s[16:17], 0x400
	v_ashrrev_i32_e32 v133, 31, v0
	v_lshrrev_b32_e32 v133, 26, v133
	v_lshlrev_b32_e32 v132, 4, v0
	v_add_u32_e32 v133, v0, v133
	v_bfe_i32 v0, v0, 27, 1
	v_lshrrev_b32_e32 v0, 22, v0
	v_add_u32_e32 v0, v132, v0
	v_and_b32_e32 v0, 0xfffffc00, v0
	v_sub_u32_e32 v0, v132, v0
	v_lshrrev_b32_e32 v134, 4, v0
	v_bitop3_b32 v0, v134, v0, 32 bitop3:0x6c
	v_ashrrev_i32_e32 v135, 31, v0
	v_lshrrev_b32_e32 v135, 26, v135
	v_add_u32_e32 v135, v0, v135
	v_lshrrev_b32_e32 v136, 6, v135
	v_and_b32_e32 v135, 0xc0, v135
	v_add_u32_e32 v132, 0x2000, v132
	v_sub_u32_e32 v0, v0, v135
	v_ashrrev_i32_e32 v135, 31, v132
	v_ashrrev_i32_e32 v133, 6, v133
	v_lshrrev_b32_e32 v135, 22, v135
	v_lshlrev_b32_e32 v134, 3, v133
	v_add_u32_e32 v135, v132, v135
	v_and_b32_e32 v134, 0x3ffff0, v134
	v_ashrrev_i32_e32 v135, 10, v135
	v_add_u32_e32 v134, v136, v134
	v_mul_i32_i24_e32 v136, 0x400, v135
	v_sub_u32_e32 v132, v132, v136
	v_lshrrev_b32_e32 v136, 4, v132
	v_bitop3_b32 v132, v136, v132, 32 bitop3:0x6c
	v_ashrrev_i32_e32 v137, 31, v132
	v_lshlrev_b32_e32 v133, 5, v133
	v_lshrrev_b32_e32 v137, 26, v137
	v_and_b32_e32 v133, 32, v133
	v_lshlrev_b32_e32 v136, 3, v135
	v_add_u32_e32 v137, v132, v137
	v_ashrrev_i16_sdwa v0, v190, sext(v0) dst_sel:DWORD dst_unused:UNUSED_PAD src0_sel:DWORD src1_sel:BYTE_0
	v_and_b32_e32 v136, 0x3ffff0, v136
	v_lshrrev_b32_e32 v138, 6, v137
	v_lshlrev_b32_e32 v135, 5, v135
	v_and_b32_e32 v137, 0xc0, v137
	v_lshl_or_b32 v133, v134, 10, v133
	v_add_u32_e32 v136, v138, v136
	v_and_b32_e32 v135, 32, v135
	v_sub_u32_e32 v132, v132, v137
	v_add_u32_sdwa v0, v133, sext(v0) dst_sel:DWORD dst_unused:UNUSED_PAD src0_sel:DWORD src1_sel:WORD_0
	v_ashrrev_i16_sdwa v132, v190, sext(v132) dst_sel:DWORD dst_unused:UNUSED_PAD src0_sel:DWORD src1_sel:BYTE_0
	v_lshl_or_b32 v133, v136, 10, v135
	v_lshlrev_b64 v[134:135], 1, v[0:1]
	v_add_u32_sdwa v132, v133, sext(v132) dst_sel:DWORD dst_unused:UNUSED_PAD src0_sel:DWORD src1_sel:WORD_0
	v_lshl_add_u64 v[136:137], s[64:65], 0, v[134:135]
	v_readfirstlane_b32 s14, v159
	v_mov_b32_e32 v133, v1
	v_lshl_add_u64 v[136:137], v[136:137], 0, s[16:17]
	s_mov_b32 m0, s14
	v_lshlrev_b64 v[132:133], 1, v[132:133]
	global_load_lds_dwordx4 v[136:137], off
	v_lshl_add_u64 v[136:137], s[64:65], 0, v[132:133]
	v_readfirstlane_b32 s14, v158
	v_lshl_add_u64 v[136:137], v[136:137], 0, s[16:17]
	s_mov_b32 m0, s14
	v_readfirstlane_b32 s14, v144
	global_load_lds_dwordx4 v[136:137], off
	v_lshl_add_u64 v[136:137], s[80:81], 0, v[134:135]
	v_lshl_add_u64 v[136:137], v[136:137], 0, s[16:17]
	s_mov_b32 m0, s14
	v_readfirstlane_b32 s14, v160
	global_load_lds_dwordx4 v[136:137], off
	v_lshl_add_u64 v[136:137], s[80:81], 0, v[132:133]
	s_add_u32 s58, s64, 0x40400
	v_lshl_add_u64 v[136:137], v[136:137], 0, s[16:17]
	s_mov_b32 m0, s14
	s_addc_u32 s59, s65, 0
	v_readfirstlane_b32 s14, v161
	global_load_lds_dwordx4 v[136:137], off
	v_lshl_add_u64 v[136:137], s[58:59], 0, v[134:135]
	s_mov_b32 m0, s14
	v_readfirstlane_b32 s14, v162
	global_load_lds_dwordx4 v[136:137], off
	v_lshl_add_u64 v[136:137], s[58:59], 0, v[132:133]
	s_add_u32 s58, s80, 0x40400
	s_mov_b32 m0, s14
	s_addc_u32 s59, s81, 0
	v_readfirstlane_b32 s14, v166
	global_load_lds_dwordx4 v[136:137], off
	v_lshl_add_u64 v[134:135], s[58:59], 0, v[134:135]
	s_mov_b32 m0, s14
	v_readfirstlane_b32 s14, v167
	global_load_lds_dwordx4 v[134:135], off
	s_mov_b32 m0, s14
	v_readfirstlane_b32 s14, v130
	s_ashr_i32 s15, s14, 2
	s_lshr_b32 s14, s14, 1
	v_lshl_add_u64 v[132:133], s[58:59], 0, v[132:133]
	s_and_b32 s14, s14, 0x60
	v_lshrrev_b32_e32 v0, 2, v130
	global_load_lds_dwordx4 v[132:133], off
	s_andn2_b32 s15, s15, 63
	v_and_or_b32 v0, v0, 12, s14
	v_mov_b32_e32 v132, 1.0
	v_or_b32_e32 v134, s15, v143
	v_lshlrev_b32_e32 v0, 1, v0
	v_readlane_b32 s14, v254, 10
	v_lshl_add_u64 v[132:133], s[10:11], 0, v[0:1]
	s_movk_i32 s22, 0x1800
	v_readlane_b32 s15, v254, 11
	v_mad_i64_i32 v[136:137], s[58:59], v134, s22, v[132:133]
	s_nop 0
	v_lshl_add_u64 v[130:131], v[130:131], 3, s[14:15]
	v_mov_b32_e32 v170, v134
	v_mad_i64_i32 v[168:169], s[98:99], v170, s22, v[132:133]
	global_load_dwordx2 v[192:193], v[168:169], off offset:2048
	global_load_dwordx2 v[196:197], v[168:169], off offset:2080
	global_load_dwordx2 v[200:201], v[168:169], off offset:2304
	global_load_dwordx2 v[204:205], v[168:169], off offset:2336
	v_add_co_u32_e32 v172, vcc, 0x1000, v130
	s_nop 1
	v_addc_co_u32_e32 v173, vcc, 0, v131, vcc
	global_load_dwordx2 v[194:195], v[172:173], off offset:-4096
	global_load_dwordx2 v[198:199], v[172:173], off
	v_add_co_u32_e32 v172, vcc, 0x3000, v130
	s_nop 1
	v_addc_co_u32_e32 v173, vcc, 0, v131, vcc
	global_load_dwordx2 v[202:203], v[172:173], off offset:-4096
	global_load_dwordx2 v[206:207], v[172:173], off
	v_add_u32_e32 v170, 0x10, v134
	v_mad_i64_i32 v[168:169], s[98:99], v170, s22, v[132:133]
	global_load_dwordx2 v[208:209], v[168:169], off offset:2048
	global_load_dwordx2 v[212:213], v[168:169], off offset:2080
	global_load_dwordx2 v[216:217], v[168:169], off offset:2304
	global_load_dwordx2 v[220:221], v[168:169], off offset:2336
	v_add_co_u32_e32 v172, vcc, 0x5000, v130
	s_nop 1
	v_addc_co_u32_e32 v173, vcc, 0, v131, vcc
	global_load_dwordx2 v[210:211], v[172:173], off offset:-4096
	global_load_dwordx2 v[214:215], v[172:173], off
	v_add_co_u32_e32 v172, vcc, 0x7000, v130
	s_nop 1
	v_addc_co_u32_e32 v173, vcc, 0, v131, vcc
	global_load_dwordx2 v[218:219], v[172:173], off offset:-4096
	global_load_dwordx2 v[222:223], v[172:173], off
	v_add_u32_e32 v170, 0x20, v134
	v_mad_i64_i32 v[168:169], s[98:99], v170, s22, v[132:133]
	global_load_dwordx2 v[224:225], v[168:169], off offset:2048
	global_load_dwordx2 v[228:229], v[168:169], off offset:2080
	global_load_dwordx2 v[232:233], v[168:169], off offset:2304
	global_load_dwordx2 v[236:237], v[168:169], off offset:2336
	v_add_co_u32_e32 v172, vcc, 0x9000, v130
	s_nop 1
	v_addc_co_u32_e32 v173, vcc, 0, v131, vcc
	global_load_dwordx2 v[226:227], v[172:173], off offset:-4096
	global_load_dwordx2 v[230:231], v[172:173], off
	v_add_co_u32_e32 v172, vcc, 0xb000, v130
	s_nop 1
	v_addc_co_u32_e32 v173, vcc, 0, v131, vcc
	global_load_dwordx2 v[234:235], v[172:173], off offset:-4096
	global_load_dwordx2 v[238:239], v[172:173], off
	v_add_u32_e32 v170, 0x30, v134
	v_mad_i64_i32 v[168:169], s[98:99], v170, s22, v[132:133]
	global_load_dwordx2 v[240:241], v[168:169], off offset:2048
	global_load_dwordx2 v[244:245], v[168:169], off offset:2080
	global_load_dwordx2 v[248:249], v[168:169], off offset:2304
	global_load_dwordx2 v[182:183], v[168:169], off offset:2336
	v_add_co_u32_e32 v172, vcc, 0xd000, v130
	s_nop 1
	v_addc_co_u32_e32 v173, vcc, 0, v131, vcc
	global_load_dwordx2 v[242:243], v[172:173], off offset:-4096
	global_load_dwordx2 v[246:247], v[172:173], off
	v_add_co_u32_e32 v172, vcc, 0xf000, v130
	s_nop 1
	v_addc_co_u32_e32 v173, vcc, 0, v131, vcc
	global_load_dwordx2 v[250:251], v[172:173], off offset:-4096
	global_load_dwordx2 v[184:185], v[172:173], off
	s_waitcnt vmcnt(0)
; __device__ __forceinline__ float bflo(unsigned w) { return __uint_as_float(w << 16); }
; __device__ __forceinline__ float bfhi(unsigned w) { return __uint_as_float(w & 0xffff0000u); }
; template <int MODE, bool PRE = false, bool NEXT = false> ...
;     ...
;         const u16* grow = (const u16*)e.aux + (long)row * e.ldaux + cbase;
;         u16* orow = (u16*)e.out + (long)row * e.ldo + cbase;
; #pragma unroll
;         for (int bj = 0; bj < 2; ++bj)
; #pragma unroll
;           for (int n = 0; n < 2; ++n) {
;             const int sidx = ((ai * 4 + m) * 2 + bj) * 2 + n;
;             const u32x2 gw = *reinterpret_cast<const u32x2*>(grow + bj * 128 + n * 16);
;             f32x4 g = {bflo(gw[0]), bfhi(gw[0]), bflo(gw[1]), bfhi(gw[1])};
;             f32x4 mval = g * acc[ai][bj][m][n];
;             u32x2* sp = reinterpret_cast<u32x2*>(e.scr) + sidx * NTHR + tid;
;             if constexpr (MODE != EP_M0) { const u32x2 pw = *sp; mval += f32x4{bflo(pw[0]), bfhi(pw[0]), bflo(pw[1]), bfhi(pw[1])}; }
;             const u32x2 w = {cvtpk(mval[0], mval[1]), cvtpk(mval[2], mval[3])};
;             if constexpr (MODE == EP_M2) *reinterpret_cast<u32x2*>(orow + bj * 128 + n * 16) = w;
;             else *sp = w;
;           }
	s_movk_i32 s14, 0x2000
	v_or_b32_e32 v0, 16, v134
	v_mov_b64_e32 v[138:139], v[192:193]
	v_mov_b64_e32 v[140:141], v[194:195]
	v_lshlrev_b32_e32 v144, 16, v138
	v_and_b32_e32 v145, 0xffff0000, v138
	v_lshlrev_b32_e32 v138, 16, v139
	v_and_b32_e32 v139, 0xffff0000, v139
	v_lshlrev_b32_e32 v146, 16, v140
	v_and_b32_e32 v147, 0xffff0000, v140
	v_lshlrev_b32_e32 v140, 16, v141
	v_and_b32_e32 v141, 0xffff0000, v141
	v_pk_fma_f32 v[128:129], v[128:129], v[138:139], v[140:141]
	v_pk_fma_f32 v[126:127], v[126:127], v[144:145], v[146:147]
	s_nop 0
	v_cvt_pk_bf16_f32 v126, v126, v127
	v_cvt_pk_bf16_f32 v127, v128, v129
	v_add_co_u32_e32 v128, vcc, s14, v130
	global_store_dwordx2 v[130:131], v[126:127], off
	s_nop 0
	v_addc_co_u32_e32 v129, vcc, 0, v131, vcc
	s_movk_i32 s14, 0x4000
	v_mov_b64_e32 v[126:127], v[196:197]
	v_mov_b64_e32 v[138:139], v[198:199]
	v_lshlrev_b32_e32 v140, 16, v126
	v_and_b32_e32 v141, 0xffff0000, v126
	v_lshlrev_b32_e32 v144, 16, v138
	v_and_b32_e32 v145, 0xffff0000, v138
	v_lshlrev_b32_e32 v126, 16, v127
	v_and_b32_e32 v127, 0xffff0000, v127
	v_lshlrev_b32_e32 v138, 16, v139
	v_and_b32_e32 v139, 0xffff0000, v139
	v_pk_fma_f32 v[122:123], v[122:123], v[140:141], v[144:145]
	v_pk_fma_f32 v[124:125], v[124:125], v[126:127], v[138:139]
	v_cvt_pk_bf16_f32 v122, v122, v123
	s_nop 0
	v_cvt_pk_bf16_f32 v123, v124, v125
	global_store_dwordx2 v[128:129], v[122:123], off offset:-4096
	s_nop 0
	v_mov_b64_e32 v[122:123], v[200:201]
	v_mov_b64_e32 v[124:125], v[202:203]
	v_lshlrev_b32_e32 v126, 16, v122
	v_and_b32_e32 v127, 0xffff0000, v122
	v_lshlrev_b32_e32 v122, 16, v123
	v_and_b32_e32 v123, 0xffff0000, v123
	v_lshlrev_b32_e32 v138, 16, v124
	v_and_b32_e32 v139, 0xffff0000, v124
	v_lshlrev_b32_e32 v124, 16, v125
	v_and_b32_e32 v125, 0xffff0000, v125
	v_pk_fma_f32 v[120:121], v[120:121], v[122:123], v[124:125]
	v_pk_fma_f32 v[118:119], v[118:119], v[126:127], v[138:139]
	v_mad_i64_i32 v[124:125], s[58:59], v0, s22, v[132:133]
	v_cvt_pk_bf16_f32 v118, v118, v119
	v_cvt_pk_bf16_f32 v119, v120, v121
	v_add_co_u32_e32 v120, vcc, s14, v130
	global_store_dwordx2 v[128:129], v[118:119], off
	s_nop 0
	v_addc_co_u32_e32 v121, vcc, 0, v131, vcc
	s_movk_i32 s14, 0x6000
	v_or_b32_e32 v0, 32, v134
	v_mov_b64_e32 v[118:119], v[204:205]
	v_mov_b64_e32 v[122:123], v[206:207]
	v_lshlrev_b32_e32 v126, 16, v118
	v_and_b32_e32 v127, 0xffff0000, v118
	v_lshlrev_b32_e32 v128, 16, v122
	v_and_b32_e32 v129, 0xffff0000, v122
	v_lshlrev_b32_e32 v118, 16, v119
	v_and_b32_e32 v119, 0xffff0000, v119
	v_lshlrev_b32_e32 v122, 16, v123
	v_and_b32_e32 v123, 0xffff0000, v123
	v_pk_fma_f32 v[114:115], v[114:115], v[126:127], v[128:129]
	v_pk_fma_f32 v[116:117], v[116:117], v[118:119], v[122:123]
	v_cvt_pk_bf16_f32 v114, v114, v115
	s_nop 0
	v_cvt_pk_bf16_f32 v115, v116, v117
	global_store_dwordx2 v[120:121], v[114:115], off offset:-4096
	s_nop 0
	v_mov_b64_e32 v[114:115], v[208:209]
	v_mov_b64_e32 v[116:117], v[210:211]
	v_lshlrev_b32_e32 v118, 16, v114
	v_and_b32_e32 v119, 0xffff0000, v114
	v_lshlrev_b32_e32 v114, 16, v115
	v_and_b32_e32 v115, 0xffff0000, v115
	v_lshlrev_b32_e32 v122, 16, v116
	v_and_b32_e32 v123, 0xffff0000, v116
	v_lshlrev_b32_e32 v116, 16, v117
	v_and_b32_e32 v117, 0xffff0000, v117
	v_pk_fma_f32 v[112:113], v[112:113], v[114:115], v[116:117]
	v_pk_fma_f32 v[110:111], v[110:111], v[118:119], v[122:123]
	s_nop 0
	v_cvt_pk_bf16_f32 v110, v110, v111
	v_cvt_pk_bf16_f32 v111, v112, v113
	v_add_co_u32_e32 v112, vcc, s14, v130
	global_store_dwordx2 v[120:121], v[110:111], off
	s_nop 0
	v_addc_co_u32_e32 v113, vcc, 0, v131, vcc
	s_mov_b32 s14, 0x8000
	v_mov_b64_e32 v[110:111], v[212:213]
	v_mov_b64_e32 v[114:115], v[214:215]
	v_lshlrev_b32_e32 v116, 16, v110
	v_and_b32_e32 v117, 0xffff0000, v110
	v_lshlrev_b32_e32 v118, 16, v114
	v_and_b32_e32 v119, 0xffff0000, v114
	v_lshlrev_b32_e32 v110, 16, v111
	v_and_b32_e32 v111, 0xffff0000, v111
	v_lshlrev_b32_e32 v114, 16, v115
	v_and_b32_e32 v115, 0xffff0000, v115
	v_pk_fma_f32 v[106:107], v[106:107], v[116:117], v[118:119]
	v_pk_fma_f32 v[108:109], v[108:109], v[110:111], v[114:115]
	v_cvt_pk_bf16_f32 v106, v106, v107
	s_nop 0
	v_cvt_pk_bf16_f32 v107, v108, v109
	global_store_dwordx2 v[112:113], v[106:107], off offset:-4096
	s_nop 0
	v_mov_b64_e32 v[106:107], v[216:217]
	v_mov_b64_e32 v[108:109], v[218:219]
	v_lshlrev_b32_e32 v110, 16, v106
	v_and_b32_e32 v111, 0xffff0000, v106
	v_lshlrev_b32_e32 v106, 16, v107
	v_and_b32_e32 v107, 0xffff0000, v107
	v_lshlrev_b32_e32 v114, 16, v108
	v_and_b32_e32 v115, 0xffff0000, v108
	v_lshlrev_b32_e32 v108, 16, v109
	v_and_b32_e32 v109, 0xffff0000, v109
	v_pk_fma_f32 v[104:105], v[104:105], v[106:107], v[108:109]
	v_pk_fma_f32 v[102:103], v[102:103], v[110:111], v[114:115]
	v_mad_i64_i32 v[108:109], s[58:59], v0, s22, v[132:133]
	v_cvt_pk_bf16_f32 v102, v102, v103
	v_cvt_pk_bf16_f32 v103, v104, v105
	v_add_co_u32_e32 v104, vcc, s14, v130
	global_store_dwordx2 v[112:113], v[102:103], off
	s_nop 0
	v_addc_co_u32_e32 v105, vcc, 0, v131, vcc
	s_mov_b32 s14, 0xa000
	v_or_b32_e32 v0, 48, v134
	v_mov_b64_e32 v[102:103], v[220:221]
	v_mov_b64_e32 v[106:107], v[222:223]
	v_lshlrev_b32_e32 v110, 16, v102
	v_and_b32_e32 v111, 0xffff0000, v102
	v_lshlrev_b32_e32 v112, 16, v106
	v_and_b32_e32 v113, 0xffff0000, v106
	v_lshlrev_b32_e32 v102, 16, v103
	v_and_b32_e32 v103, 0xffff0000, v103
	v_lshlrev_b32_e32 v106, 16, v107
	v_and_b32_e32 v107, 0xffff0000, v107
	v_pk_fma_f32 v[98:99], v[98:99], v[110:111], v[112:113]
	v_pk_fma_f32 v[100:101], v[100:101], v[102:103], v[106:107]
	v_cvt_pk_bf16_f32 v98, v98, v99
	s_nop 0
	v_cvt_pk_bf16_f32 v99, v100, v101
	global_store_dwordx2 v[104:105], v[98:99], off offset:-4096
; __device__ __forceinline__ float bflo(unsigned w) { return __uint_as_float(w << 16); }
; __device__ __forceinline__ float bfhi(unsigned w) { return __uint_as_float(w & 0xffff0000u); }
; template <int MODE, bool PRE = false, bool NEXT = false> ...
;     ...
;         const u16* grow = (const u16*)e.aux + (long)row * e.ldaux + cbase;
;         u16* orow = (u16*)e.out + (long)row * e.ldo + cbase;
; #pragma unroll
;         for (int bj = 0; bj < 2; ++bj)
; #pragma unroll
;           for (int n = 0; n < 2; ++n) {
;             const int sidx = ((ai * 4 + m) * 2 + bj) * 2 + n;
;             const u32x2 gw = *reinterpret_cast<const u32x2*>(grow + bj * 128 + n * 16);
;             f32x4 g = {bflo(gw[0]), bfhi(gw[0]), bflo(gw[1]), bfhi(gw[1])};
;             f32x4 mval = g * acc[ai][bj][m][n];
;             u32x2* sp = reinterpret_cast<u32x2*>(e.scr) + sidx * NTHR + tid;
;             if constexpr (MODE != EP_M0) { const u32x2 pw = *sp; mval += f32x4{bflo(pw[0]), bfhi(pw[0]), bflo(pw[1]), bfhi(pw[1])}; }
;             const u32x2 w = {cvtpk(mval[0], mval[1]), cvtpk(mval[2], mval[3])};
;             if constexpr (MODE == EP_M2) *reinterpret_cast<u32x2*>(orow + bj * 128 + n * 16) = w;
;             else *sp = w;
;           }
	s_nop 0
	v_mov_b64_e32 v[98:99], v[224:225]
	v_mov_b64_e32 v[100:101], v[226:227]
	v_lshlrev_b32_e32 v102, 16, v98
	v_and_b32_e32 v103, 0xffff0000, v98
	v_lshlrev_b32_e32 v98, 16, v99
	v_and_b32_e32 v99, 0xffff0000, v99
	v_lshlrev_b32_e32 v106, 16, v100
	v_and_b32_e32 v107, 0xffff0000, v100
	v_lshlrev_b32_e32 v100, 16, v101
	v_and_b32_e32 v101, 0xffff0000, v101
	v_pk_fma_f32 v[96:97], v[96:97], v[98:99], v[100:101]
	v_pk_fma_f32 v[94:95], v[94:95], v[102:103], v[106:107]
	s_nop 0
	v_cvt_pk_bf16_f32 v94, v94, v95
	v_cvt_pk_bf16_f32 v95, v96, v97
	v_add_co_u32_e32 v96, vcc, s14, v130
	global_store_dwordx2 v[104:105], v[94:95], off
	s_nop 0
	v_addc_co_u32_e32 v97, vcc, 0, v131, vcc
	s_mov_b32 s14, 0xc000
	v_mov_b64_e32 v[94:95], v[228:229]
	v_mov_b64_e32 v[98:99], v[230:231]
	v_lshlrev_b32_e32 v100, 16, v94
	v_and_b32_e32 v101, 0xffff0000, v94
	v_lshlrev_b32_e32 v102, 16, v98
	v_and_b32_e32 v103, 0xffff0000, v98
	v_lshlrev_b32_e32 v94, 16, v95
	v_and_b32_e32 v95, 0xffff0000, v95
	v_lshlrev_b32_e32 v98, 16, v99
	v_and_b32_e32 v99, 0xffff0000, v99
	v_pk_fma_f32 v[90:91], v[90:91], v[100:101], v[102:103]
	v_pk_fma_f32 v[92:93], v[92:93], v[94:95], v[98:99]
	v_cvt_pk_bf16_f32 v90, v90, v91
	s_nop 0
	v_cvt_pk_bf16_f32 v91, v92, v93
	global_store_dwordx2 v[96:97], v[90:91], off offset:-4096
	s_nop 0
	v_mov_b64_e32 v[90:91], v[232:233]
	v_mov_b64_e32 v[92:93], v[234:235]
	v_lshlrev_b32_e32 v94, 16, v90
	v_and_b32_e32 v95, 0xffff0000, v90
	v_lshlrev_b32_e32 v90, 16, v91
	v_and_b32_e32 v91, 0xffff0000, v91
	v_lshlrev_b32_e32 v98, 16, v92
	v_and_b32_e32 v99, 0xffff0000, v92
	v_lshlrev_b32_e32 v92, 16, v93
	v_and_b32_e32 v93, 0xffff0000, v93
	v_pk_fma_f32 v[88:89], v[88:89], v[90:91], v[92:93]
	v_pk_fma_f32 v[86:87], v[86:87], v[94:95], v[98:99]
	v_mad_i64_i32 v[92:93], s[58:59], v0, s22, v[132:133]
	v_cvt_pk_bf16_f32 v86, v86, v87
	v_cvt_pk_bf16_f32 v87, v88, v89
	v_add_co_u32_e32 v88, vcc, s14, v130
	global_store_dwordx2 v[96:97], v[86:87], off
	s_nop 0
	v_addc_co_u32_e32 v89, vcc, 0, v131, vcc
	s_mov_b32 s14, 0xe000
	v_mov_b64_e32 v[86:87], v[236:237]
	v_mov_b64_e32 v[90:91], v[238:239]
	v_lshlrev_b32_e32 v94, 16, v86
	v_and_b32_e32 v95, 0xffff0000, v86
	v_lshlrev_b32_e32 v96, 16, v90
	v_and_b32_e32 v97, 0xffff0000, v90
	v_lshlrev_b32_e32 v86, 16, v87
	v_and_b32_e32 v87, 0xffff0000, v87
	v_lshlrev_b32_e32 v90, 16, v91
	v_and_b32_e32 v91, 0xffff0000, v91
	v_pk_fma_f32 v[82:83], v[82:83], v[94:95], v[96:97]
	v_pk_fma_f32 v[84:85], v[84:85], v[86:87], v[90:91]
	v_cvt_pk_bf16_f32 v82, v82, v83
	s_nop 0
	v_cvt_pk_bf16_f32 v83, v84, v85
	global_store_dwordx2 v[88:89], v[82:83], off offset:-4096
	s_nop 0
	v_mov_b64_e32 v[82:83], v[240:241]
	v_mov_b64_e32 v[84:85], v[242:243]
	v_lshlrev_b32_e32 v86, 16, v82
	v_and_b32_e32 v87, 0xffff0000, v82
	v_lshlrev_b32_e32 v82, 16, v83
	v_and_b32_e32 v83, 0xffff0000, v83
	v_lshlrev_b32_e32 v90, 16, v84
	v_and_b32_e32 v91, 0xffff0000, v84
	v_lshlrev_b32_e32 v84, 16, v85
	v_and_b32_e32 v85, 0xffff0000, v85
	v_pk_fma_f32 v[80:81], v[80:81], v[82:83], v[84:85]
	v_pk_fma_f32 v[78:79], v[78:79], v[86:87], v[90:91]
	s_nop 0
	v_cvt_pk_bf16_f32 v78, v78, v79
	v_cvt_pk_bf16_f32 v79, v80, v81
	v_add_co_u32_e32 v80, vcc, s14, v130
	global_store_dwordx2 v[88:89], v[78:79], off
	s_nop 0
	v_addc_co_u32_e32 v81, vcc, 0, v131, vcc
	s_mov_b32 s14, 0x10000
	v_mov_b64_e32 v[78:79], v[244:245]
	v_mov_b64_e32 v[82:83], v[246:247]
	v_lshlrev_b32_e32 v84, 16, v78
	v_and_b32_e32 v85, 0xffff0000, v78
	v_lshlrev_b32_e32 v86, 16, v82
	v_and_b32_e32 v87, 0xffff0000, v82
	v_lshlrev_b32_e32 v78, 16, v79
	v_and_b32_e32 v79, 0xffff0000, v79
	v_lshlrev_b32_e32 v82, 16, v83
	v_and_b32_e32 v83, 0xffff0000, v83
	v_pk_fma_f32 v[74:75], v[74:75], v[84:85], v[86:87]
	v_pk_fma_f32 v[76:77], v[76:77], v[78:79], v[82:83]
	v_cvt_pk_bf16_f32 v74, v74, v75
	s_nop 0
	v_cvt_pk_bf16_f32 v75, v76, v77
	global_store_dwordx2 v[80:81], v[74:75], off offset:-4096
	s_nop 0
	v_mov_b64_e32 v[74:75], v[248:249]
	v_mov_b64_e32 v[76:77], v[250:251]
	v_lshlrev_b32_e32 v78, 16, v74
	v_and_b32_e32 v79, 0xffff0000, v74
	v_lshlrev_b32_e32 v74, 16, v75
	v_and_b32_e32 v75, 0xffff0000, v75
	v_lshlrev_b32_e32 v82, 16, v76
	v_and_b32_e32 v83, 0xffff0000, v76
	v_lshlrev_b32_e32 v76, 16, v77
	v_and_b32_e32 v77, 0xffff0000, v77
	v_pk_fma_f32 v[72:73], v[72:73], v[74:75], v[76:77]
	v_pk_fma_f32 v[70:71], v[70:71], v[78:79], v[82:83]
	s_nop 0
	v_cvt_pk_bf16_f32 v70, v70, v71
	v_cvt_pk_bf16_f32 v71, v72, v73
	v_add_co_u32_e32 v72, vcc, s14, v130
	global_store_dwordx2 v[80:81], v[70:71], off
	s_nop 0
	v_addc_co_u32_e32 v73, vcc, 0, v131, vcc
	v_mov_b64_e32 v[70:71], v[182:183]
	v_mov_b64_e32 v[74:75], v[184:185]
	v_lshlrev_b32_e32 v76, 16, v70
	v_and_b32_e32 v77, 0xffff0000, v70
	v_lshlrev_b32_e32 v78, 16, v74
	v_and_b32_e32 v79, 0xffff0000, v74
	v_lshlrev_b32_e32 v70, 16, v71
	v_and_b32_e32 v71, 0xffff0000, v71
	v_lshlrev_b32_e32 v74, 16, v75
	v_and_b32_e32 v75, 0xffff0000, v75
	v_pk_fma_f32 v[66:67], v[66:67], v[76:77], v[78:79]
	v_pk_fma_f32 v[68:69], v[68:69], v[70:71], v[74:75]
	v_cvt_pk_bf16_f32 v66, v66, v67
	s_nop 0
	v_cvt_pk_bf16_f32 v67, v68, v69
	global_store_dwordx2 v[72:73], v[66:67], off offset:-4096
	v_add_u32_e32 v0, 0x80, v134
	v_mad_i64_i32 v[66:67], s[58:59], v0, s22, v[132:133]
	v_add_u32_e32 v170, 0x80, v134
	v_mad_i64_i32 v[168:169], s[98:99], v170, s22, v[132:133]
	global_load_dwordx2 v[192:193], v[168:169], off offset:2048
	global_load_dwordx2 v[196:197], v[168:169], off offset:2080
	global_load_dwordx2 v[200:201], v[168:169], off offset:2304
	global_load_dwordx2 v[204:205], v[168:169], off offset:2336
	v_add_co_u32_e32 v172, vcc, 0x11000, v130
	s_nop 1
; __device__ __forceinline__ float bflo(unsigned w) { return __uint_as_float(w << 16); }
; __device__ __forceinline__ float bfhi(unsigned w) { return __uint_as_float(w & 0xffff0000u); }
; template <int MODE, bool PRE = false, bool NEXT = false> ...
;     ...
;         const u16* grow = (const u16*)e.aux + (long)row * e.ldaux + cbase;
;         u16* orow = (u16*)e.out + (long)row * e.ldo + cbase;
; #pragma unroll
;         for (int bj = 0; bj < 2; ++bj)
; #pragma unroll
;           for (int n = 0; n < 2; ++n) {
;             const int sidx = ((ai * 4 + m) * 2 + bj) * 2 + n;
;             const u32x2 gw = *reinterpret_cast<const u32x2*>(grow + bj * 128 + n * 16);
;             f32x4 g = {bflo(gw[0]), bfhi(gw[0]), bflo(gw[1]), bfhi(gw[1])};
;             f32x4 mval = g * acc[ai][bj][m][n];
;             u32x2* sp = reinterpret_cast<u32x2*>(e.scr) + sidx * NTHR + tid;
;             if constexpr (MODE != EP_M0) { const u32x2 pw = *sp; mval += f32x4{bflo(pw[0]), bfhi(pw[0]), bflo(pw[1]), bfhi(pw[1])}; }
;             const u32x2 w = {cvtpk(mval[0], mval[1]), cvtpk(mval[2], mval[3])};
;             if constexpr (MODE == EP_M2) *reinterpret_cast<u32x2*>(orow + bj * 128 + n * 16) = w;
;             else *sp = w;
;           }
	v_addc_co_u32_e32 v173, vcc, 0, v131, vcc
	global_load_dwordx2 v[194:195], v[172:173], off offset:-4096
	global_load_dwordx2 v[198:199], v[172:173], off
	v_add_co_u32_e32 v172, vcc, 0x13000, v130
	s_nop 1
	v_addc_co_u32_e32 v173, vcc, 0, v131, vcc
	global_load_dwordx2 v[202:203], v[172:173], off offset:-4096
	global_load_dwordx2 v[206:207], v[172:173], off
	v_add_u32_e32 v170, 0x90, v134
	v_mad_i64_i32 v[168:169], s[98:99], v170, s22, v[132:133]
	global_load_dwordx2 v[208:209], v[168:169], off offset:2048
	global_load_dwordx2 v[212:213], v[168:169], off offset:2080
	global_load_dwordx2 v[216:217], v[168:169], off offset:2304
	global_load_dwordx2 v[220:221], v[168:169], off offset:2336
	v_add_co_u32_e32 v172, vcc, 0x15000, v130
	s_nop 1
	v_addc_co_u32_e32 v173, vcc, 0, v131, vcc
	global_load_dwordx2 v[210:211], v[172:173], off offset:-4096
	global_load_dwordx2 v[214:215], v[172:173], off
	v_add_co_u32_e32 v172, vcc, 0x17000, v130
	s_nop 1
	v_addc_co_u32_e32 v173, vcc, 0, v131, vcc
	global_load_dwordx2 v[218:219], v[172:173], off offset:-4096
	global_load_dwordx2 v[222:223], v[172:173], off
	v_add_u32_e32 v170, 0xa0, v134
	v_mad_i64_i32 v[168:169], s[98:99], v170, s22, v[132:133]
	global_load_dwordx2 v[224:225], v[168:169], off offset:2048
	global_load_dwordx2 v[228:229], v[168:169], off offset:2080
	global_load_dwordx2 v[232:233], v[168:169], off offset:2304
	global_load_dwordx2 v[236:237], v[168:169], off offset:2336
	v_add_co_u32_e32 v172, vcc, 0x19000, v130
	s_nop 1
	v_addc_co_u32_e32 v173, vcc, 0, v131, vcc
	global_load_dwordx2 v[226:227], v[172:173], off offset:-4096
	global_load_dwordx2 v[230:231], v[172:173], off
	v_add_co_u32_e32 v172, vcc, 0x1b000, v130
	s_nop 1
	v_addc_co_u32_e32 v173, vcc, 0, v131, vcc
	global_load_dwordx2 v[234:235], v[172:173], off offset:-4096
	global_load_dwordx2 v[238:239], v[172:173], off
	v_add_u32_e32 v170, 0xb0, v134
	v_mad_i64_i32 v[168:169], s[98:99], v170, s22, v[132:133]
	global_load_dwordx2 v[240:241], v[168:169], off offset:2048
	global_load_dwordx2 v[244:245], v[168:169], off offset:2080
	global_load_dwordx2 v[248:249], v[168:169], off offset:2304
	global_load_dwordx2 v[182:183], v[168:169], off offset:2336
	v_add_co_u32_e32 v172, vcc, 0x1d000, v130
	s_nop 1
	v_addc_co_u32_e32 v173, vcc, 0, v131, vcc
	global_load_dwordx2 v[242:243], v[172:173], off offset:-4096
	global_load_dwordx2 v[246:247], v[172:173], off
	v_add_co_u32_e32 v172, vcc, 0x1f000, v130
	s_nop 1
	v_addc_co_u32_e32 v173, vcc, 0, v131, vcc
	global_load_dwordx2 v[250:251], v[172:173], off offset:-4096
	global_load_dwordx2 v[184:185], v[172:173], off
	s_waitcnt vmcnt(0)
	s_mov_b32 s14, 0x12000
	v_add_u32_e32 v0, 0x90, v134
	v_mov_b64_e32 v[68:69], v[192:193]
	v_mov_b64_e32 v[70:71], v[194:195]
	v_lshlrev_b32_e32 v74, 16, v68
	v_and_b32_e32 v75, 0xffff0000, v68
	v_lshlrev_b32_e32 v68, 16, v69
	v_and_b32_e32 v69, 0xffff0000, v69
	v_lshlrev_b32_e32 v76, 16, v70
	v_and_b32_e32 v77, 0xffff0000, v70
	v_lshlrev_b32_e32 v70, 16, v71
	v_and_b32_e32 v71, 0xffff0000, v71
	v_pk_fma_f32 v[64:65], v[64:65], v[68:69], v[70:71]
	v_pk_fma_f32 v[62:63], v[62:63], v[74:75], v[76:77]
	s_nop 0
	v_cvt_pk_bf16_f32 v62, v62, v63
	v_cvt_pk_bf16_f32 v63, v64, v65
	v_add_co_u32_e32 v64, vcc, s14, v130
	global_store_dwordx2 v[72:73], v[62:63], off
	s_nop 0
	v_addc_co_u32_e32 v65, vcc, 0, v131, vcc
	s_mov_b32 s14, 0x14000
	v_mov_b64_e32 v[62:63], v[196:197]
	v_mov_b64_e32 v[68:69], v[198:199]
	v_lshlrev_b32_e32 v70, 16, v62
	v_and_b32_e32 v71, 0xffff0000, v62
	v_lshlrev_b32_e32 v72, 16, v68
	v_and_b32_e32 v73, 0xffff0000, v68
	v_lshlrev_b32_e32 v62, 16, v63
	v_and_b32_e32 v63, 0xffff0000, v63
	v_lshlrev_b32_e32 v68, 16, v69
	v_and_b32_e32 v69, 0xffff0000, v69
	v_pk_fma_f32 v[58:59], v[58:59], v[70:71], v[72:73]
	v_pk_fma_f32 v[60:61], v[60:61], v[62:63], v[68:69]
	v_cvt_pk_bf16_f32 v58, v58, v59
	s_nop 0
	v_cvt_pk_bf16_f32 v59, v60, v61
	global_store_dwordx2 v[64:65], v[58:59], off offset:-4096
	s_nop 0
	v_mov_b64_e32 v[58:59], v[200:201]
	v_mov_b64_e32 v[60:61], v[202:203]
	v_lshlrev_b32_e32 v62, 16, v58
	v_and_b32_e32 v63, 0xffff0000, v58
	v_lshlrev_b32_e32 v58, 16, v59
	v_and_b32_e32 v59, 0xffff0000, v59
	v_lshlrev_b32_e32 v68, 16, v60
	v_and_b32_e32 v69, 0xffff0000, v60
	v_lshlrev_b32_e32 v60, 16, v61
	v_and_b32_e32 v61, 0xffff0000, v61
	v_pk_fma_f32 v[56:57], v[56:57], v[58:59], v[60:61]
	v_pk_fma_f32 v[54:55], v[54:55], v[62:63], v[68:69]
	v_mad_i64_i32 v[60:61], s[58:59], v0, s22, v[132:133]
	v_cvt_pk_bf16_f32 v54, v54, v55
	v_cvt_pk_bf16_f32 v55, v56, v57
	v_add_co_u32_e32 v56, vcc, s14, v130
	global_store_dwordx2 v[64:65], v[54:55], off
	s_nop 0
	v_addc_co_u32_e32 v57, vcc, 0, v131, vcc
	s_mov_b32 s14, 0x16000
	v_add_u32_e32 v0, 0xa0, v134
	v_mov_b64_e32 v[54:55], v[204:205]
	v_mov_b64_e32 v[58:59], v[206:207]
	v_lshlrev_b32_e32 v62, 16, v54
	v_and_b32_e32 v63, 0xffff0000, v54
	v_lshlrev_b32_e32 v64, 16, v58
	v_and_b32_e32 v65, 0xffff0000, v58
	v_lshlrev_b32_e32 v54, 16, v55
	v_and_b32_e32 v55, 0xffff0000, v55
	v_lshlrev_b32_e32 v58, 16, v59
	v_and_b32_e32 v59, 0xffff0000, v59
	v_pk_fma_f32 v[50:51], v[50:51], v[62:63], v[64:65]
	v_pk_fma_f32 v[52:53], v[52:53], v[54:55], v[58:59]
	v_cvt_pk_bf16_f32 v50, v50, v51
	s_nop 0
	v_cvt_pk_bf16_f32 v51, v52, v53
	global_store_dwordx2 v[56:57], v[50:51], off offset:-4096
	s_nop 0
	v_mov_b64_e32 v[50:51], v[208:209]
	v_mov_b64_e32 v[52:53], v[210:211]
	v_lshlrev_b32_e32 v54, 16, v50
	v_and_b32_e32 v55, 0xffff0000, v50
	v_lshlrev_b32_e32 v50, 16, v51
	v_and_b32_e32 v51, 0xffff0000, v51
	v_lshlrev_b32_e32 v58, 16, v52
	v_and_b32_e32 v59, 0xffff0000, v52
	v_lshlrev_b32_e32 v52, 16, v53
	v_and_b32_e32 v53, 0xffff0000, v53
; __device__ __forceinline__ float bflo(unsigned w) { return __uint_as_float(w << 16); }
; __device__ __forceinline__ float bfhi(unsigned w) { return __uint_as_float(w & 0xffff0000u); }
; template <int MODE, bool PRE = false, bool NEXT = false> ...
;     ...
;         const u16* grow = (const u16*)e.aux + (long)row * e.ldaux + cbase;
;         u16* orow = (u16*)e.out + (long)row * e.ldo + cbase;
; #pragma unroll
;         for (int bj = 0; bj < 2; ++bj)
; #pragma unroll
;           for (int n = 0; n < 2; ++n) {
;             const int sidx = ((ai * 4 + m) * 2 + bj) * 2 + n;
;             const u32x2 gw = *reinterpret_cast<const u32x2*>(grow + bj * 128 + n * 16);
;             f32x4 g = {bflo(gw[0]), bfhi(gw[0]), bflo(gw[1]), bfhi(gw[1])};
;             f32x4 mval = g * acc[ai][bj][m][n];
;             u32x2* sp = reinterpret_cast<u32x2*>(e.scr) + sidx * NTHR + tid;
;             if constexpr (MODE != EP_M0) { const u32x2 pw = *sp; mval += f32x4{bflo(pw[0]), bfhi(pw[0]), bflo(pw[1]), bfhi(pw[1])}; }
;             const u32x2 w = {cvtpk(mval[0], mval[1]), cvtpk(mval[2], mval[3])};
;             if constexpr (MODE == EP_M2) *reinterpret_cast<u32x2*>(orow + bj * 128 + n * 16) = w;
;             else *sp = w;
;           }
	v_pk_fma_f32 v[48:49], v[48:49], v[50:51], v[52:53]
	v_pk_fma_f32 v[46:47], v[46:47], v[54:55], v[58:59]
	s_nop 0
	v_cvt_pk_bf16_f32 v46, v46, v47
	v_cvt_pk_bf16_f32 v47, v48, v49
	v_add_co_u32_e32 v48, vcc, s14, v130
	global_store_dwordx2 v[56:57], v[46:47], off
	s_nop 0
	v_addc_co_u32_e32 v49, vcc, 0, v131, vcc
	s_mov_b32 s14, 0x18000
	v_mov_b64_e32 v[46:47], v[212:213]
	v_mov_b64_e32 v[50:51], v[214:215]
	v_lshlrev_b32_e32 v52, 16, v46
	v_and_b32_e32 v53, 0xffff0000, v46
	v_lshlrev_b32_e32 v54, 16, v50
	v_and_b32_e32 v55, 0xffff0000, v50
	v_lshlrev_b32_e32 v46, 16, v47
	v_and_b32_e32 v47, 0xffff0000, v47
	v_lshlrev_b32_e32 v50, 16, v51
	v_and_b32_e32 v51, 0xffff0000, v51
	v_pk_fma_f32 v[42:43], v[42:43], v[52:53], v[54:55]
	v_pk_fma_f32 v[44:45], v[44:45], v[46:47], v[50:51]
	v_cvt_pk_bf16_f32 v42, v42, v43
	s_nop 0
	v_cvt_pk_bf16_f32 v43, v44, v45
	global_store_dwordx2 v[48:49], v[42:43], off offset:-4096
	s_nop 0
	v_mov_b64_e32 v[42:43], v[216:217]
	v_mov_b64_e32 v[44:45], v[218:219]
	v_lshlrev_b32_e32 v46, 16, v42
	v_and_b32_e32 v47, 0xffff0000, v42
	v_lshlrev_b32_e32 v42, 16, v43
	v_and_b32_e32 v43, 0xffff0000, v43
	v_lshlrev_b32_e32 v50, 16, v44
	v_and_b32_e32 v51, 0xffff0000, v44
	v_lshlrev_b32_e32 v44, 16, v45
	v_and_b32_e32 v45, 0xffff0000, v45
	v_pk_fma_f32 v[40:41], v[40:41], v[42:43], v[44:45]
	v_pk_fma_f32 v[38:39], v[38:39], v[46:47], v[50:51]
	v_mad_i64_i32 v[44:45], s[58:59], v0, s22, v[132:133]
	v_cvt_pk_bf16_f32 v38, v38, v39
	v_cvt_pk_bf16_f32 v39, v40, v41
	v_add_co_u32_e32 v40, vcc, s14, v130
	global_store_dwordx2 v[48:49], v[38:39], off
	s_nop 0
	v_addc_co_u32_e32 v41, vcc, 0, v131, vcc
	s_mov_b32 s14, 0x1a000
	v_add_u32_e32 v0, 0xb0, v134
	v_mov_b64_e32 v[38:39], v[220:221]
	v_mov_b64_e32 v[42:43], v[222:223]
	v_lshlrev_b32_e32 v46, 16, v38
	v_and_b32_e32 v47, 0xffff0000, v38
	v_lshlrev_b32_e32 v48, 16, v42
	v_and_b32_e32 v49, 0xffff0000, v42
	v_lshlrev_b32_e32 v38, 16, v39
	v_and_b32_e32 v39, 0xffff0000, v39
	v_lshlrev_b32_e32 v42, 16, v43
	v_and_b32_e32 v43, 0xffff0000, v43
	v_pk_fma_f32 v[34:35], v[34:35], v[46:47], v[48:49]
	v_pk_fma_f32 v[36:37], v[36:37], v[38:39], v[42:43]
	v_cvt_pk_bf16_f32 v34, v34, v35
	s_nop 0
	v_cvt_pk_bf16_f32 v35, v36, v37
	global_store_dwordx2 v[40:41], v[34:35], off offset:-4096
	s_nop 0
	v_mov_b64_e32 v[34:35], v[224:225]
	v_mov_b64_e32 v[36:37], v[226:227]
	v_lshlrev_b32_e32 v38, 16, v34
	v_and_b32_e32 v39, 0xffff0000, v34
	v_lshlrev_b32_e32 v34, 16, v35
	v_and_b32_e32 v35, 0xffff0000, v35
	v_lshlrev_b32_e32 v42, 16, v36
	v_and_b32_e32 v43, 0xffff0000, v36
	v_lshlrev_b32_e32 v36, 16, v37
	v_and_b32_e32 v37, 0xffff0000, v37
	v_pk_fma_f32 v[32:33], v[32:33], v[34:35], v[36:37]
	v_pk_fma_f32 v[30:31], v[30:31], v[38:39], v[42:43]
	s_nop 0
	v_cvt_pk_bf16_f32 v30, v30, v31
	v_cvt_pk_bf16_f32 v31, v32, v33
	v_add_co_u32_e32 v32, vcc, s14, v130
	global_store_dwordx2 v[40:41], v[30:31], off
	s_nop 0
	v_addc_co_u32_e32 v33, vcc, 0, v131, vcc
	s_mov_b32 s14, 0x1c000
	v_mov_b64_e32 v[30:31], v[228:229]
	v_mov_b64_e32 v[34:35], v[230:231]
	v_lshlrev_b32_e32 v36, 16, v30
	v_and_b32_e32 v37, 0xffff0000, v30
	v_lshlrev_b32_e32 v38, 16, v34
	v_and_b32_e32 v39, 0xffff0000, v34
	v_lshlrev_b32_e32 v30, 16, v31
	v_and_b32_e32 v31, 0xffff0000, v31
	v_lshlrev_b32_e32 v34, 16, v35
	v_and_b32_e32 v35, 0xffff0000, v35
	v_pk_fma_f32 v[26:27], v[26:27], v[36:37], v[38:39]
	v_pk_fma_f32 v[28:29], v[28:29], v[30:31], v[34:35]
	v_cvt_pk_bf16_f32 v26, v26, v27
	s_nop 0
	v_cvt_pk_bf16_f32 v27, v28, v29
	global_store_dwordx2 v[32:33], v[26:27], off offset:-4096
	s_nop 0
	v_mov_b64_e32 v[26:27], v[232:233]
	v_mov_b64_e32 v[28:29], v[234:235]
	v_lshlrev_b32_e32 v30, 16, v26
	v_and_b32_e32 v31, 0xffff0000, v26
	v_lshlrev_b32_e32 v26, 16, v27
	v_and_b32_e32 v27, 0xffff0000, v27
	v_lshlrev_b32_e32 v34, 16, v28
; __device__ __forceinline__ float bflo(unsigned w) { return __uint_as_float(w << 16); }
; __device__ __forceinline__ float bfhi(unsigned w) { return __uint_as_float(w & 0xffff0000u); }
; #define BAR __builtin_amdgcn_s_barrier()
; template <bool PRE, bool NEXT> ...
;     ...
;   if (wr == 1) BAR;
; template <int MODE, bool PRE = false, bool NEXT = false> ...
;     ...
;         const u16* grow = (const u16*)e.aux + (long)row * e.ldaux + cbase;
;         u16* orow = (u16*)e.out + (long)row * e.ldo + cbase;
; #pragma unroll
;         for (int bj = 0; bj < 2; ++bj)
; #pragma unroll
;           for (int n = 0; n < 2; ++n) {
;             const int sidx = ((ai * 4 + m) * 2 + bj) * 2 + n;
;             const u32x2 gw = *reinterpret_cast<const u32x2*>(grow + bj * 128 + n * 16);
;             f32x4 g = {bflo(gw[0]), bfhi(gw[0]), bflo(gw[1]), bfhi(gw[1])};
;             f32x4 mval = g * acc[ai][bj][m][n];
;             u32x2* sp = reinterpret_cast<u32x2*>(e.scr) + sidx * NTHR + tid;
;             if constexpr (MODE != EP_M0) { const u32x2 pw = *sp; mval += f32x4{bflo(pw[0]), bfhi(pw[0]), bflo(pw[1]), bfhi(pw[1])}; }
;             const u32x2 w = {cvtpk(mval[0], mval[1]), cvtpk(mval[2], mval[3])};
;             if constexpr (MODE == EP_M2) *reinterpret_cast<u32x2*>(orow + bj * 128 + n * 16) = w;
;             else *sp = w;
;           }
	v_and_b32_e32 v35, 0xffff0000, v28
	v_lshlrev_b32_e32 v28, 16, v29
	v_and_b32_e32 v29, 0xffff0000, v29
	v_pk_fma_f32 v[24:25], v[24:25], v[26:27], v[28:29]
	v_pk_fma_f32 v[22:23], v[22:23], v[30:31], v[34:35]
	v_mad_i64_i32 v[28:29], s[58:59], v0, s22, v[132:133]
	v_cvt_pk_bf16_f32 v22, v22, v23
	v_cvt_pk_bf16_f32 v23, v24, v25
	v_add_co_u32_e32 v24, vcc, s14, v130
	global_store_dwordx2 v[32:33], v[22:23], off
	s_nop 0
	v_addc_co_u32_e32 v25, vcc, 0, v131, vcc
	s_mov_b32 s14, 0x1e000
	v_mov_b64_e32 v[22:23], v[236:237]
	v_mov_b64_e32 v[26:27], v[238:239]
	v_lshlrev_b32_e32 v30, 16, v22
	v_and_b32_e32 v31, 0xffff0000, v22
	v_lshlrev_b32_e32 v32, 16, v26
	v_and_b32_e32 v33, 0xffff0000, v26
	v_lshlrev_b32_e32 v22, 16, v23
	v_and_b32_e32 v23, 0xffff0000, v23
	v_lshlrev_b32_e32 v26, 16, v27
	v_and_b32_e32 v27, 0xffff0000, v27
	v_pk_fma_f32 v[18:19], v[18:19], v[30:31], v[32:33]
	v_pk_fma_f32 v[20:21], v[20:21], v[22:23], v[26:27]
	v_cvt_pk_bf16_f32 v18, v18, v19
	s_nop 0
	v_cvt_pk_bf16_f32 v19, v20, v21
	global_store_dwordx2 v[24:25], v[18:19], off offset:-4096
	s_nop 0
	v_mov_b64_e32 v[18:19], v[240:241]
	v_mov_b64_e32 v[20:21], v[242:243]
	v_lshlrev_b32_e32 v22, 16, v18
	v_and_b32_e32 v23, 0xffff0000, v18
	v_lshlrev_b32_e32 v18, 16, v19
	v_and_b32_e32 v19, 0xffff0000, v19
	v_lshlrev_b32_e32 v26, 16, v20
	v_and_b32_e32 v27, 0xffff0000, v20
	v_lshlrev_b32_e32 v20, 16, v21
	v_and_b32_e32 v21, 0xffff0000, v21
	v_pk_fma_f32 v[16:17], v[16:17], v[18:19], v[20:21]
	v_pk_fma_f32 v[14:15], v[14:15], v[22:23], v[26:27]
	s_nop 0
	v_cvt_pk_bf16_f32 v14, v14, v15
	v_cvt_pk_bf16_f32 v15, v16, v17
	v_add_co_u32_e32 v16, vcc, s14, v130
	global_store_dwordx2 v[24:25], v[14:15], off
	s_nop 0
	v_addc_co_u32_e32 v17, vcc, 0, v131, vcc
	s_mov_b32 s14, 0x1f000
	v_mov_b64_e32 v[14:15], v[244:245]
	v_mov_b64_e32 v[18:19], v[246:247]
	v_lshlrev_b32_e32 v20, 16, v14
	v_and_b32_e32 v21, 0xffff0000, v14
	v_lshlrev_b32_e32 v22, 16, v18
	v_and_b32_e32 v23, 0xffff0000, v18
	v_lshlrev_b32_e32 v14, 16, v15
	v_and_b32_e32 v15, 0xffff0000, v15
	v_lshlrev_b32_e32 v18, 16, v19
	v_and_b32_e32 v19, 0xffff0000, v19
	v_pk_fma_f32 v[10:11], v[10:11], v[20:21], v[22:23]
	v_pk_fma_f32 v[12:13], v[12:13], v[14:15], v[18:19]
	v_cvt_pk_bf16_f32 v10, v10, v11
	s_nop 0
	v_cvt_pk_bf16_f32 v11, v12, v13
	global_store_dwordx2 v[16:17], v[10:11], off offset:-4096
	s_nop 0
	v_mov_b64_e32 v[10:11], v[248:249]
	v_mov_b64_e32 v[12:13], v[250:251]
	v_lshlrev_b32_e32 v14, 16, v10
	v_and_b32_e32 v15, 0xffff0000, v10
	v_lshlrev_b32_e32 v10, 16, v11
	v_and_b32_e32 v11, 0xffff0000, v11
	v_lshlrev_b32_e32 v18, 16, v12
	v_and_b32_e32 v19, 0xffff0000, v12
	v_lshlrev_b32_e32 v12, 16, v13
	v_and_b32_e32 v13, 0xffff0000, v13
	v_pk_fma_f32 v[8:9], v[8:9], v[10:11], v[12:13]
	v_pk_fma_f32 v[6:7], v[6:7], v[14:15], v[18:19]
	s_nop 0
	v_cvt_pk_bf16_f32 v6, v6, v7
	v_cvt_pk_bf16_f32 v7, v8, v9
	v_add_co_u32_e32 v8, vcc, s14, v130
	global_store_dwordx2 v[16:17], v[6:7], off
	s_nop 0
	v_addc_co_u32_e32 v9, vcc, 0, v131, vcc
	v_mov_b64_e32 v[6:7], v[182:183]
	v_mov_b64_e32 v[10:11], v[184:185]
	v_lshlrev_b32_e32 v12, 16, v6
	v_and_b32_e32 v13, 0xffff0000, v6
	v_lshlrev_b32_e32 v14, 16, v10
	v_and_b32_e32 v15, 0xffff0000, v10
	v_lshlrev_b32_e32 v6, 16, v7
	v_and_b32_e32 v7, 0xffff0000, v7
	v_lshlrev_b32_e32 v10, 16, v11
	v_and_b32_e32 v11, 0xffff0000, v11
	v_pk_fma_f32 v[2:3], v[2:3], v[12:13], v[14:15]
	v_pk_fma_f32 v[4:5], v[4:5], v[6:7], v[10:11]
	v_cvt_pk_bf16_f32 v2, v2, v3
	s_nop 0
	v_cvt_pk_bf16_f32 v3, v4, v5
	global_store_dwordx2 v[8:9], v[2:3], off
	v_mov_b32_e32 v130, v181
	s_mov_b64 s[18:19], 0x31f72080
	v_readfirstlane_b32 s31, v130
	s_ashr_i32 s58, s31, 8
	s_cmp_lg_u32 s58, 1
	s_mov_b64 s[20:21], 0xea0500
	s_mov_b64 s[24:25], 0x31f32100
	s_mov_b64 s[26:27], 0xee0500
	s_mov_b64 s[94:95], 0x31f72100
	s_cbranch_scc1 .LBB0_595
	s_barrier
